# speedup vs baseline: 1.0165x; 1.0059x over previous
; template <int NK, bool BNT = false> ...
;     ...
;   const int lane = tidf & 63, wid = tidf >> 6, wr = wid >> 1, wc = wid & 1, fr = lane & 15, fq = lane >> 4;
; #pragma unroll
;   for (int m = 0; m < 4; ++m)
; #pragma unroll
;     for (int n = 0; n < 8; ++n) acc[m][n] = f32x4{0.f, 0.f, 0.f, 0.f};
;   const int sb0 = tidf * 16;
;   const int sr0 = sb0 >> 6;
;   const unsigned soff = (unsigned)(sr0 * 64 + ((((sb0 >> 4) & 3) ^ (((sr0 >> 3) & 1) << 1)) * 16));
;   const unsigned char* Abase = reinterpret_cast<const unsigned char*>(A);
;   const unsigned char* Bbase = reinterpret_cast<const unsigned char*>(B);
;   auto stage = [&](int kt, int bufc) {
;     unsigned char* sa = smem + bufc * BIG_STAGE;
;     const unsigned char* Ab = Abase + (long)kt * 8192 + soff;
;     const unsigned char* Bb = Bbase + (long)kt * 8192 + soff;
;     glds16(Ab, sa + sb0);
;     glds16(Ab + astride * 2, sa + 8192 + sb0);
;     if constexpr (BNT) {
;       glds16_nt(Bb, sa + 16384 + sb0);
;       glds16_nt(Bb + bstride * 2, sa + 24576 + sb0);
;     } else {
;       glds16(Bb, sa + 16384 + sb0);
;       glds16(Bb + bstride * 2, sa + 24576 + sb0);
;     }
;   };
.LBB0_67:
	s_ashr_i32 s9, s15, 31
	s_lshr_b32 s9, s9, 27
	s_add_i32 s9, s15, s9
	s_ashr_i32 s10, s9, 5
	s_and_b32 s9, s9, 0xffe0
	s_sub_i32 s9, s15, s9
	s_bfe_i32 s11, s9, 0x80000
	s_bfe_u32 s11, s11, 0x2000d
	s_add_i32 s11, s9, s11
	s_bfe_i32 s14, s11, 0x80000
	s_and_b32 s11, s11, 0xfffc
	s_sext_i32_i16 s17, s14
	s_sub_i32 s14, s9, s11
	s_lshl_b32 s9, s10, 3
	s_ashr_i32 s10, s17, 2
	s_bfe_i64 s[18:19], s[14:15], 0x80000
	s_add_i32 s10, s9, s10
	s_lshl_b64 s[18:19], s[18:19], 19
	s_add_u32 s20, s6, s18
	s_addc_u32 s21, s7, s19
	s_ashr_i32 s11, s10, 31
	v_readlane_b32 s64, v252, 4
	s_lshl_b64 s[22:23], s[10:11], 19
	v_readlane_b32 s76, v252, 16
	v_readfirstlane_b32 s9, v166
	v_add_u32_e32 v146, 0x2000, v166
	v_readlane_b32 s77, v252, 17
	s_add_u32 s24, s76, s22
	v_lshl_add_u64 v[130:131], s[20:21], 0, v[132:133]
	s_mov_b32 m0, s9
	s_mov_b64 s[20:21], 0x40000
	v_readfirstlane_b32 s9, v146
	v_add_u32_e32 v147, 0x4000, v166
	s_addc_u32 s25, s77, s23
	global_load_lds_dwordx4 v[130:131], off
	v_lshl_add_u64 v[0:1], v[130:131], 0, s[20:21]
	s_mov_b32 m0, s9
	v_readfirstlane_b32 s9, v147
	v_add_u32_e32 v148, 0x6000, v166
	v_lshl_add_u64 v[128:129], s[24:25], 0, v[132:133]
	global_load_lds_dwordx4 v[0:1], off
	s_mov_b32 m0, s9
	v_readfirstlane_b32 s9, v148
	v_add_u32_e32 v149, 0x8000, v166
	global_load_lds_dwordx4 v[128:129], off
	v_lshl_add_u64 v[0:1], v[128:129], 0, s[20:21]
	s_mov_b32 m0, s9
	s_mov_b64 s[20:21], 0x2000
	v_readfirstlane_b32 s9, v149
	v_add_u32_e32 v150, 0xa000, v166
	global_load_lds_dwordx4 v[0:1], off
	v_lshl_add_u64 v[0:1], v[130:131], 0, s[20:21]
	v_lshl_add_u64 v[2:3], v[128:129], 0, s[20:21]
	s_mov_b32 m0, s9
	s_mov_b64 s[20:21], 0x42000
	v_readfirstlane_b32 s9, v150
	v_add_u32_e32 v151, 0xc000, v166
	global_load_lds_dwordx4 v[0:1], off
	v_lshl_add_u64 v[0:1], v[130:131], 0, s[20:21]
	s_mov_b32 m0, s9
	v_readfirstlane_b32 s9, v151
	v_add_u32_e32 v152, 0xe000, v166
	global_load_lds_dwordx4 v[0:1], off
	s_mov_b32 m0, s9
	v_readfirstlane_b32 s9, v152
	v_add_u32_e32 v154, 0x10000, v166
	global_load_lds_dwordx4 v[2:3], off
	v_lshl_add_u64 v[0:1], v[128:129], 0, s[20:21]
	s_mov_b32 m0, s9
	v_readfirstlane_b32 s9, v154
	v_add_u32_e32 v155, 0x12000, v166
	global_load_lds_dwordx4 v[0:1], off
	v_lshl_add_u64 v[0:1], v[130:131], 0, s[94:95]
	s_mov_b32 m0, s9
	s_mov_b64 s[20:21], 0x44000
	v_readfirstlane_b32 s9, v155
	v_add_u32_e32 v156, 0x14000, v166
	global_load_lds_dwordx4 v[0:1], off
	v_lshl_add_u64 v[0:1], v[130:131], 0, s[20:21]
	s_mov_b32 m0, s9
	v_readfirstlane_b32 s9, v156
	v_add_u32_e32 v157, 0x16000, v166
	v_lshl_add_u64 v[2:3], v[128:129], 0, s[94:95]
	global_load_lds_dwordx4 v[0:1], off
	s_mov_b32 m0, s9
	v_readfirstlane_b32 s9, v157
	global_load_lds_dwordx4 v[2:3], off
	v_lshl_add_u64 v[0:1], v[128:129], 0, s[20:21]
	s_mov_b32 m0, s9
	v_lshl_add_u64 v[138:139], v[134:135], 0, s[18:19]
	global_load_lds_dwordx4 v[0:1], off
	v_mov_b32_e32 v0, 0
	v_lshl_add_u64 v[140:141], v[136:137], 0, s[22:23]
	s_mov_b64 s[36:37], 0
	v_mov_b32_e32 v1, v0
	v_mov_b32_e32 v2, v0
	v_mov_b32_e32 v3, v0
	v_mov_b32_e32 v4, v0
	s_waitcnt lgkmcnt(0)
	v_mov_b32_e32 v5, v0
	v_mov_b32_e32 v6, v0
	v_mov_b32_e32 v7, v0
	v_mov_b32_e32 v8, v0
	v_mov_b32_e32 v9, v0
	v_mov_b32_e32 v10, v0
	v_mov_b32_e32 v11, v0
	v_mov_b32_e32 v12, v0
	v_mov_b32_e32 v13, v0
	v_mov_b32_e32 v14, v0
	v_mov_b32_e32 v15, v0
	v_mov_b32_e32 v32, v0
	v_mov_b32_e32 v33, v0
	v_mov_b32_e32 v34, v0
	v_mov_b32_e32 v35, v0
	v_mov_b32_e32 v36, v0
	v_mov_b32_e32 v37, v0
	v_mov_b32_e32 v38, v0
	v_mov_b32_e32 v39, v0
	v_mov_b32_e32 v40, v0
	v_mov_b32_e32 v41, v0
	v_mov_b32_e32 v42, v0
	v_mov_b32_e32 v43, v0
	v_mov_b32_e32 v44, v0
	v_mov_b32_e32 v45, v0
	v_mov_b32_e32 v46, v0
	v_mov_b32_e32 v47, v0
	v_mov_b32_e32 v16, v0
	v_mov_b32_e32 v17, v0
	v_mov_b32_e32 v18, v0
	v_mov_b32_e32 v19, v0
	v_mov_b32_e32 v20, v0
	v_mov_b32_e32 v21, v0
	v_mov_b32_e32 v22, v0
	v_mov_b32_e32 v23, v0
	v_mov_b32_e32 v24, v0
	v_mov_b32_e32 v25, v0
	v_mov_b32_e32 v26, v0
	v_mov_b32_e32 v27, v0
	v_mov_b32_e32 v28, v0
	v_mov_b32_e32 v29, v0
	v_mov_b32_e32 v30, v0
	v_mov_b32_e32 v31, v0
	v_mov_b32_e32 v64, v0
	v_mov_b32_e32 v65, v0
	v_mov_b32_e32 v66, v0
	v_mov_b32_e32 v67, v0
	v_mov_b32_e32 v68, v0
	v_mov_b32_e32 v69, v0
	v_mov_b32_e32 v70, v0
	v_mov_b32_e32 v71, v0
	v_mov_b32_e32 v76, v0
	v_mov_b32_e32 v77, v0
	v_mov_b32_e32 v78, v0
	v_mov_b32_e32 v79, v0
	v_mov_b32_e32 v88, v0
	v_mov_b32_e32 v89, v0
	v_mov_b32_e32 v90, v0
	v_mov_b32_e32 v91, v0
	v_mov_b32_e32 v48, v0
	v_mov_b32_e32 v49, v0
	v_mov_b32_e32 v50, v0
	v_mov_b32_e32 v51, v0
	v_mov_b32_e32 v52, v0
	v_mov_b32_e32 v53, v0
	v_mov_b32_e32 v54, v0
	v_mov_b32_e32 v55, v0
	v_mov_b32_e32 v56, v0
	v_mov_b32_e32 v57, v0
	v_mov_b32_e32 v58, v0
	v_mov_b32_e32 v59, v0
	v_mov_b32_e32 v60, v0
	v_mov_b32_e32 v61, v0
	v_mov_b32_e32 v62, v0
	v_mov_b32_e32 v63, v0
	v_mov_b32_e32 v96, v0
	v_mov_b32_e32 v97, v0
	v_mov_b32_e32 v98, v0
	v_mov_b32_e32 v99, v0
	v_mov_b32_e32 v100, v0
	v_mov_b32_e32 v101, v0
	v_mov_b32_e32 v102, v0
	v_mov_b32_e32 v103, v0
	v_mov_b32_e32 v104, v0
	v_mov_b32_e32 v105, v0
	v_mov_b32_e32 v106, v0
	v_mov_b32_e32 v107, v0
	v_mov_b32_e32 v108, v0
	v_mov_b32_e32 v109, v0
	v_mov_b32_e32 v110, v0
	v_mov_b32_e32 v111, v0
	v_mov_b32_e32 v72, v0
	v_mov_b32_e32 v73, v0
	v_mov_b32_e32 v74, v0
	v_mov_b32_e32 v75, v0
	v_mov_b32_e32 v80, v0
	v_mov_b32_e32 v81, v0
	v_mov_b32_e32 v82, v0
	v_mov_b32_e32 v83, v0
	v_mov_b32_e32 v84, v0
	v_mov_b32_e32 v85, v0
	v_mov_b32_e32 v86, v0
	v_mov_b32_e32 v87, v0
	v_mov_b32_e32 v92, v0
	v_mov_b32_e32 v93, v0
	v_mov_b32_e32 v94, v0
	v_mov_b32_e32 v95, v0
	v_mov_b32_e32 v112, v0
	v_mov_b32_e32 v113, v0
	v_mov_b32_e32 v114, v0
	v_mov_b32_e32 v115, v0
	v_mov_b32_e32 v116, v0
	v_mov_b32_e32 v117, v0
	v_mov_b32_e32 v118, v0
	v_mov_b32_e32 v119, v0
	v_mov_b32_e32 v120, v0
	v_mov_b32_e32 v121, v0
	v_mov_b32_e32 v122, v0
	v_mov_b32_e32 v123, v0
	v_mov_b32_e32 v124, v0
	v_mov_b32_e32 v125, v0
	v_mov_b32_e32 v126, v0
	v_mov_b32_e32 v127, v0
	v_readlane_b32 s65, v252, 5
	v_readlane_b32 s66, v252, 6
	v_readlane_b32 s67, v252, 7
	v_readlane_b32 s68, v252, 8
	v_readlane_b32 s69, v252, 9
	v_readlane_b32 s70, v252, 10
	v_readlane_b32 s71, v252, 11
	v_readlane_b32 s72, v252, 12
	v_readlane_b32 s73, v252, 13
	v_readlane_b32 s74, v252, 14
	v_readlane_b32 s75, v252, 15
	v_readlane_b32 s78, v252, 18
	v_readlane_b32 s79, v252, 19
	s_waitcnt vmcnt(8)
	s_barrier
	v_add_u32_e32 v162, 0x10000, v167
	v_or_b32_e32 v163, 0x10000, v169
	v_add_u32_e32 v176, 0x18000, v167
	v_or_b32_e32 v179, 0x18000, v169
	v_add_u32_e32 v210, 0x10000, v167
	v_or_b32_e32 v211, 0x10000, v169
	v_add_u32_e32 v212, 0x18000, v167
	v_or_b32_e32 v213, 0x18000, v169
	v_readfirstlane_b32 s100, v166
	ds_read_b128 v[216:219], v167
	ds_read_b128 v[220:223], v167 offset:1024
	ds_read_b128 v[224:227], v167 offset:2048
	ds_read_b128 v[228:231], v167 offset:3072
	ds_read_b128 v[232:235], v168 offset:16384
	ds_read_b128 v[236:239], v168 offset:17408
	ds_read_b128 v[240:243], v168 offset:18432
	ds_read_b128 v[244:247], v168 offset:19456
; #define BIG_SYNC(N)                                              \
;   asm volatile("s_waitcnt vmcnt(%0)" ::"n"(N) : "memory");       \
;   __builtin_amdgcn_s_barrier();                                  \
;   asm volatile("" ::: "memory");                                 \
;   __builtin_amdgcn_sched_barrier(0);
; template <int NK, bool BNT = false> ...
;     ...
;   auto kstep = [&](int T, int cur, int nxt, bool do_stage) {
;     const unsigned char* sa = smem + cur * BIG_STAGE;
;     bf16x8 af[4], bfr[4];
; #pragma unroll
;     for (int m = 0; m < 4; ++m) af[m] = *reinterpret_cast<const bf16x8*>(sa + aoff + m * 1024);
; #pragma unroll
;     for (int n = 0; n < 4; ++n) bfr[n] = *reinterpret_cast<const bf16x8*>(sa + boff + n * 1024);
;     __builtin_amdgcn_sched_barrier(0);
;     if (do_stage) stage(T + 3, nxt);
; #pragma unroll
;     for (int m = 0; m < 4; ++m)
; #pragma unroll
;       for (int n = 0; n < 4; ++n) acc[m][n] = __builtin_amdgcn_mfma_f32_16x16x32_bf16(af[m], bfr[n], acc[m][n], 0, 0, 0);
;     if (do_stage) {
; #pragma unroll
;       for (int q = 0; q < NG; ++q) {
;         __builtin_amdgcn_sched_group_barrier(0x008, 3, 0);
;         __builtin_amdgcn_sched_group_barrier(0x010, 1, 0);
;       }
;       __builtin_amdgcn_sched_group_barrier(0x008, 16 - 3 * NG, 0);
;     }
;     __builtin_amdgcn_sched_barrier(0);
; #pragma unroll
;     for (int n = 0; n < 4; ++n) bfr[n] = *reinterpret_cast<const bf16x8*>(sa + boff + (4 + n) * 1024);
; #pragma unroll
;     for (int m = 0; m < 4; ++m)
; #pragma unroll
;       for (int n = 0; n < 4; ++n)
;         acc[m][4 + n] = __builtin_amdgcn_mfma_f32_16x16x32_bf16(af[m], bfr[n], acc[m][4 + n], 0, 0, 0);
;     __builtin_amdgcn_sched_barrier(0);
;   };
;     ...
;   stage(0, 0);
;   stage(1, 1);
;   stage(2, 2);
;   for (int it = 0; it < NK / 4 - 1; ++it) {
;     const int t = it * 4;
;     BIG_SYNC(2 * NG); kstep(t, 0, 3, true);
;     BIG_SYNC(2 * NG); kstep(t + 1, 1, 0, true);
;     BIG_SYNC(2 * NG); kstep(t + 2, 2, 1, true);
;     BIG_SYNC(2 * NG); kstep(t + 3, 3, 2, true);
.LBB0_68:
	s_waitcnt lgkmcnt(3)
	v_mfma_f32_16x16x32_bf16 v[124:127], v[216:219], v[232:235], v[124:127]
	v_add_u32_e32 v158, 0x18000, v166
	v_mfma_f32_16x16x32_bf16 v[108:111], v[220:223], v[232:235], v[108:111]
	v_lshl_add_u64 v[144:145], v[138:139], 0, s[36:37]
	v_mfma_f32_16x16x32_bf16 v[88:91], v[224:227], v[232:235], v[88:91]
	s_waitcnt vmcnt(4)
	s_barrier
	v_add_u32_e32 v159, 0x1a000, v166
	v_mfma_f32_16x16x32_bf16 v[44:47], v[228:231], v[232:235], v[44:47]
	v_lshl_add_u64 v[160:161], v[144:145], 0, s[60:61]
	s_waitcnt lgkmcnt(2)
	v_mfma_f32_16x16x32_bf16 v[120:123], v[216:219], v[236:239], v[120:123]
	ds_read_b128 v[232:235], v168 offset:20480
	v_mfma_f32_16x16x32_bf16 v[104:107], v[220:223], v[236:239], v[104:107]
	s_add_i32 m0, s100, 0x18000
	v_mfma_f32_16x16x32_bf16 v[76:79], v[224:227], v[236:239], v[76:79]
	v_lshl_add_u64 v[142:143], v[140:141], 0, s[36:37]
	v_mfma_f32_16x16x32_bf16 v[40:43], v[228:231], v[236:239], v[40:43]
	v_lshl_add_u64 v[182:183], v[142:143], 0, s[60:61]
	s_waitcnt lgkmcnt(2)
	v_mfma_f32_16x16x32_bf16 v[116:119], v[216:219], v[240:243], v[116:119]
	ds_read_b128 v[236:239], v168 offset:21504
	v_mfma_f32_16x16x32_bf16 v[100:103], v[220:223], v[240:243], v[100:103]
	global_load_lds_dwordx4 v[160:161], off
	v_mfma_f32_16x16x32_bf16 v[68:71], v[224:227], v[240:243], v[68:71]
	v_lshl_add_u64 v[160:161], v[144:145], 0, s[80:81]
	v_mfma_f32_16x16x32_bf16 v[36:39], v[228:231], v[240:243], v[36:39]
	s_add_i32 m0, s100, 0x1a000
	s_waitcnt lgkmcnt(2)
	v_mfma_f32_16x16x32_bf16 v[112:115], v[216:219], v[244:247], v[112:115]
	ds_read_b128 v[240:243], v168 offset:22528
	v_mfma_f32_16x16x32_bf16 v[96:99], v[220:223], v[244:247], v[96:99]
	global_load_lds_dwordx4 v[160:161], off
	v_mfma_f32_16x16x32_bf16 v[64:67], v[224:227], v[244:247], v[64:67]
	v_add_u32_e32 v160, 0x1c000, v166
	v_mfma_f32_16x16x32_bf16 v[32:35], v[228:231], v[244:247], v[32:35]
	v_add_u32_e32 v161, 0x1e000, v166
	s_waitcnt lgkmcnt(2)
	v_mfma_f32_16x16x32_bf16 v[92:95], v[216:219], v[232:235], v[92:95]
	ds_read_b128 v[244:247], v168 offset:23552
	v_mfma_f32_16x16x32_bf16 v[60:63], v[220:223], v[232:235], v[60:63]
	ds_read_b128 v[186:189], v167 offset:32768
	v_mfma_f32_16x16x32_bf16 v[28:31], v[224:227], v[232:235], v[28:31]
	ds_read_b128 v[190:193], v167 offset:33792
	v_mfma_f32_16x16x32_bf16 v[12:15], v[228:231], v[232:235], v[12:15]
	ds_read_b128 v[194:197], v167 offset:34816
	s_waitcnt lgkmcnt(5)
	v_mfma_f32_16x16x32_bf16 v[84:87], v[216:219], v[236:239], v[84:87]
	ds_read_b128 v[202:205], v167 offset:35840
	ds_read_b128 v[232:235], v168 offset:49152
	v_mfma_f32_16x16x32_bf16 v[56:59], v[220:223], v[236:239], v[56:59]
	s_add_i32 m0, s100, 0x1c000
	v_mfma_f32_16x16x32_bf16 v[24:27], v[224:227], v[236:239], v[24:27]
	global_load_lds_dwordx4 v[182:183], off
	v_mfma_f32_16x16x32_bf16 v[8:11], v[228:231], v[236:239], v[8:11]
	v_lshl_add_u64 v[182:183], v[142:143], 0, s[80:81]
	s_waitcnt lgkmcnt(6)
	v_mfma_f32_16x16x32_bf16 v[80:83], v[216:219], v[240:243], v[80:83]
	ds_read_b128 v[236:239], v168 offset:50176
	v_mfma_f32_16x16x32_bf16 v[52:55], v[220:223], v[240:243], v[52:55]
	s_add_i32 m0, s100, 0x1e000
	v_mfma_f32_16x16x32_bf16 v[20:23], v[224:227], v[240:243], v[20:23]
	global_load_lds_dwordx4 v[182:183], off
	v_mfma_f32_16x16x32_bf16 v[4:7], v[228:231], v[240:243], v[4:7]
	s_waitcnt lgkmcnt(6)
	v_mfma_f32_16x16x32_bf16 v[72:75], v[216:219], v[244:247], v[72:75]
	ds_read_b128 v[240:243], v168 offset:51200
	v_mfma_f32_16x16x32_bf16 v[48:51], v[220:223], v[244:247], v[48:51]
	v_mfma_f32_16x16x32_bf16 v[16:19], v[224:227], v[244:247], v[16:19]
	v_mfma_f32_16x16x32_bf16 v[0:3], v[228:231], v[244:247], v[0:3]
	ds_read_b128 v[244:247], v168 offset:52224
	s_waitcnt lgkmcnt(3)
	v_mfma_f32_16x16x32_bf16 v[124:127], v[186:189], v[232:235], v[124:127]
	v_lshl_add_u64 v[182:183], v[144:145], 0, s[62:63]
	v_mfma_f32_16x16x32_bf16 v[108:111], v[190:193], v[232:235], v[108:111]
	s_mov_b32 m0, s100
	v_mfma_f32_16x16x32_bf16 v[88:91], v[194:197], v[232:235], v[88:91]
	s_waitcnt vmcnt(4)
	s_barrier
	v_lshl_add_u64 v[198:199], v[142:143], 0, s[62:63]
	v_mfma_f32_16x16x32_bf16 v[44:47], v[202:205], v[232:235], v[44:47]
	global_load_lds_dwordx4 v[182:183], off
	s_waitcnt lgkmcnt(2)
	v_mfma_f32_16x16x32_bf16 v[120:123], v[186:189], v[236:239], v[120:123]
	ds_read_b128 v[232:235], v168 offset:53248
	v_mfma_f32_16x16x32_bf16 v[104:107], v[190:193], v[236:239], v[104:107]
	v_lshl_add_u64 v[182:183], v[144:145], 0, s[0:1]
	v_mfma_f32_16x16x32_bf16 v[76:79], v[194:197], v[236:239], v[76:79]
	s_add_i32 m0, s100, 0x2000
	v_mfma_f32_16x16x32_bf16 v[40:43], v[202:205], v[236:239], v[40:43]
	global_load_lds_dwordx4 v[182:183], off
	s_waitcnt lgkmcnt(2)
	v_mfma_f32_16x16x32_bf16 v[116:119], v[186:189], v[240:243], v[116:119]
	ds_read_b128 v[236:239], v168 offset:54272
	v_mfma_f32_16x16x32_bf16 v[100:103], v[190:193], v[240:243], v[100:103]
	s_add_i32 m0, s100, 0x4000
	v_mfma_f32_16x16x32_bf16 v[68:71], v[194:197], v[240:243], v[68:71]
	v_lshl_add_u64 v[182:183], v[142:143], 0, s[0:1]
	v_mfma_f32_16x16x32_bf16 v[36:39], v[202:205], v[240:243], v[36:39]
	global_load_lds_dwordx4 v[198:199], off
	s_waitcnt lgkmcnt(2)
	v_mfma_f32_16x16x32_bf16 v[112:115], v[186:189], v[244:247], v[112:115]
	ds_read_b128 v[240:243], v168 offset:55296
	v_mfma_f32_16x16x32_bf16 v[96:99], v[190:193], v[244:247], v[96:99]
	s_add_i32 m0, s100, 0x6000
	v_mfma_f32_16x16x32_bf16 v[64:67], v[194:197], v[244:247], v[64:67]
	global_load_lds_dwordx4 v[182:183], off
	v_mfma_f32_16x16x32_bf16 v[32:35], v[202:205], v[244:247], v[32:35]
	s_waitcnt lgkmcnt(2)
; #define BIG_SYNC(N)                                              \
;   asm volatile("s_waitcnt vmcnt(%0)" ::"n"(N) : "memory");       \
;   __builtin_amdgcn_s_barrier();                                  \
;   asm volatile("" ::: "memory");                                 \
;   __builtin_amdgcn_sched_barrier(0);
; template <int NK, bool BNT = false> ...
;     ...
;   auto kstep = [&](int T, int cur, int nxt, bool do_stage) {
;     const unsigned char* sa = smem + cur * BIG_STAGE;
;     bf16x8 af[4], bfr[4];
; #pragma unroll
;     for (int m = 0; m < 4; ++m) af[m] = *reinterpret_cast<const bf16x8*>(sa + aoff + m * 1024);
; #pragma unroll
;     for (int n = 0; n < 4; ++n) bfr[n] = *reinterpret_cast<const bf16x8*>(sa + boff + n * 1024);
;     __builtin_amdgcn_sched_barrier(0);
;     if (do_stage) stage(T + 3, nxt);
; #pragma unroll
;     for (int m = 0; m < 4; ++m)
; #pragma unroll
;       for (int n = 0; n < 4; ++n) acc[m][n] = __builtin_amdgcn_mfma_f32_16x16x32_bf16(af[m], bfr[n], acc[m][n], 0, 0, 0);
;     if (do_stage) {
; #pragma unroll
;       for (int q = 0; q < NG; ++q) {
;         __builtin_amdgcn_sched_group_barrier(0x008, 3, 0);
;         __builtin_amdgcn_sched_group_barrier(0x010, 1, 0);
;       }
;       __builtin_amdgcn_sched_group_barrier(0x008, 16 - 3 * NG, 0);
;     }
;     __builtin_amdgcn_sched_barrier(0);
; #pragma unroll
;     for (int n = 0; n < 4; ++n) bfr[n] = *reinterpret_cast<const bf16x8*>(sa + boff + (4 + n) * 1024);
; #pragma unroll
;     for (int m = 0; m < 4; ++m)
; #pragma unroll
;       for (int n = 0; n < 4; ++n)
;         acc[m][4 + n] = __builtin_amdgcn_mfma_f32_16x16x32_bf16(af[m], bfr[n], acc[m][4 + n], 0, 0, 0);
;     __builtin_amdgcn_sched_barrier(0);
;   };
;     ...
;   stage(0, 0);
;   stage(1, 1);
;   stage(2, 2);
;   for (int it = 0; it < NK / 4 - 1; ++it) {
;     const int t = it * 4;
;     BIG_SYNC(2 * NG); kstep(t, 0, 3, true);
;     BIG_SYNC(2 * NG); kstep(t + 1, 1, 0, true);
;     BIG_SYNC(2 * NG); kstep(t + 2, 2, 1, true);
;     BIG_SYNC(2 * NG); kstep(t + 3, 3, 2, true);
	v_mfma_f32_16x16x32_bf16 v[92:95], v[186:189], v[232:235], v[92:95]
	ds_read_b128 v[244:247], v168 offset:56320
	v_mfma_f32_16x16x32_bf16 v[60:63], v[190:193], v[232:235], v[60:63]
	ds_read_b128 v[216:219], v210
	v_mfma_f32_16x16x32_bf16 v[28:31], v[194:197], v[232:235], v[28:31]
	ds_read_b128 v[220:223], v210 offset:1024
	v_mfma_f32_16x16x32_bf16 v[12:15], v[202:205], v[232:235], v[12:15]
	ds_read_b128 v[224:227], v210 offset:2048
	s_waitcnt lgkmcnt(5)
	v_mfma_f32_16x16x32_bf16 v[84:87], v[186:189], v[236:239], v[84:87]
	ds_read_b128 v[228:231], v210 offset:3072
	ds_read_b128 v[232:235], v211
	v_mfma_f32_16x16x32_bf16 v[56:59], v[190:193], v[236:239], v[56:59]
	v_mfma_f32_16x16x32_bf16 v[24:27], v[194:197], v[236:239], v[24:27]
	v_mfma_f32_16x16x32_bf16 v[8:11], v[202:205], v[236:239], v[8:11]
	s_waitcnt lgkmcnt(6)
	v_mfma_f32_16x16x32_bf16 v[80:83], v[186:189], v[240:243], v[80:83]
	ds_read_b128 v[236:239], v211 offset:1024
	v_mfma_f32_16x16x32_bf16 v[52:55], v[190:193], v[240:243], v[52:55]
	v_mfma_f32_16x16x32_bf16 v[20:23], v[194:197], v[240:243], v[20:23]
	v_mfma_f32_16x16x32_bf16 v[4:7], v[202:205], v[240:243], v[4:7]
	s_waitcnt lgkmcnt(6)
	v_mfma_f32_16x16x32_bf16 v[72:75], v[186:189], v[244:247], v[72:75]
	ds_read_b128 v[240:243], v211 offset:2048
	v_mfma_f32_16x16x32_bf16 v[48:51], v[190:193], v[244:247], v[48:51]
	v_mfma_f32_16x16x32_bf16 v[16:19], v[194:197], v[244:247], v[16:19]
	v_mfma_f32_16x16x32_bf16 v[0:3], v[202:205], v[244:247], v[0:3]
	ds_read_b128 v[244:247], v211 offset:3072
	s_waitcnt lgkmcnt(3)
	v_mfma_f32_16x16x32_bf16 v[124:127], v[216:219], v[232:235], v[124:127]
	v_lshl_add_u64 v[174:175], v[144:145], 0, s[2:3]
	v_mfma_f32_16x16x32_bf16 v[108:111], v[220:223], v[232:235], v[108:111]
	s_add_i32 m0, s100, 0x8000
	v_mfma_f32_16x16x32_bf16 v[88:91], v[224:227], v[232:235], v[88:91]
	s_waitcnt vmcnt(4)
	s_barrier
	v_lshl_add_u64 v[178:179], v[142:143], 0, s[2:3]
	v_mfma_f32_16x16x32_bf16 v[44:47], v[228:231], v[232:235], v[44:47]
	global_load_lds_dwordx4 v[174:175], off
	s_waitcnt lgkmcnt(2)
	v_mfma_f32_16x16x32_bf16 v[120:123], v[216:219], v[236:239], v[120:123]
	ds_read_b128 v[232:235], v211 offset:4096
	v_mfma_f32_16x16x32_bf16 v[104:107], v[220:223], v[236:239], v[104:107]
	v_lshl_add_u64 v[174:175], v[144:145], 0, s[52:53]
	v_mfma_f32_16x16x32_bf16 v[76:79], v[224:227], v[236:239], v[76:79]
	s_add_i32 m0, s100, 0xa000
	v_mfma_f32_16x16x32_bf16 v[40:43], v[228:231], v[236:239], v[40:43]
	global_load_lds_dwordx4 v[174:175], off
	s_waitcnt lgkmcnt(2)
	v_mfma_f32_16x16x32_bf16 v[116:119], v[216:219], v[240:243], v[116:119]
	ds_read_b128 v[236:239], v211 offset:5120
	v_mfma_f32_16x16x32_bf16 v[100:103], v[220:223], v[240:243], v[100:103]
	s_add_i32 m0, s100, 0xc000
	v_mfma_f32_16x16x32_bf16 v[68:71], v[224:227], v[240:243], v[68:71]
	v_lshl_add_u64 v[174:175], v[142:143], 0, s[52:53]
	v_mfma_f32_16x16x32_bf16 v[36:39], v[228:231], v[240:243], v[36:39]
	global_load_lds_dwordx4 v[178:179], off
	s_waitcnt lgkmcnt(2)
	v_mfma_f32_16x16x32_bf16 v[112:115], v[216:219], v[244:247], v[112:115]
	ds_read_b128 v[240:243], v211 offset:6144
	v_mfma_f32_16x16x32_bf16 v[96:99], v[220:223], v[244:247], v[96:99]
	s_add_i32 m0, s100, 0xe000
	v_mfma_f32_16x16x32_bf16 v[64:67], v[224:227], v[244:247], v[64:67]
	global_load_lds_dwordx4 v[174:175], off
	v_mfma_f32_16x16x32_bf16 v[32:35], v[228:231], v[244:247], v[32:35]
	s_waitcnt lgkmcnt(2)
	v_mfma_f32_16x16x32_bf16 v[92:95], v[216:219], v[232:235], v[92:95]
	ds_read_b128 v[244:247], v211 offset:7168
	v_mfma_f32_16x16x32_bf16 v[60:63], v[220:223], v[232:235], v[60:63]
	ds_read_b128 v[186:189], v210 offset:32768
	v_mfma_f32_16x16x32_bf16 v[28:31], v[224:227], v[232:235], v[28:31]
	ds_read_b128 v[190:193], v210 offset:33792
	v_mfma_f32_16x16x32_bf16 v[12:15], v[228:231], v[232:235], v[12:15]
	ds_read_b128 v[194:197], v210 offset:34816
	s_waitcnt lgkmcnt(5)
	v_mfma_f32_16x16x32_bf16 v[84:87], v[216:219], v[236:239], v[84:87]
	ds_read_b128 v[202:205], v210 offset:35840
	ds_read_b128 v[232:235], v211 offset:32768
	v_mfma_f32_16x16x32_bf16 v[56:59], v[220:223], v[236:239], v[56:59]
	v_mfma_f32_16x16x32_bf16 v[24:27], v[224:227], v[236:239], v[24:27]
	v_mfma_f32_16x16x32_bf16 v[8:11], v[228:231], v[236:239], v[8:11]
	s_waitcnt lgkmcnt(6)
	v_mfma_f32_16x16x32_bf16 v[80:83], v[216:219], v[240:243], v[80:83]
	ds_read_b128 v[236:239], v211 offset:33792
	v_mfma_f32_16x16x32_bf16 v[52:55], v[220:223], v[240:243], v[52:55]
	v_mfma_f32_16x16x32_bf16 v[20:23], v[224:227], v[240:243], v[20:23]
	v_mfma_f32_16x16x32_bf16 v[4:7], v[228:231], v[240:243], v[4:7]
	s_waitcnt lgkmcnt(6)
	v_mfma_f32_16x16x32_bf16 v[72:75], v[216:219], v[244:247], v[72:75]
	ds_read_b128 v[240:243], v211 offset:34816
	v_mfma_f32_16x16x32_bf16 v[48:51], v[220:223], v[244:247], v[48:51]
	v_mfma_f32_16x16x32_bf16 v[16:19], v[224:227], v[244:247], v[16:19]
	v_mfma_f32_16x16x32_bf16 v[0:3], v[228:231], v[244:247], v[0:3]
	ds_read_b128 v[244:247], v211 offset:35840
	s_waitcnt lgkmcnt(3)
	v_mfma_f32_16x16x32_bf16 v[124:127], v[186:189], v[232:235], v[124:127]
	v_lshl_add_u64 v[248:249], v[144:145], 0, s[54:55]
	v_mfma_f32_16x16x32_bf16 v[108:111], v[190:193], v[232:235], v[108:111]
	s_add_i32 m0, s100, 0x10000
	v_mfma_f32_16x16x32_bf16 v[88:91], v[194:197], v[232:235], v[88:91]
	s_waitcnt vmcnt(4)
	s_barrier
; #define BIG_SYNC(N)                                              \
;   asm volatile("s_waitcnt vmcnt(%0)" ::"n"(N) : "memory");       \
;   __builtin_amdgcn_s_barrier();                                  \
;   asm volatile("" ::: "memory");                                 \
;   __builtin_amdgcn_sched_barrier(0);
; template <int NK, bool BNT = false> ...
;     ...
;   auto kstep = [&](int T, int cur, int nxt, bool do_stage) {
;     const unsigned char* sa = smem + cur * BIG_STAGE;
;     bf16x8 af[4], bfr[4];
; #pragma unroll
;     for (int m = 0; m < 4; ++m) af[m] = *reinterpret_cast<const bf16x8*>(sa + aoff + m * 1024);
; #pragma unroll
;     for (int n = 0; n < 4; ++n) bfr[n] = *reinterpret_cast<const bf16x8*>(sa + boff + n * 1024);
;     __builtin_amdgcn_sched_barrier(0);
;     if (do_stage) stage(T + 3, nxt);
; #pragma unroll
;     for (int m = 0; m < 4; ++m)
; #pragma unroll
;       for (int n = 0; n < 4; ++n) acc[m][n] = __builtin_amdgcn_mfma_f32_16x16x32_bf16(af[m], bfr[n], acc[m][n], 0, 0, 0);
;     if (do_stage) {
; #pragma unroll
;       for (int q = 0; q < NG; ++q) {
;         __builtin_amdgcn_sched_group_barrier(0x008, 3, 0);
;         __builtin_amdgcn_sched_group_barrier(0x010, 1, 0);
;       }
;       __builtin_amdgcn_sched_group_barrier(0x008, 16 - 3 * NG, 0);
;     }
;     __builtin_amdgcn_sched_barrier(0);
; #pragma unroll
;     for (int n = 0; n < 4; ++n) bfr[n] = *reinterpret_cast<const bf16x8*>(sa + boff + (4 + n) * 1024);
; #pragma unroll
;     for (int m = 0; m < 4; ++m)
; #pragma unroll
;       for (int n = 0; n < 4; ++n)
;         acc[m][4 + n] = __builtin_amdgcn_mfma_f32_16x16x32_bf16(af[m], bfr[n], acc[m][4 + n], 0, 0, 0);
;     __builtin_amdgcn_sched_barrier(0);
;   };
;     ...
;   stage(0, 0);
;   stage(1, 1);
;   stage(2, 2);
;   for (int it = 0; it < NK / 4 - 1; ++it) {
;     const int t = it * 4;
;     BIG_SYNC(2 * NG); kstep(t, 0, 3, true);
;     BIG_SYNC(2 * NG); kstep(t + 1, 1, 0, true);
;     BIG_SYNC(2 * NG); kstep(t + 2, 2, 1, true);
;     BIG_SYNC(2 * NG); kstep(t + 3, 3, 2, true);
;   }
;   BIG_SYNC(2 * NG); kstep(NK - 4, 0, 3, true);
;   BIG_SYNC(2 * NG); kstep(NK - 3, 1, 0, false);
;   BIG_SYNC(NG);     kstep(NK - 2, 2, 0, false);
;   BIG_SYNC(0);      kstep(NK - 1, 3, 0, false);
	v_lshl_add_u64 v[144:145], v[144:145], 0, s[56:57]
	v_mfma_f32_16x16x32_bf16 v[44:47], v[202:205], v[232:235], v[44:47]
	v_lshl_add_u64 v[250:251], v[142:143], 0, s[54:55]
	s_waitcnt lgkmcnt(2)
	v_mfma_f32_16x16x32_bf16 v[120:123], v[186:189], v[236:239], v[120:123]
	ds_read_b128 v[232:235], v211 offset:36864
	v_mfma_f32_16x16x32_bf16 v[104:107], v[190:193], v[236:239], v[104:107]
	v_lshl_add_u64 v[142:143], v[142:143], 0, s[56:57]
	v_mfma_f32_16x16x32_bf16 v[76:79], v[194:197], v[236:239], v[76:79]
	global_load_lds_dwordx4 v[248:249], off
	v_mfma_f32_16x16x32_bf16 v[40:43], v[202:205], v[236:239], v[40:43]
	s_add_i32 m0, s100, 0x12000
	s_waitcnt lgkmcnt(2)
	v_mfma_f32_16x16x32_bf16 v[116:119], v[186:189], v[240:243], v[116:119]
	ds_read_b128 v[236:239], v211 offset:37888
	v_mfma_f32_16x16x32_bf16 v[100:103], v[190:193], v[240:243], v[100:103]
	global_load_lds_dwordx4 v[144:145], off
	v_mfma_f32_16x16x32_bf16 v[68:71], v[194:197], v[240:243], v[68:71]
	s_add_i32 m0, s100, 0x14000
	v_mfma_f32_16x16x32_bf16 v[36:39], v[202:205], v[240:243], v[36:39]
	global_load_lds_dwordx4 v[250:251], off
	s_waitcnt lgkmcnt(2)
	v_mfma_f32_16x16x32_bf16 v[112:115], v[186:189], v[244:247], v[112:115]
	ds_read_b128 v[240:243], v211 offset:38912
	v_mfma_f32_16x16x32_bf16 v[96:99], v[190:193], v[244:247], v[96:99]
	s_add_i32 m0, s100, 0x16000
	v_mfma_f32_16x16x32_bf16 v[64:67], v[194:197], v[244:247], v[64:67]
	global_load_lds_dwordx4 v[142:143], off
	v_mfma_f32_16x16x32_bf16 v[32:35], v[202:205], v[244:247], v[32:35]
	s_waitcnt lgkmcnt(2)
	v_mfma_f32_16x16x32_bf16 v[92:95], v[186:189], v[232:235], v[92:95]
	ds_read_b128 v[244:247], v211 offset:39936
	v_mfma_f32_16x16x32_bf16 v[60:63], v[190:193], v[232:235], v[60:63]
	ds_read_b128 v[216:219], v167
	v_mfma_f32_16x16x32_bf16 v[28:31], v[194:197], v[232:235], v[28:31]
	ds_read_b128 v[220:223], v167 offset:1024
	v_mfma_f32_16x16x32_bf16 v[12:15], v[202:205], v[232:235], v[12:15]
	ds_read_b128 v[224:227], v167 offset:2048
	s_waitcnt lgkmcnt(5)
	v_mfma_f32_16x16x32_bf16 v[84:87], v[186:189], v[236:239], v[84:87]
	ds_read_b128 v[228:231], v167 offset:3072
	ds_read_b128 v[232:235], v168 offset:16384
	v_mfma_f32_16x16x32_bf16 v[56:59], v[190:193], v[236:239], v[56:59]
	v_mfma_f32_16x16x32_bf16 v[24:27], v[194:197], v[236:239], v[24:27]
	v_mfma_f32_16x16x32_bf16 v[8:11], v[202:205], v[236:239], v[8:11]
	s_waitcnt lgkmcnt(6)
	v_mfma_f32_16x16x32_bf16 v[80:83], v[186:189], v[240:243], v[80:83]
	ds_read_b128 v[236:239], v168 offset:17408
	v_mfma_f32_16x16x32_bf16 v[52:55], v[190:193], v[240:243], v[52:55]
	v_mfma_f32_16x16x32_bf16 v[20:23], v[194:197], v[240:243], v[20:23]
	v_mfma_f32_16x16x32_bf16 v[4:7], v[202:205], v[240:243], v[4:7]
	s_waitcnt lgkmcnt(6)
	v_mfma_f32_16x16x32_bf16 v[72:75], v[186:189], v[244:247], v[72:75]
	ds_read_b128 v[240:243], v168 offset:18432
	v_mfma_f32_16x16x32_bf16 v[48:51], v[190:193], v[244:247], v[48:51]
	v_mfma_f32_16x16x32_bf16 v[16:19], v[194:197], v[244:247], v[16:19]
	v_mfma_f32_16x16x32_bf16 v[0:3], v[202:205], v[244:247], v[0:3]
	ds_read_b128 v[244:247], v168 offset:19456
	s_add_u32 s36, s36, 0x8000
	s_addc_u32 s37, s37, 0
	s_cmp_lg_u32 s36, 0x38000
	s_cbranch_scc1 .LBB0_68
	v_add_u32_e32 v162, 0x10000, v167
	v_or_b32_e32 v163, 0x10000, v169
	v_add_u32_e32 v164, 0x10400, v169
	v_add_u32_e32 v165, 0x10800, v169
	v_add_u32_e32 v172, 0x10c00, v169
	v_add_u32_e32 v173, 0x11000, v169
	v_add_u32_e32 v174, 0x11400, v169
	v_add_u32_e32 v175, 0x11800, v169
	v_add_u32_e32 v178, 0x11c00, v169
	v_add_u32_e32 v176, 0x18000, v167
	v_or_b32_e32 v179, 0x18000, v169
	v_add_u32_e32 v180, 0x18400, v169
	v_add_u32_e32 v181, 0x18800, v169
	v_add_u32_e32 v182, 0x18c00, v169
	v_add_u32_e32 v142, 0x19000, v169
	v_add_u32_e32 v143, 0x19400, v169
	v_add_u32_e32 v144, 0x19800, v169
	v_add_u32_e32 v145, 0x19c00, v169
	s_waitcnt lgkmcnt(3)
	v_mfma_f32_16x16x32_bf16 v[124:127], v[216:219], v[232:235], v[124:127]
	s_sext_i32_i8 s9, s14
	v_mfma_f32_16x16x32_bf16 v[108:111], v[220:223], v[232:235], v[108:111]
	s_mov_b64 s[18:19], 0x3e000
	v_mfma_f32_16x16x32_bf16 v[88:91], v[224:227], v[232:235], v[88:91]
	s_waitcnt vmcnt(4)
	s_barrier
	v_readfirstlane_b32 s11, v158
	v_mfma_f32_16x16x32_bf16 v[44:47], v[228:231], v[232:235], v[44:47]
	v_lshl_add_u64 v[150:151], v[130:131], 0, s[18:19]
	s_waitcnt lgkmcnt(2)
	v_mfma_f32_16x16x32_bf16 v[120:123], v[216:219], v[236:239], v[120:123]
	ds_read_b128 v[232:235], v168 offset:20480
	v_mfma_f32_16x16x32_bf16 v[104:107], v[220:223], v[236:239], v[104:107]
	v_lshl_add_u64 v[198:199], v[128:129], 0, s[18:19]
	v_mfma_f32_16x16x32_bf16 v[76:79], v[224:227], v[236:239], v[76:79]
	s_mov_b32 m0, s11
	v_mfma_f32_16x16x32_bf16 v[40:43], v[228:231], v[236:239], v[40:43]
	s_mov_b64 s[18:19], 0x7e000
	s_waitcnt lgkmcnt(2)
	v_mfma_f32_16x16x32_bf16 v[116:119], v[216:219], v[240:243], v[116:119]
	ds_read_b128 v[236:239], v168 offset:21504
	v_mfma_f32_16x16x32_bf16 v[100:103], v[220:223], v[240:243], v[100:103]
	v_readfirstlane_b32 s11, v159
	v_mfma_f32_16x16x32_bf16 v[68:71], v[224:227], v[240:243], v[68:71]
	v_lshl_add_u64 v[130:131], v[130:131], 0, s[18:19]
	v_mfma_f32_16x16x32_bf16 v[36:39], v[228:231], v[240:243], v[36:39]
	v_lshl_add_u64 v[128:129], v[128:129], 0, s[18:19]
	s_waitcnt lgkmcnt(2)
	v_mfma_f32_16x16x32_bf16 v[112:115], v[216:219], v[244:247], v[112:115]
	ds_read_b128 v[240:243], v168 offset:22528
	v_mfma_f32_16x16x32_bf16 v[96:99], v[220:223], v[244:247], v[96:99]
	global_load_lds_dwordx4 v[150:151], off
	v_mfma_f32_16x16x32_bf16 v[64:67], v[224:227], v[244:247], v[64:67]
	s_mov_b32 m0, s11
	v_mfma_f32_16x16x32_bf16 v[32:35], v[228:231], v[244:247], v[32:35]
	v_readfirstlane_b32 s11, v160
	s_waitcnt lgkmcnt(2)
; #define BIG_SYNC(N)                                              \
;   asm volatile("s_waitcnt vmcnt(%0)" ::"n"(N) : "memory");       \
;   __builtin_amdgcn_s_barrier();                                  \
;   asm volatile("" ::: "memory");                                 \
;   __builtin_amdgcn_sched_barrier(0);
; template <int NK, bool BNT = false> ...
;     ...
;   auto kstep = [&](int T, int cur, int nxt, bool do_stage) {
;     const unsigned char* sa = smem + cur * BIG_STAGE;
;     bf16x8 af[4], bfr[4];
; #pragma unroll
;     for (int m = 0; m < 4; ++m) af[m] = *reinterpret_cast<const bf16x8*>(sa + aoff + m * 1024);
; #pragma unroll
;     for (int n = 0; n < 4; ++n) bfr[n] = *reinterpret_cast<const bf16x8*>(sa + boff + n * 1024);
;     __builtin_amdgcn_sched_barrier(0);
;     if (do_stage) stage(T + 3, nxt);
; #pragma unroll
;     for (int m = 0; m < 4; ++m)
; #pragma unroll
;       for (int n = 0; n < 4; ++n) acc[m][n] = __builtin_amdgcn_mfma_f32_16x16x32_bf16(af[m], bfr[n], acc[m][n], 0, 0, 0);
;     if (do_stage) {
; #pragma unroll
;       for (int q = 0; q < NG; ++q) {
;         __builtin_amdgcn_sched_group_barrier(0x008, 3, 0);
;         __builtin_amdgcn_sched_group_barrier(0x010, 1, 0);
;       }
;       __builtin_amdgcn_sched_group_barrier(0x008, 16 - 3 * NG, 0);
;     }
;     __builtin_amdgcn_sched_barrier(0);
; #pragma unroll
;     for (int n = 0; n < 4; ++n) bfr[n] = *reinterpret_cast<const bf16x8*>(sa + boff + (4 + n) * 1024);
; #pragma unroll
;     for (int m = 0; m < 4; ++m)
; #pragma unroll
;       for (int n = 0; n < 4; ++n)
;         acc[m][4 + n] = __builtin_amdgcn_mfma_f32_16x16x32_bf16(af[m], bfr[n], acc[m][4 + n], 0, 0, 0);
;     __builtin_amdgcn_sched_barrier(0);
;   };
;     ...
;   stage(0, 0);
;   stage(1, 1);
;   stage(2, 2);
;   for (int it = 0; it < NK / 4 - 1; ++it) {
;     const int t = it * 4;
;     BIG_SYNC(2 * NG); kstep(t, 0, 3, true);
;     BIG_SYNC(2 * NG); kstep(t + 1, 1, 0, true);
;     BIG_SYNC(2 * NG); kstep(t + 2, 2, 1, true);
;     BIG_SYNC(2 * NG); kstep(t + 3, 3, 2, true);
;   }
;   BIG_SYNC(2 * NG); kstep(NK - 4, 0, 3, true);
;   BIG_SYNC(2 * NG); kstep(NK - 3, 1, 0, false);
;   BIG_SYNC(NG);     kstep(NK - 2, 2, 0, false);
;   BIG_SYNC(0);      kstep(NK - 1, 3, 0, false);
	v_mfma_f32_16x16x32_bf16 v[92:95], v[216:219], v[232:235], v[92:95]
	ds_read_b128 v[244:247], v168 offset:23552
	v_mfma_f32_16x16x32_bf16 v[60:63], v[220:223], v[232:235], v[60:63]
	ds_read_b128 v[186:189], v167 offset:32768
	v_mfma_f32_16x16x32_bf16 v[28:31], v[224:227], v[232:235], v[28:31]
	ds_read_b128 v[190:193], v167 offset:33792
	v_mfma_f32_16x16x32_bf16 v[12:15], v[228:231], v[232:235], v[12:15]
	ds_read_b128 v[194:197], v167 offset:34816
	s_waitcnt lgkmcnt(5)
	v_mfma_f32_16x16x32_bf16 v[84:87], v[216:219], v[236:239], v[84:87]
	ds_read_b128 v[202:205], v167 offset:35840
	ds_read_b128 v[232:235], v168 offset:49152
	v_mfma_f32_16x16x32_bf16 v[56:59], v[220:223], v[236:239], v[56:59]
	global_load_lds_dwordx4 v[130:131], off
	v_mfma_f32_16x16x32_bf16 v[24:27], v[224:227], v[236:239], v[24:27]
	s_mov_b32 m0, s11
	v_mfma_f32_16x16x32_bf16 v[8:11], v[228:231], v[236:239], v[8:11]
	v_readfirstlane_b32 s11, v161
	s_waitcnt lgkmcnt(6)
	v_mfma_f32_16x16x32_bf16 v[80:83], v[216:219], v[240:243], v[80:83]
	ds_read_b128 v[236:239], v168 offset:50176
	v_mfma_f32_16x16x32_bf16 v[52:55], v[220:223], v[240:243], v[52:55]
	global_load_lds_dwordx4 v[198:199], off
	v_mfma_f32_16x16x32_bf16 v[20:23], v[224:227], v[240:243], v[20:23]
	s_mov_b32 m0, s11
	v_mfma_f32_16x16x32_bf16 v[4:7], v[228:231], v[240:243], v[4:7]
	global_load_lds_dwordx4 v[128:129], off
	s_waitcnt lgkmcnt(6)
	v_mfma_f32_16x16x32_bf16 v[72:75], v[216:219], v[244:247], v[72:75]
	ds_read_b128 v[240:243], v168 offset:51200
	v_mfma_f32_16x16x32_bf16 v[48:51], v[220:223], v[244:247], v[48:51]
	v_mfma_f32_16x16x32_bf16 v[16:19], v[224:227], v[244:247], v[16:19]
	v_mfma_f32_16x16x32_bf16 v[0:3], v[228:231], v[244:247], v[0:3]
	ds_read_b128 v[244:247], v168 offset:52224
	s_waitcnt lgkmcnt(3)
	v_mfma_f32_16x16x32_bf16 v[124:127], v[186:189], v[232:235], v[124:127]
	v_mfma_f32_16x16x32_bf16 v[108:111], v[190:193], v[232:235], v[108:111]
	v_mfma_f32_16x16x32_bf16 v[88:91], v[194:197], v[232:235], v[88:91]
	v_mfma_f32_16x16x32_bf16 v[44:47], v[202:205], v[232:235], v[44:47]
	s_waitcnt vmcnt(4)
	s_barrier
	s_waitcnt lgkmcnt(2)
	v_mfma_f32_16x16x32_bf16 v[120:123], v[186:189], v[236:239], v[120:123]
	ds_read_b128 v[232:235], v168 offset:53248
	v_mfma_f32_16x16x32_bf16 v[104:107], v[190:193], v[236:239], v[104:107]
	v_mfma_f32_16x16x32_bf16 v[76:79], v[194:197], v[236:239], v[76:79]
	v_mfma_f32_16x16x32_bf16 v[40:43], v[202:205], v[236:239], v[40:43]
	s_waitcnt lgkmcnt(2)
	v_mfma_f32_16x16x32_bf16 v[116:119], v[186:189], v[240:243], v[116:119]
	ds_read_b128 v[236:239], v168 offset:54272
	v_mfma_f32_16x16x32_bf16 v[100:103], v[190:193], v[240:243], v[100:103]
	v_mfma_f32_16x16x32_bf16 v[68:71], v[194:197], v[240:243], v[68:71]
	v_mfma_f32_16x16x32_bf16 v[36:39], v[202:205], v[240:243], v[36:39]
	s_waitcnt lgkmcnt(2)
	v_mfma_f32_16x16x32_bf16 v[112:115], v[186:189], v[244:247], v[112:115]
	ds_read_b128 v[240:243], v168 offset:55296
	v_mfma_f32_16x16x32_bf16 v[96:99], v[190:193], v[244:247], v[96:99]
	v_mfma_f32_16x16x32_bf16 v[64:67], v[194:197], v[244:247], v[64:67]
	v_mfma_f32_16x16x32_bf16 v[32:35], v[202:205], v[244:247], v[32:35]
	s_waitcnt lgkmcnt(2)
	v_mfma_f32_16x16x32_bf16 v[92:95], v[186:189], v[232:235], v[92:95]
	ds_read_b128 v[244:247], v168 offset:56320
	v_mfma_f32_16x16x32_bf16 v[60:63], v[190:193], v[232:235], v[60:63]
	v_mfma_f32_16x16x32_bf16 v[28:31], v[194:197], v[232:235], v[28:31]
	v_mfma_f32_16x16x32_bf16 v[12:15], v[202:205], v[232:235], v[12:15]
	s_waitcnt lgkmcnt(2)
	v_mfma_f32_16x16x32_bf16 v[84:87], v[186:189], v[236:239], v[84:87]
	v_mfma_f32_16x16x32_bf16 v[56:59], v[190:193], v[236:239], v[56:59]
	v_mfma_f32_16x16x32_bf16 v[24:27], v[194:197], v[236:239], v[24:27]
	v_mfma_f32_16x16x32_bf16 v[8:11], v[202:205], v[236:239], v[8:11]
	s_waitcnt lgkmcnt(1)
	v_mfma_f32_16x16x32_bf16 v[80:83], v[186:189], v[240:243], v[80:83]
	v_mfma_f32_16x16x32_bf16 v[52:55], v[190:193], v[240:243], v[52:55]
	v_mfma_f32_16x16x32_bf16 v[20:23], v[194:197], v[240:243], v[20:23]
	v_mfma_f32_16x16x32_bf16 v[4:7], v[202:205], v[240:243], v[4:7]
	s_waitcnt lgkmcnt(0)
	v_mfma_f32_16x16x32_bf16 v[72:75], v[186:189], v[244:247], v[72:75]
	v_mfma_f32_16x16x32_bf16 v[48:51], v[190:193], v[244:247], v[48:51]
	v_mfma_f32_16x16x32_bf16 v[16:19], v[194:197], v[244:247], v[16:19]
	v_mfma_f32_16x16x32_bf16 v[0:3], v[202:205], v[244:247], v[0:3]
	v_mov_b32_e32 v186, 0xf149f2ca
	v_mov_b32_e32 v187, 0x3c0881c4
	v_mov_b32_e32 v188, 0xbab64f3b
	v_mov_b32_e32 v189, 0x24800
	v_mov_b32_e32 v190, 1
	v_mov_b32_e32 v191, 0x24804
	v_mov_b32_e32 v192, 0xfcf
	v_mov_b32_e32 v193, 0x7cf
	v_mov_b32_e32 v194, 0xfdf
	v_mov_b32_e32 v195, 0x7df
	v_mov_b32_e32 v196, 0xfef
	v_mov_b32_e32 v197, 0x7ef
	v_mov_b32_e32 v198, 0xfff
	v_mov_b32_e32 v199, 0x7ff
	v_mov_b32_e32 v200, 0x20000
	v_mov_b32_e32 v201, 0xf8f
	v_mov_b32_e32 v202, 0x78f
	v_mov_b32_e32 v203, 0xf9f
	v_mov_b32_e32 v204, 0x79f
	v_mov_b32_e32 v205, 0xfaf
	v_mov_b32_e32 v210, 0x7f800000
	v_not_b32_e32 v211, 63
	v_not_b32_e32 v212, 31
	v_mov_b32_e32 v213, 0x7fc00000
	s_waitcnt vmcnt(4)
	s_barrier
; template <int NK, bool BNT = false> ...
;     ...
;   auto kstep = [&](int T, int cur, int nxt, bool do_stage) {
;     const unsigned char* sa = smem + cur * BIG_STAGE;
;     bf16x8 af[4], bfr[4];
; #pragma unroll
;     for (int m = 0; m < 4; ++m) af[m] = *reinterpret_cast<const bf16x8*>(sa + aoff + m * 1024);
; #pragma unroll
;     for (int n = 0; n < 4; ++n) bfr[n] = *reinterpret_cast<const bf16x8*>(sa + boff + n * 1024);
;     __builtin_amdgcn_sched_barrier(0);
;     if (do_stage) stage(T + 3, nxt);
; #pragma unroll
;     for (int m = 0; m < 4; ++m)
; #pragma unroll
;       for (int n = 0; n < 4; ++n) acc[m][n] = __builtin_amdgcn_mfma_f32_16x16x32_bf16(af[m], bfr[n], acc[m][n], 0, 0, 0);
;     if (do_stage) {
; #pragma unroll
;       for (int q = 0; q < NG; ++q) {
;         __builtin_amdgcn_sched_group_barrier(0x008, 3, 0);
;         __builtin_amdgcn_sched_group_barrier(0x010, 1, 0);
;       }
;       __builtin_amdgcn_sched_group_barrier(0x008, 16 - 3 * NG, 0);
;     }
;     __builtin_amdgcn_sched_barrier(0);
; #pragma unroll
;     for (int n = 0; n < 4; ++n) bfr[n] = *reinterpret_cast<const bf16x8*>(sa + boff + (4 + n) * 1024);
; #pragma unroll
;     for (int m = 0; m < 4; ++m)
; #pragma unroll
;       for (int n = 0; n < 4; ++n)
;         acc[m][4 + n] = __builtin_amdgcn_mfma_f32_16x16x32_bf16(af[m], bfr[n], acc[m][4 + n], 0, 0, 0);
;     __builtin_amdgcn_sched_barrier(0);
	ds_read_b128 v[128:131], v162
	ds_read_b128 v[138:141], v162 offset:1024
	ds_read_b128 v[146:149], v162 offset:2048
	ds_read_b128 v[154:157], v162 offset:3072
	ds_read_b128 v[158:161], v163
	ds_read_b128 v[216:219], v164
	ds_read_b128 v[162:165], v165
	ds_read_b128 v[220:223], v172
	s_waitcnt lgkmcnt(0)
	v_mfma_f32_16x16x32_bf16 v[124:127], v[128:131], v[158:161], v[124:127]
	v_mfma_f32_16x16x32_bf16 v[116:119], v[128:131], v[162:165], v[116:119]
	v_mfma_f32_16x16x32_bf16 v[112:115], v[128:131], v[220:223], v[112:115]
	v_mfma_f32_16x16x32_bf16 v[104:107], v[138:141], v[216:219], v[104:107]
	v_mfma_f32_16x16x32_bf16 v[100:103], v[138:141], v[162:165], v[100:103]
	v_mfma_f32_16x16x32_bf16 v[96:99], v[138:141], v[220:223], v[96:99]
	v_mfma_f32_16x16x32_bf16 v[68:71], v[146:149], v[162:165], v[68:71]
	v_mfma_f32_16x16x32_bf16 v[64:67], v[146:149], v[220:223], v[64:67]
	v_mfma_f32_16x16x32_bf16 v[44:47], v[154:157], v[158:161], v[44:47]
	v_mfma_f32_16x16x32_bf16 v[40:43], v[154:157], v[216:219], v[40:43]
	v_mfma_f32_16x16x32_bf16 v[36:39], v[154:157], v[162:165], v[36:39]
	v_mfma_f32_16x16x32_bf16 v[32:35], v[154:157], v[220:223], v[32:35]
	v_mfma_f32_16x16x32_bf16 v[120:123], v[128:131], v[216:219], v[120:123]
	v_mfma_f32_16x16x32_bf16 v[224:227], v[138:141], v[158:161], v[108:111]
	v_mfma_f32_16x16x32_bf16 v[228:231], v[146:149], v[158:161], v[88:91]
	v_mfma_f32_16x16x32_bf16 v[232:235], v[146:149], v[216:219], v[76:79]
	s_nop 2
	ds_read_b128 v[76:79], v173
	ds_read_b128 v[88:91], v174
	s_waitcnt lgkmcnt(0)
	v_mfma_f32_16x16x32_bf16 v[158:161], v[128:131], v[76:79], v[92:95]
	s_nop 2
	ds_read_b128 v[92:95], v178
	v_mfma_f32_16x16x32_bf16 v[162:165], v[128:131], v[88:91], v[84:87]
	s_nop 2
	ds_read_b128 v[84:87], v175
	s_waitcnt lgkmcnt(0)
	v_mfma_f32_16x16x32_bf16 v[172:175], v[128:131], v[84:87], v[80:83]
	v_mfma_f32_16x16x32_bf16 v[128:131], v[128:131], v[92:95], v[72:75]
	v_mfma_f32_16x16x32_bf16 v[216:219], v[138:141], v[76:79], v[60:63]
	v_mfma_f32_16x16x32_bf16 v[220:223], v[138:141], v[88:91], v[56:59]
	v_mfma_f32_16x16x32_bf16 v[52:55], v[138:141], v[84:87], v[52:55]
	v_mfma_f32_16x16x32_bf16 v[48:51], v[138:141], v[92:95], v[48:51]
	v_mfma_f32_16x16x32_bf16 v[138:141], v[146:149], v[76:79], v[28:31]
	v_mfma_f32_16x16x32_bf16 v[236:239], v[146:149], v[88:91], v[24:27]
	v_mfma_f32_16x16x32_bf16 v[20:23], v[146:149], v[84:87], v[20:23]
	v_mfma_f32_16x16x32_bf16 v[16:19], v[146:149], v[92:95], v[16:19]
	v_mfma_f32_16x16x32_bf16 v[146:149], v[154:157], v[76:79], v[12:15]
	v_mfma_f32_16x16x32_bf16 v[0:3], v[154:157], v[92:95], v[0:3]
	v_mfma_f32_16x16x32_bf16 v[240:243], v[154:157], v[88:91], v[8:11]
	v_mfma_f32_16x16x32_bf16 v[244:247], v[154:157], v[84:87], v[4:7]
	s_waitcnt vmcnt(0)
	s_barrier
	s_nop 1
	ds_read_b128 v[4:7], v176
	ds_read_b128 v[8:11], v176 offset:1024
	ds_read_b128 v[154:157], v176 offset:2048
	ds_read_b128 v[12:15], v179
	ds_read_b128 v[24:27], v180
	ds_read_b128 v[28:31], v181
	ds_read_b128 v[56:59], v182
	ds_read_b128 v[248:251], v176 offset:3072
	s_waitcnt lgkmcnt(0)
	v_mfma_f32_16x16x32_bf16 v[108:111], v[4:7], v[24:27], v[120:123]
	v_mfma_f32_16x16x32_bf16 v[92:95], v[4:7], v[28:31], v[116:119]
	v_mfma_f32_16x16x32_bf16 v[76:79], v[4:7], v[56:59], v[112:115]
	v_mfma_f32_16x16x32_bf16 v[104:107], v[8:11], v[24:27], v[104:107]
	v_mfma_f32_16x16x32_bf16 v[88:91], v[8:11], v[28:31], v[100:103]
	v_mfma_f32_16x16x32_bf16 v[72:75], v[8:11], v[56:59], v[96:99]
	v_mfma_f32_16x16x32_bf16 v[100:103], v[154:157], v[24:27], v[232:235]
	v_mfma_f32_16x16x32_bf16 v[84:87], v[154:157], v[28:31], v[68:71]
	v_mfma_f32_16x16x32_bf16 v[68:71], v[154:157], v[56:59], v[64:67]
	v_mfma_f32_16x16x32_bf16 v[116:119], v[248:251], v[12:15], v[44:47]
	v_mfma_f32_16x16x32_bf16 v[96:99], v[248:251], v[24:27], v[40:43]
	v_mfma_f32_16x16x32_bf16 v[80:83], v[248:251], v[28:31], v[36:39]
	v_mfma_f32_16x16x32_bf16 v[64:67], v[248:251], v[56:59], v[32:35]
	v_mfma_f32_16x16x32_bf16 v[178:181], v[4:7], v[12:15], v[124:127]
	v_mfma_f32_16x16x32_bf16 v[224:227], v[8:11], v[12:15], v[224:227]
	v_mfma_f32_16x16x32_bf16 v[120:123], v[154:157], v[12:15], v[228:231]
	ds_read_b128 v[32:35], v142
	ds_read_b128 v[112:115], v143
	ds_read_b128 v[124:127], v144
	ds_read_b128 v[142:145], v145
	s_waitcnt lgkmcnt(0)
; __device__ __forceinline__ float bf2f(bf16_t b) { return __uint_as_float(((unsigned)b) << 16); }
; __device__ __forceinline__ int widen_off(int fq) { return ((fq & 1) << 4) + ((fq >> 1) << 3); }
; template <int MODE, int NSUB>
; __device__ __forceinline__ void epilogue(const Params& p, int layer, f32x4 (&acc)[4][NSUB], int tm, int tn, int g,
;                                          const float* s_rstd, const int tid_in) {
;     ...
;     const int fb = tm * 128 + wr * 64 + fq * 4;
;     const int tb = tn * (NSUB * 32) + wc * (NSUB * 16) + fr;
;     const int fw = tm * 128 + wr * 64 + widen_off(fq);
;     u32x4 curw[2], nxtw[2];
; #pragma unroll
;     for (int mp = 0; mp < 2; ++mp) curw[mp] = *reinterpret_cast<const u32x4*>(p.xb + blk(tb, fw + mp * 32, 32));
; #pragma unroll
;     for (int n = 0; n < NSUB; ++n) {
;       if (n + 1 < NSUB) {
; #pragma unroll
;         for (int mp = 0; mp < 2; ++mp) nxtw[mp] = *reinterpret_cast<const u32x4*>(p.xb + blk(tb + (n + 1) * 16, fw + mp * 32, 32));
;       }
;       bf16x4 cur[4];
;       unwiden_pair(curw[0], cur[0], cur[1]);
;       unwiden_pair(curw[1], cur[2], cur[3]);
;       const int t = tb + n * 16;
;       float ss = 0.f;
; #pragma unroll
;       for (int mp = 0; mp < 2; ++mp) {
;         bf16x4 pk[2];
; #pragma unroll
;         for (int h2 = 0; h2 < 2; ++h2) {
;           const int m = mp * 2 + h2;
;           const float x0 = bf2f((bf16_t)cur[m][0]) + acc[m][n][0], x1 = bf2f((bf16_t)cur[m][1]) + acc[m][n][1];
;           const float x2 = bf2f((bf16_t)cur[m][2]) + acc[m][n][2], x3 = bf2f((bf16_t)cur[m][3]) + acc[m][n][3];
;           ss += x0 * x0 + x1 * x1 + x2 * x2 + x3 * x3;
;           pk[h2] = pack4(x0, x1, x2, x3);
;         }
;         const int f = tm * 128 + wr * 64 + mp * 32 + widen_off(fq);
;         *reinterpret_cast<u32x4*>(p.xb + blk(t, f, 32)) = widen_pair(pk[0], pk[1]);
;       }
;       ss = red_fq(ss);
;       if (fq == 0) p.part[(long)t * 16 + tm * 2 + wr] = ss;
	v_mfma_f32_16x16x32_bf16 v[60:63], v[4:7], v[32:35], v[158:161]
	v_mfma_f32_16x16x32_bf16 v[44:47], v[4:7], v[112:115], v[162:165]
	v_mfma_f32_16x16x32_bf16 v[28:31], v[4:7], v[124:127], v[172:175]
	v_mfma_f32_16x16x32_bf16 v[12:15], v[4:7], v[142:145], v[128:131]
	v_mfma_f32_16x16x32_bf16 v[56:59], v[8:11], v[32:35], v[216:219]
	v_mfma_f32_16x16x32_bf16 v[40:43], v[8:11], v[112:115], v[220:223]
	v_mfma_f32_16x16x32_bf16 v[24:27], v[8:11], v[124:127], v[52:55]
	v_mfma_f32_16x16x32_bf16 v[8:11], v[8:11], v[142:145], v[48:51]
	v_mfma_f32_16x16x32_bf16 v[52:55], v[154:157], v[32:35], v[138:141]
	v_mfma_f32_16x16x32_bf16 v[36:39], v[154:157], v[112:115], v[236:239]
	v_mfma_f32_16x16x32_bf16 v[20:23], v[154:157], v[124:127], v[20:23]
	v_mfma_f32_16x16x32_bf16 v[4:7], v[154:157], v[142:145], v[16:19]
	v_mfma_f32_16x16x32_bf16 v[48:51], v[248:251], v[32:35], v[146:149]
	v_mfma_f32_16x16x32_bf16 v[32:35], v[248:251], v[112:115], v[240:243]
	v_mfma_f32_16x16x32_bf16 v[16:19], v[248:251], v[124:127], v[244:247]
	v_mfma_f32_16x16x32_bf16 v[0:3], v[248:251], v[142:145], v[0:3]
	v_lshl_add_u32 v124, s9, 1, v170
	v_mov_b32_e32 v112, v215
	v_lshlrev_b32_e32 v113, 7, v124
	v_ashrrev_i32_e32 v138, 7, v112
	v_lshl_add_u32 v114, v138, 6, v113
	v_lshlrev_b32_e32 v113, 1, v112
	v_and_b32_e32 v113, 0x80, v113
	v_lshl_or_b32 v127, s10, 8, v113
	v_lshrrev_b32_e32 v113, 2, v112
	v_and_b32_e32 v125, 15, v112
	v_and_b32_e32 v113, 8, v113
	v_ashrrev_i32_e32 v115, 2, v127
	v_readlane_b32 s80, v253, 25
	v_ashrrev_i32_e32 v114, 5, v114
	v_bfe_u32 v126, v112, 4, 2
	v_and_or_b32 v112, v112, 16, v113
	v_lshlrev_b32_e32 v156, 6, v125
	v_mov_b32_e32 v157, v153
	v_readlane_b32 s84, v253, 29
	v_readlane_b32 s85, v253, 30
	v_add_u32_e32 v114, v114, v115
	v_lshlrev_b32_e32 v152, 1, v112
	v_lshl_add_u64 v[144:145], s[84:85], 0, v[156:157]
	v_ashrrev_i32_e32 v115, 31, v114
	v_lshl_add_u64 v[112:113], v[144:145], 0, v[152:153]
	v_lshlrev_b64 v[146:147], 13, v[114:115]
	v_or_b32_e32 v114, 1, v114
	v_lshl_add_u64 v[150:151], v[112:113], 0, v[146:147]
	v_ashrrev_i32_e32 v115, 31, v114
	global_load_dwordx4 v[158:161], v[150:151], off
	v_lshlrev_b64 v[148:149], 13, v[114:115]
	v_lshl_add_u64 v[154:155], v[112:113], 0, v[148:149]
	global_load_dwordx4 v[128:131], v[154:155], off
	v_and_b32_e32 v113, 64, v185
	v_xor_b32_e32 v112, 16, v185
	v_add_u32_e32 v113, 64, v113
	v_cmp_lt_i32_e32 vcc, v112, v113
	v_or_b32_e32 v142, v127, v125
	v_lshlrev_b32_e32 v140, 1, v124
	v_cndmask_b32_e32 v112, v185, v112, vcc
	v_lshlrev_b32_e32 v172, 2, v112
	v_xor_b32_e32 v112, 32, v185
	v_cmp_lt_i32_e32 vcc, v112, v113
	v_ashrrev_i32_e32 v141, 31, v140
	v_ashrrev_i32_e32 v139, 31, v138
	v_cndmask_b32_e32 v112, v185, v112, vcc
	v_lshlrev_b32_e32 v173, 2, v112
	v_cmp_eq_u32_e32 vcc, 0, v126
	global_load_dwordx4 v[124:127], v[150:151], off offset:1024
	global_load_dwordx4 v[112:115], v[154:155], off offset:1024
	v_readlane_b32 s81, v253, 26
	v_readlane_b32 s82, v253, 27
	v_readlane_b32 s83, v253, 28
	v_readlane_b32 s86, v253, 31
	v_readlane_b32 s87, v253, 32
	v_readlane_b32 s88, v253, 33
	v_readlane_b32 s89, v253, 34
	v_readlane_b32 s90, v253, 35
	v_readlane_b32 s91, v253, 36
	v_readlane_b32 s92, v253, 37
	v_readlane_b32 s93, v253, 38
	v_readlane_b32 s94, v253, 39
	v_readlane_b32 s95, v253, 40
	s_waitcnt vmcnt(0)
	v_mov_b32_e32 v143, v160
	s_nop 1
	v_permlane16_swap_b32_e32 v158, v143
	v_mov_b32_e32 v164, v161
	s_nop 1
	v_permlane16_swap_b32_e32 v159, v164
	v_mov_b32_e32 v176, v130
	v_mov_b32_e32 v182, v131
	v_and_b32_e32 v131, 0xffff0000, v158
	v_lshlrev_b32_e32 v130, 16, v158
	v_pk_add_f32 v[130:131], v[178:179], v[130:131]
	v_and_b32_e32 v161, 0xffff0000, v159
	v_lshlrev_b32_e32 v160, 16, v159
	v_pk_add_f32 v[162:163], v[180:181], v[160:161]
	v_pk_mul_f32 v[160:161], v[130:131], v[130:131]
	v_cvt_pk_bf16_f32 v178, v130, v131
	v_and_b32_e32 v131, 0xffff0000, v143
	v_lshlrev_b32_e32 v130, 16, v143
	v_pk_mul_f32 v[158:159], v[162:163], v[162:163]
	v_cvt_pk_bf16_f32 v179, v162, v163
	v_pk_add_f32 v[130:131], v[224:225], v[130:131]
	v_and_b32_e32 v163, 0xffff0000, v164
	v_lshlrev_b32_e32 v162, 16, v164
	v_pk_add_f32 v[174:175], v[226:227], v[162:163]
	v_pk_mul_f32 v[164:165], v[130:131], v[130:131]
	v_cvt_pk_bf16_f32 v180, v130, v131
	v_lshl_add_u64 v[130:131], s[84:85], 0, v[146:147]
	v_pk_mul_f32 v[162:163], v[174:175], v[174:175]
	v_cvt_pk_bf16_f32 v181, v174, v175
	v_lshl_add_u64 v[174:175], v[130:131], 0, v[156:157]
	v_permlane16_swap_b32_e32 v128, v176
	v_permlane16_swap_b32_e32 v178, v180
	v_permlane16_swap_b32_e32 v179, v181
	v_lshl_add_u64 v[174:175], v[174:175], 0, v[152:153]
	v_permlane16_swap_b32_e32 v129, v182
	global_store_dwordx4 v[174:175], v[178:181], off
	v_and_b32_e32 v175, 0xffff0000, v128
	v_lshlrev_b32_e32 v174, 16, v128
	v_pk_add_f32 v[120:121], v[120:121], v[174:175]
	v_and_b32_e32 v175, 0xffff0000, v129
	v_lshlrev_b32_e32 v174, 16, v129
	v_pk_add_f32 v[122:123], v[122:123], v[174:175]
	v_pk_mul_f32 v[128:129], v[120:121], v[120:121]
	v_pk_mul_f32 v[174:175], v[122:123], v[122:123]
	v_cvt_pk_bf16_f32 v120, v120, v121
	v_cvt_pk_bf16_f32 v121, v122, v123
	v_and_b32_e32 v123, 0xffff0000, v176
	v_lshlrev_b32_e32 v122, 16, v176
	v_pk_add_f32 v[116:117], v[116:117], v[122:123]
	v_and_b32_e32 v123, 0xffff0000, v182
	v_lshlrev_b32_e32 v122, 16, v182
	v_add_f32_e32 v143, v164, v165
	v_add_f32_e32 v160, v160, v161
	v_pk_add_f32 v[118:119], v[118:119], v[122:123]
	v_pk_mul_f32 v[122:123], v[116:117], v[116:117]
	v_add_f32_e32 v143, v162, v143
	v_add_f32_e32 v158, v158, v160
	v_add_f32_e32 v128, v128, v129
	v_pk_mul_f32 v[178:179], v[118:119], v[118:119]
	v_add_f32_e32 v143, v163, v143
	v_add_f32_e32 v158, v159, v158
	v_add_f32_e32 v128, v174, v128
	v_add_f32_e32 v122, v122, v123
	v_add_f32_e32 v143, v158, v143
	v_add_f32_e32 v128, v175, v128
	v_add_f32_e32 v122, v178, v122
	v_add_f32_e32 v128, v143, v128
	v_add_f32_e32 v122, v179, v122
	v_add_f32_e32 v143, v122, v128
	v_lshl_add_u64 v[128:129], s[84:85], 0, v[148:149]
	v_cvt_pk_bf16_f32 v122, v116, v117
	v_cvt_pk_bf16_f32 v123, v118, v119
	v_lshl_add_u64 v[116:117], v[128:129], 0, v[156:157]
	v_permlane16_swap_b32_e32 v120, v122
	v_permlane16_swap_b32_e32 v121, v123
	v_lshl_add_u64 v[116:117], v[116:117], 0, v[152:153]
	global_store_dwordx4 v[116:117], v[120:123], off
	ds_bpermute_b32 v116, v172, v143
	s_waitcnt lgkmcnt(0)
	v_add_f32_e32 v116, v143, v116
	ds_bpermute_b32 v117, v173, v116
	s_and_saveexec_b64 s[10:11], vcc
	s_cbranch_execz .LBB0_71
; template <int MODE, int NSUB>
; __device__ __forceinline__ void epilogue(const Params& p, int layer, f32x4 (&acc)[4][NSUB], int tm, int tn, int g,
;                                          const float* s_rstd, const int tid_in) {
;     ...
;       ss = red_fq(ss);
;       if (fq == 0) p.part[(long)t * 16 + tm * 2 + wr] = ss;
	v_ashrrev_i32_e32 v143, 31, v142
	v_readlane_b32 s64, v253, 25
	v_lshlrev_b64 v[118:119], 6, v[142:143]
	v_readlane_b32 s70, v253, 31
	v_readlane_b32 s71, v253, 32
	s_waitcnt lgkmcnt(0)
	v_add_f32_e32 v116, v116, v117
	v_readlane_b32 s65, v253, 26
	v_lshl_add_u64 v[118:119], s[70:71], 0, v[118:119]
	v_lshl_add_u64 v[118:119], v[140:141], 2, v[118:119]
	v_lshl_add_u64 v[118:119], v[138:139], 2, v[118:119]
	v_readlane_b32 s66, v253, 27
	v_readlane_b32 s67, v253, 28
	v_readlane_b32 s68, v253, 29
	v_readlane_b32 s69, v253, 30
	v_readlane_b32 s72, v253, 33
	v_readlane_b32 s73, v253, 34
	v_readlane_b32 s74, v253, 35
	v_readlane_b32 s75, v253, 36
	v_readlane_b32 s76, v253, 37
	v_readlane_b32 s77, v253, 38
	v_readlane_b32 s78, v253, 39
	v_readlane_b32 s79, v253, 40
	global_store_dword v[118:119], v116, off

; template <int NK, bool BNT = false> ...
;     ...
;   const int lane = tidf & 63, wid = tidf >> 6, wr = wid >> 1, wc = wid & 1, fr = lane & 15, fq = lane >> 4;
; #pragma unroll
;   for (int m = 0; m < 4; ++m)
; #pragma unroll
;     for (int n = 0; n < 8; ++n) acc[m][n] = f32x4{0.f, 0.f, 0.f, 0.f};
;   const int sb0 = tidf * 16;
;   const int sr0 = sb0 >> 6;
;   const unsigned soff = (unsigned)(sr0 * 64 + ((((sb0 >> 4) & 3) ^ (((sr0 >> 3) & 1) << 1)) * 16));
;   const unsigned char* Abase = reinterpret_cast<const unsigned char*>(A);
;   const unsigned char* Bbase = reinterpret_cast<const unsigned char*>(B);
;   auto stage = [&](int kt, int bufc) {
;     unsigned char* sa = smem + bufc * BIG_STAGE;
;     const unsigned char* Ab = Abase + (long)kt * 8192 + soff;
;     const unsigned char* Bb = Bbase + (long)kt * 8192 + soff;
;     glds16(Ab, sa + sb0);
;     glds16(Ab + astride * 2, sa + 8192 + sb0);
;     if constexpr (BNT) {
;       glds16_nt(Bb, sa + 16384 + sb0);
;       glds16_nt(Bb + bstride * 2, sa + 24576 + sb0);
;     } else {
;       glds16(Bb, sa + 16384 + sb0);
;       glds16(Bb + bstride * 2, sa + 24576 + sb0);
;     }
;   };
; __global__ void __launch_bounds__(NTHREADS) fwd_megakernel(Params p) {
;     ...
;           for (int id = rvid; id < 4 * CHUNK_TT; id += Greal) {
;             int ftb, ttl;
;             tile_decode(id, 4, ftb, ttl);
;             f32x4 acc[4][8];
;             gemm_big<128, true>(acc, W + (long)ftb * 256 * 4096, 128 * 4096, p.hm + (long)ttl * 256 * 4096, 128 * 4096, smem_all, tid_full);
.LBB0_263:
	s_ashr_i32 s12, s9, 31
	s_lshr_b32 s12, s12, 27
	s_add_i32 s12, s9, s12
	s_ashr_i32 s13, s12, 5
	s_and_b32 s12, s12, 0xffe0
	s_sub_i32 s12, s9, s12
	s_bfe_i32 s14, s12, 0x80000
	s_bfe_u32 s14, s14, 0x2000d
	s_add_i32 s14, s12, s14
	s_bfe_i32 s17, s14, 0x80000
	s_and_b32 s14, s14, 0xfffc
	s_sext_i32_i16 s17, s17
	s_sub_i32 s14, s12, s14
	s_lshl_b32 s12, s13, 3
	s_ashr_i32 s13, s17, 2
	s_bfe_i64 s[18:19], s[14:15], 0x80000
	s_add_i32 s12, s12, s13
	s_lshl_b64 s[18:19], s[18:19], 21
	s_add_u32 s20, s10, s18
	s_addc_u32 s21, s11, s19
	s_ashr_i32 s13, s12, 31
	v_readlane_b32 s64, v252, 4
	s_lshl_b64 s[22:23], s[12:13], 21
	v_readlane_b32 s78, v252, 18
	v_readfirstlane_b32 s13, v166
	v_add_u32_e32 v146, 0x2000, v166
	v_readlane_b32 s79, v252, 19
	s_add_u32 s24, s78, s22
	v_lshl_add_u64 v[130:131], s[20:21], 0, v[132:133]
	s_mov_b32 m0, s13
	s_mov_b64 s[20:21], 0x100000
	v_readfirstlane_b32 s13, v146
	v_add_u32_e32 v147, 0x4000, v166
	s_addc_u32 s25, s79, s23
	global_load_lds_dwordx4 v[130:131], off
	v_lshl_add_u64 v[0:1], v[130:131], 0, s[20:21]
	s_mov_b32 m0, s13
	v_readfirstlane_b32 s13, v147
	v_add_u32_e32 v148, 0x6000, v166
	v_lshl_add_u64 v[128:129], s[24:25], 0, v[132:133]
	global_load_lds_dwordx4 v[0:1], off
	s_mov_b32 m0, s13
	v_readfirstlane_b32 s13, v148
	v_add_u32_e32 v149, 0x8000, v166
	global_load_lds_dwordx4 v[128:129], off nt
	v_lshl_add_u64 v[0:1], v[128:129], 0, s[20:21]
	s_mov_b32 m0, s13
	s_mov_b64 s[20:21], 0x2000
	v_readfirstlane_b32 s13, v149
	v_add_u32_e32 v150, 0xa000, v166
	global_load_lds_dwordx4 v[0:1], off nt
	v_lshl_add_u64 v[0:1], v[130:131], 0, s[20:21]
	v_lshl_add_u64 v[2:3], v[128:129], 0, s[20:21]
	s_mov_b32 m0, s13
	s_mov_b64 s[20:21], 0x102000
	v_readfirstlane_b32 s13, v150
	v_add_u32_e32 v151, 0xc000, v166
	global_load_lds_dwordx4 v[0:1], off
	v_lshl_add_u64 v[0:1], v[130:131], 0, s[20:21]
	s_mov_b32 m0, s13
	v_readfirstlane_b32 s13, v151
	v_add_u32_e32 v152, 0xe000, v166
	global_load_lds_dwordx4 v[0:1], off
	s_mov_b32 m0, s13
	v_readfirstlane_b32 s13, v152
	v_add_u32_e32 v154, 0x10000, v166
	global_load_lds_dwordx4 v[2:3], off nt
	v_lshl_add_u64 v[0:1], v[128:129], 0, s[20:21]
	s_mov_b32 m0, s13
	v_readfirstlane_b32 s13, v154
	v_add_u32_e32 v155, 0x12000, v166
	global_load_lds_dwordx4 v[0:1], off nt
	v_lshl_add_u64 v[0:1], v[130:131], 0, s[94:95]
	s_mov_b32 m0, s13
	s_mov_b64 s[20:21], 0x104000
	v_readfirstlane_b32 s13, v155
	v_add_u32_e32 v156, 0x14000, v166
	global_load_lds_dwordx4 v[0:1], off
	v_lshl_add_u64 v[0:1], v[130:131], 0, s[20:21]
	s_mov_b32 m0, s13
	v_readfirstlane_b32 s13, v156
	v_add_u32_e32 v157, 0x16000, v166
	v_lshl_add_u64 v[2:3], v[128:129], 0, s[94:95]
	global_load_lds_dwordx4 v[0:1], off
	s_mov_b32 m0, s13
	v_readfirstlane_b32 s13, v157
	global_load_lds_dwordx4 v[2:3], off nt
	v_lshl_add_u64 v[0:1], v[128:129], 0, s[20:21]
	s_mov_b32 m0, s13
	v_lshl_add_u64 v[138:139], v[134:135], 0, s[18:19]
	global_load_lds_dwordx4 v[0:1], off nt
	v_mov_b32_e32 v0, 0
	v_lshl_add_u64 v[140:141], v[136:137], 0, s[22:23]
	s_mov_b64 s[36:37], 0
	v_mov_b32_e32 v1, v0
	v_mov_b32_e32 v2, v0
	v_mov_b32_e32 v3, v0
	v_mov_b32_e32 v4, v0
	s_waitcnt lgkmcnt(0)
	v_mov_b32_e32 v5, v0
	v_mov_b32_e32 v6, v0
	v_mov_b32_e32 v7, v0
	v_mov_b32_e32 v8, v0
	v_mov_b32_e32 v9, v0
	v_mov_b32_e32 v10, v0
	v_mov_b32_e32 v11, v0
	v_mov_b32_e32 v12, v0
	v_mov_b32_e32 v13, v0
	v_mov_b32_e32 v14, v0
	v_mov_b32_e32 v15, v0
	v_mov_b32_e32 v32, v0
	v_mov_b32_e32 v33, v0
	v_mov_b32_e32 v34, v0
	v_mov_b32_e32 v35, v0
	v_mov_b32_e32 v36, v0
	v_mov_b32_e32 v37, v0
	v_mov_b32_e32 v38, v0
	v_mov_b32_e32 v39, v0
	v_mov_b32_e32 v40, v0
	v_mov_b32_e32 v41, v0
	v_mov_b32_e32 v42, v0
	v_mov_b32_e32 v43, v0
	v_mov_b32_e32 v44, v0
	v_mov_b32_e32 v45, v0
	v_mov_b32_e32 v46, v0
	v_mov_b32_e32 v47, v0
	v_mov_b32_e32 v16, v0
	v_mov_b32_e32 v17, v0
	v_mov_b32_e32 v18, v0
	v_mov_b32_e32 v19, v0
	v_mov_b32_e32 v20, v0
	v_mov_b32_e32 v21, v0
	v_mov_b32_e32 v22, v0
	v_mov_b32_e32 v23, v0
	v_mov_b32_e32 v24, v0
	v_mov_b32_e32 v25, v0
	v_mov_b32_e32 v26, v0
	v_mov_b32_e32 v27, v0
	v_mov_b32_e32 v28, v0
	v_mov_b32_e32 v29, v0
	v_mov_b32_e32 v30, v0
	v_mov_b32_e32 v31, v0
	v_mov_b32_e32 v64, v0
	v_mov_b32_e32 v65, v0
	v_mov_b32_e32 v66, v0
	v_mov_b32_e32 v67, v0
	v_mov_b32_e32 v68, v0
	v_mov_b32_e32 v69, v0
	v_mov_b32_e32 v70, v0
	v_mov_b32_e32 v71, v0
	v_mov_b32_e32 v76, v0
	v_mov_b32_e32 v77, v0
	v_mov_b32_e32 v78, v0
	v_mov_b32_e32 v79, v0
	v_mov_b32_e32 v88, v0
	v_mov_b32_e32 v89, v0
	v_mov_b32_e32 v90, v0
	v_mov_b32_e32 v91, v0
	v_mov_b32_e32 v48, v0
	v_mov_b32_e32 v49, v0
	v_mov_b32_e32 v50, v0
	v_mov_b32_e32 v51, v0
	v_mov_b32_e32 v52, v0
	v_mov_b32_e32 v53, v0
	v_mov_b32_e32 v54, v0
	v_mov_b32_e32 v55, v0
	v_mov_b32_e32 v56, v0
	v_mov_b32_e32 v57, v0
	v_mov_b32_e32 v58, v0
	v_mov_b32_e32 v59, v0
	v_mov_b32_e32 v60, v0
	v_mov_b32_e32 v61, v0
	v_mov_b32_e32 v62, v0
	v_mov_b32_e32 v63, v0
	v_mov_b32_e32 v96, v0
	v_mov_b32_e32 v97, v0
	v_mov_b32_e32 v98, v0
	v_mov_b32_e32 v99, v0
	v_mov_b32_e32 v100, v0
	v_mov_b32_e32 v101, v0
	v_mov_b32_e32 v102, v0
	v_mov_b32_e32 v103, v0
	v_mov_b32_e32 v104, v0
	v_mov_b32_e32 v105, v0
	v_mov_b32_e32 v106, v0
	v_mov_b32_e32 v107, v0
	v_mov_b32_e32 v108, v0
	v_mov_b32_e32 v109, v0
	v_mov_b32_e32 v110, v0
	v_mov_b32_e32 v111, v0
	v_mov_b32_e32 v72, v0
	v_mov_b32_e32 v73, v0
	v_mov_b32_e32 v74, v0
	v_mov_b32_e32 v75, v0
	v_mov_b32_e32 v80, v0
	v_mov_b32_e32 v81, v0
	v_mov_b32_e32 v82, v0
	v_mov_b32_e32 v83, v0
	v_mov_b32_e32 v84, v0
	v_mov_b32_e32 v85, v0
	v_mov_b32_e32 v86, v0
	v_mov_b32_e32 v87, v0
	v_mov_b32_e32 v92, v0
	v_mov_b32_e32 v93, v0
	v_mov_b32_e32 v94, v0
	v_mov_b32_e32 v95, v0
	v_mov_b32_e32 v112, v0
	v_mov_b32_e32 v113, v0
	v_mov_b32_e32 v114, v0
	v_mov_b32_e32 v115, v0
	v_mov_b32_e32 v116, v0
	v_mov_b32_e32 v117, v0
	v_mov_b32_e32 v118, v0
	v_mov_b32_e32 v119, v0
	v_mov_b32_e32 v120, v0
	v_mov_b32_e32 v121, v0
	v_mov_b32_e32 v122, v0
	v_mov_b32_e32 v123, v0
	v_mov_b32_e32 v124, v0
	v_mov_b32_e32 v125, v0
	v_mov_b32_e32 v126, v0
	v_mov_b32_e32 v127, v0
	s_mov_b64 s[18:19], 0x106000
	s_mov_b64 s[20:21], 0x108000
	s_mov_b64 s[22:23], 0x10a000
	s_mov_b64 s[24:25], 0x10c000
	v_readlane_b32 s65, v252, 5
	v_readlane_b32 s66, v252, 6
	v_readlane_b32 s67, v252, 7
	v_readlane_b32 s68, v252, 8
	v_readlane_b32 s69, v252, 9
	v_readlane_b32 s70, v252, 10
	v_readlane_b32 s71, v252, 11
	v_readlane_b32 s72, v252, 12
	v_readlane_b32 s73, v252, 13
	v_readlane_b32 s74, v252, 14
	v_readlane_b32 s75, v252, 15
	v_readlane_b32 s76, v252, 16
	v_readlane_b32 s77, v252, 17
	s_waitcnt vmcnt(8)
	s_barrier
; #define BIG_SYNC(N)                                              \
;   asm volatile("s_waitcnt vmcnt(%0)" ::"n"(N) : "memory");       \
;   __builtin_amdgcn_s_barrier();                                  \
;   asm volatile("" ::: "memory");                                 \
;   __builtin_amdgcn_sched_barrier(0);
; template <int NK, bool BNT = false> ...
;     ...
;   auto kstep = [&](int T, int cur, int nxt, bool do_stage) {
;     const unsigned char* sa = smem + cur * BIG_STAGE;
;     bf16x8 af[4], bfr[4];
; #pragma unroll
;     for (int m = 0; m < 4; ++m) af[m] = *reinterpret_cast<const bf16x8*>(sa + aoff + m * 1024);
; #pragma unroll
;     for (int n = 0; n < 4; ++n) bfr[n] = *reinterpret_cast<const bf16x8*>(sa + boff + n * 1024);
;     __builtin_amdgcn_sched_barrier(0);
;     if (do_stage) stage(T + 3, nxt);
; #pragma unroll
;     for (int m = 0; m < 4; ++m)
; #pragma unroll
;       for (int n = 0; n < 4; ++n) acc[m][n] = __builtin_amdgcn_mfma_f32_16x16x32_bf16(af[m], bfr[n], acc[m][n], 0, 0, 0);
;     if (do_stage) {
; #pragma unroll
;       for (int q = 0; q < NG; ++q) {
;         __builtin_amdgcn_sched_group_barrier(0x008, 3, 0);
;         __builtin_amdgcn_sched_group_barrier(0x010, 1, 0);
;       }
;       __builtin_amdgcn_sched_group_barrier(0x008, 16 - 3 * NG, 0);
;     }
;     __builtin_amdgcn_sched_barrier(0);
; #pragma unroll
;     for (int n = 0; n < 4; ++n) bfr[n] = *reinterpret_cast<const bf16x8*>(sa + boff + (4 + n) * 1024);
; #pragma unroll
;     for (int m = 0; m < 4; ++m)
; #pragma unroll
;       for (int n = 0; n < 4; ++n)
;         acc[m][4 + n] = __builtin_amdgcn_mfma_f32_16x16x32_bf16(af[m], bfr[n], acc[m][4 + n], 0, 0, 0);
;     __builtin_amdgcn_sched_barrier(0);
;   };
;     ...
;   stage(0, 0);
;   stage(1, 1);
;   stage(2, 2);
;   for (int it = 0; it < NK / 4 - 1; ++it) {
;     const int t = it * 4;
;     BIG_SYNC(2 * NG); kstep(t, 0, 3, true);
;     BIG_SYNC(2 * NG); kstep(t + 1, 1, 0, true);
;     BIG_SYNC(2 * NG); kstep(t + 2, 2, 1, true);
;     BIG_SYNC(2 * NG); kstep(t + 3, 3, 2, true);
	v_add_u32_e32 v162, 0x10000, v167
	v_or_b32_e32 v163, 0x10000, v169
	v_add_u32_e32 v176, 0x18000, v167
	v_or_b32_e32 v179, 0x18000, v169
	v_add_u32_e32 v210, 0x10000, v167
	v_or_b32_e32 v211, 0x10000, v169
	v_add_u32_e32 v212, 0x18000, v167
	v_or_b32_e32 v213, 0x18000, v169
	v_readfirstlane_b32 s100, v166
	ds_read_b128 v[216:219], v167
	ds_read_b128 v[220:223], v167 offset:1024
	ds_read_b128 v[224:227], v167 offset:2048
	ds_read_b128 v[228:231], v167 offset:3072
	ds_read_b128 v[232:235], v168 offset:16384
	ds_read_b128 v[236:239], v168 offset:17408
	ds_read_b128 v[240:243], v168 offset:18432
	ds_read_b128 v[244:247], v168 offset:19456
.LBB0_264:
	s_waitcnt lgkmcnt(3)
	v_mfma_f32_16x16x32_bf16 v[124:127], v[216:219], v[232:235], v[124:127]
	v_add_u32_e32 v158, 0x18000, v166
	v_mfma_f32_16x16x32_bf16 v[108:111], v[220:223], v[232:235], v[108:111]
	v_lshl_add_u64 v[144:145], v[138:139], 0, s[36:37]
	v_mfma_f32_16x16x32_bf16 v[88:91], v[224:227], v[232:235], v[88:91]
	s_waitcnt vmcnt(4)
	s_barrier
	v_add_u32_e32 v159, 0x1a000, v166
	v_mfma_f32_16x16x32_bf16 v[44:47], v[228:231], v[232:235], v[44:47]
	v_lshl_add_u64 v[160:161], v[144:145], 0, s[60:61]
	s_waitcnt lgkmcnt(2)
	v_mfma_f32_16x16x32_bf16 v[120:123], v[216:219], v[236:239], v[120:123]
	ds_read_b128 v[232:235], v168 offset:20480
	v_mfma_f32_16x16x32_bf16 v[104:107], v[220:223], v[236:239], v[104:107]
	s_add_i32 m0, s100, 0x18000
	v_mfma_f32_16x16x32_bf16 v[76:79], v[224:227], v[236:239], v[76:79]
	v_lshl_add_u64 v[142:143], v[140:141], 0, s[36:37]
	v_mfma_f32_16x16x32_bf16 v[40:43], v[228:231], v[236:239], v[40:43]
	v_lshl_add_u64 v[182:183], v[142:143], 0, s[60:61]
	s_waitcnt lgkmcnt(2)
	v_mfma_f32_16x16x32_bf16 v[116:119], v[216:219], v[240:243], v[116:119]
	ds_read_b128 v[236:239], v168 offset:21504
	v_mfma_f32_16x16x32_bf16 v[100:103], v[220:223], v[240:243], v[100:103]
	global_load_lds_dwordx4 v[160:161], off
	v_mfma_f32_16x16x32_bf16 v[68:71], v[224:227], v[240:243], v[68:71]
	v_lshl_add_u64 v[160:161], v[144:145], 0, s[18:19]
	v_mfma_f32_16x16x32_bf16 v[36:39], v[228:231], v[240:243], v[36:39]
	s_add_i32 m0, s100, 0x1a000
	s_waitcnt lgkmcnt(2)
	v_mfma_f32_16x16x32_bf16 v[112:115], v[216:219], v[244:247], v[112:115]
	ds_read_b128 v[240:243], v168 offset:22528
	v_mfma_f32_16x16x32_bf16 v[96:99], v[220:223], v[244:247], v[96:99]
	global_load_lds_dwordx4 v[160:161], off
	v_mfma_f32_16x16x32_bf16 v[64:67], v[224:227], v[244:247], v[64:67]
	v_add_u32_e32 v160, 0x1c000, v166
	v_mfma_f32_16x16x32_bf16 v[32:35], v[228:231], v[244:247], v[32:35]
	v_add_u32_e32 v161, 0x1e000, v166
	s_waitcnt lgkmcnt(2)
	v_mfma_f32_16x16x32_bf16 v[92:95], v[216:219], v[232:235], v[92:95]
	ds_read_b128 v[244:247], v168 offset:23552
	v_mfma_f32_16x16x32_bf16 v[60:63], v[220:223], v[232:235], v[60:63]
	ds_read_b128 v[186:189], v167 offset:32768
	v_mfma_f32_16x16x32_bf16 v[28:31], v[224:227], v[232:235], v[28:31]
	ds_read_b128 v[190:193], v167 offset:33792
	v_mfma_f32_16x16x32_bf16 v[12:15], v[228:231], v[232:235], v[12:15]
	ds_read_b128 v[194:197], v167 offset:34816
	s_waitcnt lgkmcnt(5)
	v_mfma_f32_16x16x32_bf16 v[84:87], v[216:219], v[236:239], v[84:87]
	ds_read_b128 v[202:205], v167 offset:35840
	ds_read_b128 v[232:235], v168 offset:49152
	v_mfma_f32_16x16x32_bf16 v[56:59], v[220:223], v[236:239], v[56:59]
	s_add_i32 m0, s100, 0x1c000
	v_mfma_f32_16x16x32_bf16 v[24:27], v[224:227], v[236:239], v[24:27]
	global_load_lds_dwordx4 v[182:183], off nt
	v_mfma_f32_16x16x32_bf16 v[8:11], v[228:231], v[236:239], v[8:11]
	v_lshl_add_u64 v[182:183], v[142:143], 0, s[18:19]
	s_waitcnt lgkmcnt(6)
	v_mfma_f32_16x16x32_bf16 v[80:83], v[216:219], v[240:243], v[80:83]
	ds_read_b128 v[236:239], v168 offset:50176
	v_mfma_f32_16x16x32_bf16 v[52:55], v[220:223], v[240:243], v[52:55]
	s_add_i32 m0, s100, 0x1e000
	v_mfma_f32_16x16x32_bf16 v[20:23], v[224:227], v[240:243], v[20:23]
	global_load_lds_dwordx4 v[182:183], off nt
	v_mfma_f32_16x16x32_bf16 v[4:7], v[228:231], v[240:243], v[4:7]
	s_waitcnt lgkmcnt(6)
	v_mfma_f32_16x16x32_bf16 v[72:75], v[216:219], v[244:247], v[72:75]
	ds_read_b128 v[240:243], v168 offset:51200
	v_mfma_f32_16x16x32_bf16 v[48:51], v[220:223], v[244:247], v[48:51]
	v_mfma_f32_16x16x32_bf16 v[16:19], v[224:227], v[244:247], v[16:19]
	v_mfma_f32_16x16x32_bf16 v[0:3], v[228:231], v[244:247], v[0:3]
	ds_read_b128 v[244:247], v168 offset:52224
	s_waitcnt lgkmcnt(3)
	v_mfma_f32_16x16x32_bf16 v[124:127], v[186:189], v[232:235], v[124:127]
	v_lshl_add_u64 v[182:183], v[144:145], 0, s[62:63]
	v_mfma_f32_16x16x32_bf16 v[108:111], v[190:193], v[232:235], v[108:111]
	s_mov_b32 m0, s100
	v_mfma_f32_16x16x32_bf16 v[88:91], v[194:197], v[232:235], v[88:91]
	s_waitcnt vmcnt(4)
	s_barrier
; #define BIG_SYNC(N)                                              \
;   asm volatile("s_waitcnt vmcnt(%0)" ::"n"(N) : "memory");       \
;   __builtin_amdgcn_s_barrier();                                  \
;   asm volatile("" ::: "memory");                                 \
;   __builtin_amdgcn_sched_barrier(0);
; template <int NK, bool BNT = false> ...
;     ...
;   auto kstep = [&](int T, int cur, int nxt, bool do_stage) {
;     const unsigned char* sa = smem + cur * BIG_STAGE;
;     bf16x8 af[4], bfr[4];
; #pragma unroll
;     for (int m = 0; m < 4; ++m) af[m] = *reinterpret_cast<const bf16x8*>(sa + aoff + m * 1024);
; #pragma unroll
;     for (int n = 0; n < 4; ++n) bfr[n] = *reinterpret_cast<const bf16x8*>(sa + boff + n * 1024);
;     __builtin_amdgcn_sched_barrier(0);
;     if (do_stage) stage(T + 3, nxt);
; #pragma unroll
;     for (int m = 0; m < 4; ++m)
; #pragma unroll
;       for (int n = 0; n < 4; ++n) acc[m][n] = __builtin_amdgcn_mfma_f32_16x16x32_bf16(af[m], bfr[n], acc[m][n], 0, 0, 0);
;     if (do_stage) {
; #pragma unroll
;       for (int q = 0; q < NG; ++q) {
;         __builtin_amdgcn_sched_group_barrier(0x008, 3, 0);
;         __builtin_amdgcn_sched_group_barrier(0x010, 1, 0);
;       }
;       __builtin_amdgcn_sched_group_barrier(0x008, 16 - 3 * NG, 0);
;     }
;     __builtin_amdgcn_sched_barrier(0);
; #pragma unroll
;     for (int n = 0; n < 4; ++n) bfr[n] = *reinterpret_cast<const bf16x8*>(sa + boff + (4 + n) * 1024);
; #pragma unroll
;     for (int m = 0; m < 4; ++m)
; #pragma unroll
;       for (int n = 0; n < 4; ++n)
;         acc[m][4 + n] = __builtin_amdgcn_mfma_f32_16x16x32_bf16(af[m], bfr[n], acc[m][4 + n], 0, 0, 0);
;     __builtin_amdgcn_sched_barrier(0);
;   };
;     ...
;   stage(0, 0);
;   stage(1, 1);
;   stage(2, 2);
;   for (int it = 0; it < NK / 4 - 1; ++it) {
;     const int t = it * 4;
;     BIG_SYNC(2 * NG); kstep(t, 0, 3, true);
;     BIG_SYNC(2 * NG); kstep(t + 1, 1, 0, true);
;     BIG_SYNC(2 * NG); kstep(t + 2, 2, 1, true);
;     BIG_SYNC(2 * NG); kstep(t + 3, 3, 2, true);
	v_lshl_add_u64 v[198:199], v[142:143], 0, s[62:63]
	v_mfma_f32_16x16x32_bf16 v[44:47], v[202:205], v[232:235], v[44:47]
	global_load_lds_dwordx4 v[182:183], off
	s_waitcnt lgkmcnt(2)
	v_mfma_f32_16x16x32_bf16 v[120:123], v[186:189], v[236:239], v[120:123]
	ds_read_b128 v[232:235], v168 offset:53248
	v_mfma_f32_16x16x32_bf16 v[104:107], v[190:193], v[236:239], v[104:107]
	v_lshl_add_u64 v[182:183], v[144:145], 0, s[20:21]
	v_mfma_f32_16x16x32_bf16 v[76:79], v[194:197], v[236:239], v[76:79]
	s_add_i32 m0, s100, 0x2000
	v_mfma_f32_16x16x32_bf16 v[40:43], v[202:205], v[236:239], v[40:43]
	global_load_lds_dwordx4 v[182:183], off
	s_waitcnt lgkmcnt(2)
	v_mfma_f32_16x16x32_bf16 v[116:119], v[186:189], v[240:243], v[116:119]
	ds_read_b128 v[236:239], v168 offset:54272
	v_mfma_f32_16x16x32_bf16 v[100:103], v[190:193], v[240:243], v[100:103]
	s_add_i32 m0, s100, 0x4000
	v_mfma_f32_16x16x32_bf16 v[68:71], v[194:197], v[240:243], v[68:71]
	v_lshl_add_u64 v[182:183], v[142:143], 0, s[20:21]
	v_mfma_f32_16x16x32_bf16 v[36:39], v[202:205], v[240:243], v[36:39]
	global_load_lds_dwordx4 v[198:199], off nt
	s_waitcnt lgkmcnt(2)
	v_mfma_f32_16x16x32_bf16 v[112:115], v[186:189], v[244:247], v[112:115]
	ds_read_b128 v[240:243], v168 offset:55296
	v_mfma_f32_16x16x32_bf16 v[96:99], v[190:193], v[244:247], v[96:99]
	s_add_i32 m0, s100, 0x6000
	v_mfma_f32_16x16x32_bf16 v[64:67], v[194:197], v[244:247], v[64:67]
	global_load_lds_dwordx4 v[182:183], off nt
	v_mfma_f32_16x16x32_bf16 v[32:35], v[202:205], v[244:247], v[32:35]
	s_waitcnt lgkmcnt(2)
	v_mfma_f32_16x16x32_bf16 v[92:95], v[186:189], v[232:235], v[92:95]
	ds_read_b128 v[244:247], v168 offset:56320
	v_mfma_f32_16x16x32_bf16 v[60:63], v[190:193], v[232:235], v[60:63]
	ds_read_b128 v[216:219], v210
	v_mfma_f32_16x16x32_bf16 v[28:31], v[194:197], v[232:235], v[28:31]
	ds_read_b128 v[220:223], v210 offset:1024
	v_mfma_f32_16x16x32_bf16 v[12:15], v[202:205], v[232:235], v[12:15]
	ds_read_b128 v[224:227], v210 offset:2048
	s_waitcnt lgkmcnt(5)
	v_mfma_f32_16x16x32_bf16 v[84:87], v[186:189], v[236:239], v[84:87]
	ds_read_b128 v[228:231], v210 offset:3072
	ds_read_b128 v[232:235], v211
	v_mfma_f32_16x16x32_bf16 v[56:59], v[190:193], v[236:239], v[56:59]
	v_mfma_f32_16x16x32_bf16 v[24:27], v[194:197], v[236:239], v[24:27]
	v_mfma_f32_16x16x32_bf16 v[8:11], v[202:205], v[236:239], v[8:11]
	s_waitcnt lgkmcnt(6)
	v_mfma_f32_16x16x32_bf16 v[80:83], v[186:189], v[240:243], v[80:83]
	ds_read_b128 v[236:239], v211 offset:1024
	v_mfma_f32_16x16x32_bf16 v[52:55], v[190:193], v[240:243], v[52:55]
	v_mfma_f32_16x16x32_bf16 v[20:23], v[194:197], v[240:243], v[20:23]
	v_mfma_f32_16x16x32_bf16 v[4:7], v[202:205], v[240:243], v[4:7]
	s_waitcnt lgkmcnt(6)
	v_mfma_f32_16x16x32_bf16 v[72:75], v[186:189], v[244:247], v[72:75]
	ds_read_b128 v[240:243], v211 offset:2048
	v_mfma_f32_16x16x32_bf16 v[48:51], v[190:193], v[244:247], v[48:51]
	v_mfma_f32_16x16x32_bf16 v[16:19], v[194:197], v[244:247], v[16:19]
	v_mfma_f32_16x16x32_bf16 v[0:3], v[202:205], v[244:247], v[0:3]
	ds_read_b128 v[244:247], v211 offset:3072
	s_waitcnt lgkmcnt(3)
	v_mfma_f32_16x16x32_bf16 v[124:127], v[216:219], v[232:235], v[124:127]
	v_lshl_add_u64 v[174:175], v[144:145], 0, s[2:3]
	v_mfma_f32_16x16x32_bf16 v[108:111], v[220:223], v[232:235], v[108:111]
	s_add_i32 m0, s100, 0x8000
	v_mfma_f32_16x16x32_bf16 v[88:91], v[224:227], v[232:235], v[88:91]
	s_waitcnt vmcnt(4)
	s_barrier
	v_lshl_add_u64 v[178:179], v[142:143], 0, s[2:3]
	v_mfma_f32_16x16x32_bf16 v[44:47], v[228:231], v[232:235], v[44:47]
	global_load_lds_dwordx4 v[174:175], off
	s_waitcnt lgkmcnt(2)
	v_mfma_f32_16x16x32_bf16 v[120:123], v[216:219], v[236:239], v[120:123]
	ds_read_b128 v[232:235], v211 offset:4096
	v_mfma_f32_16x16x32_bf16 v[104:107], v[220:223], v[236:239], v[104:107]
	v_lshl_add_u64 v[174:175], v[144:145], 0, s[22:23]
	v_mfma_f32_16x16x32_bf16 v[76:79], v[224:227], v[236:239], v[76:79]
	s_add_i32 m0, s100, 0xa000
	v_mfma_f32_16x16x32_bf16 v[40:43], v[228:231], v[236:239], v[40:43]
	global_load_lds_dwordx4 v[174:175], off
	s_waitcnt lgkmcnt(2)
	v_mfma_f32_16x16x32_bf16 v[116:119], v[216:219], v[240:243], v[116:119]
	ds_read_b128 v[236:239], v211 offset:5120
	v_mfma_f32_16x16x32_bf16 v[100:103], v[220:223], v[240:243], v[100:103]
	s_add_i32 m0, s100, 0xc000
	v_mfma_f32_16x16x32_bf16 v[68:71], v[224:227], v[240:243], v[68:71]
	v_lshl_add_u64 v[174:175], v[142:143], 0, s[22:23]
	v_mfma_f32_16x16x32_bf16 v[36:39], v[228:231], v[240:243], v[36:39]
	global_load_lds_dwordx4 v[178:179], off nt
	s_waitcnt lgkmcnt(2)
	v_mfma_f32_16x16x32_bf16 v[112:115], v[216:219], v[244:247], v[112:115]
	ds_read_b128 v[240:243], v211 offset:6144
	v_mfma_f32_16x16x32_bf16 v[96:99], v[220:223], v[244:247], v[96:99]
	s_add_i32 m0, s100, 0xe000
	v_mfma_f32_16x16x32_bf16 v[64:67], v[224:227], v[244:247], v[64:67]
	global_load_lds_dwordx4 v[174:175], off nt
	v_mfma_f32_16x16x32_bf16 v[32:35], v[228:231], v[244:247], v[32:35]
	s_waitcnt lgkmcnt(2)
	v_mfma_f32_16x16x32_bf16 v[92:95], v[216:219], v[232:235], v[92:95]
	ds_read_b128 v[244:247], v211 offset:7168
	v_mfma_f32_16x16x32_bf16 v[60:63], v[220:223], v[232:235], v[60:63]
	ds_read_b128 v[186:189], v210 offset:32768
	v_mfma_f32_16x16x32_bf16 v[28:31], v[224:227], v[232:235], v[28:31]
	ds_read_b128 v[190:193], v210 offset:33792
	v_mfma_f32_16x16x32_bf16 v[12:15], v[228:231], v[232:235], v[12:15]
	ds_read_b128 v[194:197], v210 offset:34816
	s_waitcnt lgkmcnt(5)
	v_mfma_f32_16x16x32_bf16 v[84:87], v[216:219], v[236:239], v[84:87]
	ds_read_b128 v[202:205], v210 offset:35840
	ds_read_b128 v[232:235], v211 offset:32768
	v_mfma_f32_16x16x32_bf16 v[56:59], v[220:223], v[236:239], v[56:59]
	v_mfma_f32_16x16x32_bf16 v[24:27], v[224:227], v[236:239], v[24:27]
	v_mfma_f32_16x16x32_bf16 v[8:11], v[228:231], v[236:239], v[8:11]
	s_waitcnt lgkmcnt(6)
	v_mfma_f32_16x16x32_bf16 v[80:83], v[216:219], v[240:243], v[80:83]
	ds_read_b128 v[236:239], v211 offset:33792
	v_mfma_f32_16x16x32_bf16 v[52:55], v[220:223], v[240:243], v[52:55]
	v_mfma_f32_16x16x32_bf16 v[20:23], v[224:227], v[240:243], v[20:23]
	v_mfma_f32_16x16x32_bf16 v[4:7], v[228:231], v[240:243], v[4:7]
	s_waitcnt lgkmcnt(6)
	v_mfma_f32_16x16x32_bf16 v[72:75], v[216:219], v[244:247], v[72:75]
	ds_read_b128 v[240:243], v211 offset:34816
	v_mfma_f32_16x16x32_bf16 v[48:51], v[220:223], v[244:247], v[48:51]
	v_mfma_f32_16x16x32_bf16 v[16:19], v[224:227], v[244:247], v[16:19]
	v_mfma_f32_16x16x32_bf16 v[0:3], v[228:231], v[244:247], v[0:3]
	ds_read_b128 v[244:247], v211 offset:35840
	s_waitcnt lgkmcnt(3)
	v_mfma_f32_16x16x32_bf16 v[124:127], v[186:189], v[232:235], v[124:127]
	v_lshl_add_u64 v[248:249], v[144:145], 0, s[54:55]
	v_mfma_f32_16x16x32_bf16 v[108:111], v[190:193], v[232:235], v[108:111]
	s_add_i32 m0, s100, 0x10000
	v_mfma_f32_16x16x32_bf16 v[88:91], v[194:197], v[232:235], v[88:91]
	s_waitcnt vmcnt(4)
	s_barrier
; #define BIG_SYNC(N)                                              \
;   asm volatile("s_waitcnt vmcnt(%0)" ::"n"(N) : "memory");       \
;   __builtin_amdgcn_s_barrier();                                  \
;   asm volatile("" ::: "memory");                                 \
;   __builtin_amdgcn_sched_barrier(0);
; template <int NK, bool BNT = false> ...
;     ...
;   auto kstep = [&](int T, int cur, int nxt, bool do_stage) {
;     const unsigned char* sa = smem + cur * BIG_STAGE;
;     bf16x8 af[4], bfr[4];
; #pragma unroll
;     for (int m = 0; m < 4; ++m) af[m] = *reinterpret_cast<const bf16x8*>(sa + aoff + m * 1024);
; #pragma unroll
;     for (int n = 0; n < 4; ++n) bfr[n] = *reinterpret_cast<const bf16x8*>(sa + boff + n * 1024);
;     __builtin_amdgcn_sched_barrier(0);
;     if (do_stage) stage(T + 3, nxt);
; #pragma unroll
;     for (int m = 0; m < 4; ++m)
; #pragma unroll
;       for (int n = 0; n < 4; ++n) acc[m][n] = __builtin_amdgcn_mfma_f32_16x16x32_bf16(af[m], bfr[n], acc[m][n], 0, 0, 0);
;     if (do_stage) {
; #pragma unroll
;       for (int q = 0; q < NG; ++q) {
;         __builtin_amdgcn_sched_group_barrier(0x008, 3, 0);
;         __builtin_amdgcn_sched_group_barrier(0x010, 1, 0);
;       }
;       __builtin_amdgcn_sched_group_barrier(0x008, 16 - 3 * NG, 0);
;     }
;     __builtin_amdgcn_sched_barrier(0);
; #pragma unroll
;     for (int n = 0; n < 4; ++n) bfr[n] = *reinterpret_cast<const bf16x8*>(sa + boff + (4 + n) * 1024);
; #pragma unroll
;     for (int m = 0; m < 4; ++m)
; #pragma unroll
;       for (int n = 0; n < 4; ++n)
;         acc[m][4 + n] = __builtin_amdgcn_mfma_f32_16x16x32_bf16(af[m], bfr[n], acc[m][4 + n], 0, 0, 0);
;     __builtin_amdgcn_sched_barrier(0);
;   };
;     ...
;   stage(0, 0);
;   stage(1, 1);
;   stage(2, 2);
;   for (int it = 0; it < NK / 4 - 1; ++it) {
;     const int t = it * 4;
;     BIG_SYNC(2 * NG); kstep(t, 0, 3, true);
;     BIG_SYNC(2 * NG); kstep(t + 1, 1, 0, true);
;     BIG_SYNC(2 * NG); kstep(t + 2, 2, 1, true);
;     BIG_SYNC(2 * NG); kstep(t + 3, 3, 2, true);
;   }
;   BIG_SYNC(2 * NG); kstep(NK - 4, 0, 3, true);
;   BIG_SYNC(2 * NG); kstep(NK - 3, 1, 0, false);
;   BIG_SYNC(NG);     kstep(NK - 2, 2, 0, false);
;   BIG_SYNC(0);      kstep(NK - 1, 3, 0, false);
	v_lshl_add_u64 v[144:145], v[144:145], 0, s[24:25]
	v_mfma_f32_16x16x32_bf16 v[44:47], v[202:205], v[232:235], v[44:47]
	v_lshl_add_u64 v[250:251], v[142:143], 0, s[54:55]
	s_waitcnt lgkmcnt(2)
	v_mfma_f32_16x16x32_bf16 v[120:123], v[186:189], v[236:239], v[120:123]
	ds_read_b128 v[232:235], v211 offset:36864
	v_mfma_f32_16x16x32_bf16 v[104:107], v[190:193], v[236:239], v[104:107]
	v_lshl_add_u64 v[142:143], v[142:143], 0, s[24:25]
	v_mfma_f32_16x16x32_bf16 v[76:79], v[194:197], v[236:239], v[76:79]
	global_load_lds_dwordx4 v[248:249], off
	v_mfma_f32_16x16x32_bf16 v[40:43], v[202:205], v[236:239], v[40:43]
	s_add_i32 m0, s100, 0x12000
	s_waitcnt lgkmcnt(2)
	v_mfma_f32_16x16x32_bf16 v[116:119], v[186:189], v[240:243], v[116:119]
	ds_read_b128 v[236:239], v211 offset:37888
	v_mfma_f32_16x16x32_bf16 v[100:103], v[190:193], v[240:243], v[100:103]
	global_load_lds_dwordx4 v[144:145], off
	v_mfma_f32_16x16x32_bf16 v[68:71], v[194:197], v[240:243], v[68:71]
	s_add_i32 m0, s100, 0x14000
	v_mfma_f32_16x16x32_bf16 v[36:39], v[202:205], v[240:243], v[36:39]
	global_load_lds_dwordx4 v[250:251], off nt
	s_waitcnt lgkmcnt(2)
	v_mfma_f32_16x16x32_bf16 v[112:115], v[186:189], v[244:247], v[112:115]
	ds_read_b128 v[240:243], v211 offset:38912
	v_mfma_f32_16x16x32_bf16 v[96:99], v[190:193], v[244:247], v[96:99]
	s_add_i32 m0, s100, 0x16000
	v_mfma_f32_16x16x32_bf16 v[64:67], v[194:197], v[244:247], v[64:67]
	global_load_lds_dwordx4 v[142:143], off nt
	v_mfma_f32_16x16x32_bf16 v[32:35], v[202:205], v[244:247], v[32:35]
	s_waitcnt lgkmcnt(2)
	v_mfma_f32_16x16x32_bf16 v[92:95], v[186:189], v[232:235], v[92:95]
	ds_read_b128 v[244:247], v211 offset:39936
	v_mfma_f32_16x16x32_bf16 v[60:63], v[190:193], v[232:235], v[60:63]
	ds_read_b128 v[216:219], v167
	v_mfma_f32_16x16x32_bf16 v[28:31], v[194:197], v[232:235], v[28:31]
	ds_read_b128 v[220:223], v167 offset:1024
	v_mfma_f32_16x16x32_bf16 v[12:15], v[202:205], v[232:235], v[12:15]
	ds_read_b128 v[224:227], v167 offset:2048
	s_waitcnt lgkmcnt(5)
	v_mfma_f32_16x16x32_bf16 v[84:87], v[186:189], v[236:239], v[84:87]
	ds_read_b128 v[228:231], v167 offset:3072
	ds_read_b128 v[232:235], v168 offset:16384
	v_mfma_f32_16x16x32_bf16 v[56:59], v[190:193], v[236:239], v[56:59]
	v_mfma_f32_16x16x32_bf16 v[24:27], v[194:197], v[236:239], v[24:27]
	v_mfma_f32_16x16x32_bf16 v[8:11], v[202:205], v[236:239], v[8:11]
	s_waitcnt lgkmcnt(6)
	v_mfma_f32_16x16x32_bf16 v[80:83], v[186:189], v[240:243], v[80:83]
	ds_read_b128 v[236:239], v168 offset:17408
	v_mfma_f32_16x16x32_bf16 v[52:55], v[190:193], v[240:243], v[52:55]
	v_mfma_f32_16x16x32_bf16 v[20:23], v[194:197], v[240:243], v[20:23]
	v_mfma_f32_16x16x32_bf16 v[4:7], v[202:205], v[240:243], v[4:7]
	s_waitcnt lgkmcnt(6)
	v_mfma_f32_16x16x32_bf16 v[72:75], v[186:189], v[244:247], v[72:75]
	ds_read_b128 v[240:243], v168 offset:18432
	v_mfma_f32_16x16x32_bf16 v[48:51], v[190:193], v[244:247], v[48:51]
	v_mfma_f32_16x16x32_bf16 v[16:19], v[194:197], v[244:247], v[16:19]
	v_mfma_f32_16x16x32_bf16 v[0:3], v[202:205], v[244:247], v[0:3]
	ds_read_b128 v[244:247], v168 offset:19456
	s_add_u32 s36, s36, 0x8000
	s_addc_u32 s37, s37, 0
	s_cmp_lg_u32 s36, 0xf8000
	s_cbranch_scc1 .LBB0_264
	v_add_u32_e32 v162, 0x10000, v167
	v_or_b32_e32 v163, 0x10000, v169
	v_add_u32_e32 v164, 0x10400, v169
	v_add_u32_e32 v165, 0x10800, v169
	v_add_u32_e32 v172, 0x10c00, v169
	v_add_u32_e32 v173, 0x11000, v169
	v_add_u32_e32 v174, 0x11400, v169
	v_add_u32_e32 v175, 0x11800, v169
	v_add_u32_e32 v178, 0x11c00, v169
	v_add_u32_e32 v176, 0x18000, v167
	v_or_b32_e32 v179, 0x18000, v169
	v_add_u32_e32 v180, 0x18400, v169
	v_add_u32_e32 v181, 0x18800, v169
	v_add_u32_e32 v182, 0x18c00, v169
	v_add_u32_e32 v142, 0x19000, v169
	v_add_u32_e32 v143, 0x19400, v169
	v_add_u32_e32 v144, 0x19800, v169
	v_add_u32_e32 v145, 0x19c00, v169
	s_waitcnt lgkmcnt(3)
	v_mfma_f32_16x16x32_bf16 v[124:127], v[216:219], v[232:235], v[124:127]
	s_sext_i32_i8 s13, s14
	v_mfma_f32_16x16x32_bf16 v[108:111], v[220:223], v[232:235], v[108:111]
	s_mov_b64 s[18:19], 0xfe000
	v_mfma_f32_16x16x32_bf16 v[88:91], v[224:227], v[232:235], v[88:91]
	s_waitcnt vmcnt(4)
	s_barrier
	v_readfirstlane_b32 s14, v158
	v_mfma_f32_16x16x32_bf16 v[44:47], v[228:231], v[232:235], v[44:47]
	v_lshl_add_u64 v[150:151], v[130:131], 0, s[18:19]
	s_waitcnt lgkmcnt(2)
	v_mfma_f32_16x16x32_bf16 v[120:123], v[216:219], v[236:239], v[120:123]
	ds_read_b128 v[232:235], v168 offset:20480
	v_mfma_f32_16x16x32_bf16 v[104:107], v[220:223], v[236:239], v[104:107]
	v_lshl_add_u64 v[198:199], v[128:129], 0, s[18:19]
	v_mfma_f32_16x16x32_bf16 v[76:79], v[224:227], v[236:239], v[76:79]
	s_mov_b32 m0, s14
	v_mfma_f32_16x16x32_bf16 v[40:43], v[228:231], v[236:239], v[40:43]
	s_mov_b64 s[18:19], 0x1fe000
	s_waitcnt lgkmcnt(2)
	v_mfma_f32_16x16x32_bf16 v[116:119], v[216:219], v[240:243], v[116:119]
	ds_read_b128 v[236:239], v168 offset:21504
	v_mfma_f32_16x16x32_bf16 v[100:103], v[220:223], v[240:243], v[100:103]
	v_readfirstlane_b32 s14, v159
	v_mfma_f32_16x16x32_bf16 v[68:71], v[224:227], v[240:243], v[68:71]
	v_lshl_add_u64 v[130:131], v[130:131], 0, s[18:19]
	v_mfma_f32_16x16x32_bf16 v[36:39], v[228:231], v[240:243], v[36:39]
	v_lshl_add_u64 v[128:129], v[128:129], 0, s[18:19]
	s_waitcnt lgkmcnt(2)
	v_mfma_f32_16x16x32_bf16 v[112:115], v[216:219], v[244:247], v[112:115]
	ds_read_b128 v[240:243], v168 offset:22528
	v_mfma_f32_16x16x32_bf16 v[96:99], v[220:223], v[244:247], v[96:99]
	global_load_lds_dwordx4 v[150:151], off
	v_mfma_f32_16x16x32_bf16 v[64:67], v[224:227], v[244:247], v[64:67]
	s_mov_b32 m0, s14
	v_mfma_f32_16x16x32_bf16 v[32:35], v[228:231], v[244:247], v[32:35]
	v_readfirstlane_b32 s14, v160
	s_waitcnt lgkmcnt(2)
; #define BIG_SYNC(N)                                              \
;   asm volatile("s_waitcnt vmcnt(%0)" ::"n"(N) : "memory");       \
;   __builtin_amdgcn_s_barrier();                                  \
;   asm volatile("" ::: "memory");                                 \
;   __builtin_amdgcn_sched_barrier(0);
; template <int NK, bool BNT = false> ...
;     ...
;   auto kstep = [&](int T, int cur, int nxt, bool do_stage) {
;     const unsigned char* sa = smem + cur * BIG_STAGE;
;     bf16x8 af[4], bfr[4];
; #pragma unroll
;     for (int m = 0; m < 4; ++m) af[m] = *reinterpret_cast<const bf16x8*>(sa + aoff + m * 1024);
; #pragma unroll
;     for (int n = 0; n < 4; ++n) bfr[n] = *reinterpret_cast<const bf16x8*>(sa + boff + n * 1024);
;     __builtin_amdgcn_sched_barrier(0);
;     if (do_stage) stage(T + 3, nxt);
; #pragma unroll
;     for (int m = 0; m < 4; ++m)
; #pragma unroll
;       for (int n = 0; n < 4; ++n) acc[m][n] = __builtin_amdgcn_mfma_f32_16x16x32_bf16(af[m], bfr[n], acc[m][n], 0, 0, 0);
;     if (do_stage) {
; #pragma unroll
;       for (int q = 0; q < NG; ++q) {
;         __builtin_amdgcn_sched_group_barrier(0x008, 3, 0);
;         __builtin_amdgcn_sched_group_barrier(0x010, 1, 0);
;       }
;       __builtin_amdgcn_sched_group_barrier(0x008, 16 - 3 * NG, 0);
;     }
;     __builtin_amdgcn_sched_barrier(0);
; #pragma unroll
;     for (int n = 0; n < 4; ++n) bfr[n] = *reinterpret_cast<const bf16x8*>(sa + boff + (4 + n) * 1024);
; #pragma unroll
;     for (int m = 0; m < 4; ++m)
; #pragma unroll
;       for (int n = 0; n < 4; ++n)
;         acc[m][4 + n] = __builtin_amdgcn_mfma_f32_16x16x32_bf16(af[m], bfr[n], acc[m][4 + n], 0, 0, 0);
;     __builtin_amdgcn_sched_barrier(0);
;   };
;     ...
;   stage(0, 0);
;   stage(1, 1);
;   stage(2, 2);
;   for (int it = 0; it < NK / 4 - 1; ++it) {
;     const int t = it * 4;
;     BIG_SYNC(2 * NG); kstep(t, 0, 3, true);
;     BIG_SYNC(2 * NG); kstep(t + 1, 1, 0, true);
;     BIG_SYNC(2 * NG); kstep(t + 2, 2, 1, true);
;     BIG_SYNC(2 * NG); kstep(t + 3, 3, 2, true);
;   }
;   BIG_SYNC(2 * NG); kstep(NK - 4, 0, 3, true);
;   BIG_SYNC(2 * NG); kstep(NK - 3, 1, 0, false);
;   BIG_SYNC(NG);     kstep(NK - 2, 2, 0, false);
;   BIG_SYNC(0);      kstep(NK - 1, 3, 0, false);
	v_mfma_f32_16x16x32_bf16 v[92:95], v[216:219], v[232:235], v[92:95]
	ds_read_b128 v[244:247], v168 offset:23552
	v_mfma_f32_16x16x32_bf16 v[60:63], v[220:223], v[232:235], v[60:63]
	ds_read_b128 v[186:189], v167 offset:32768
	v_mfma_f32_16x16x32_bf16 v[28:31], v[224:227], v[232:235], v[28:31]
	ds_read_b128 v[190:193], v167 offset:33792
	v_mfma_f32_16x16x32_bf16 v[12:15], v[228:231], v[232:235], v[12:15]
	ds_read_b128 v[194:197], v167 offset:34816
	s_waitcnt lgkmcnt(5)
	v_mfma_f32_16x16x32_bf16 v[84:87], v[216:219], v[236:239], v[84:87]
	ds_read_b128 v[202:205], v167 offset:35840
	ds_read_b128 v[232:235], v168 offset:49152
	v_mfma_f32_16x16x32_bf16 v[56:59], v[220:223], v[236:239], v[56:59]
	global_load_lds_dwordx4 v[130:131], off
	v_mfma_f32_16x16x32_bf16 v[24:27], v[224:227], v[236:239], v[24:27]
	s_mov_b32 m0, s14
	v_mfma_f32_16x16x32_bf16 v[8:11], v[228:231], v[236:239], v[8:11]
	v_readfirstlane_b32 s14, v161
	s_waitcnt lgkmcnt(6)
	v_mfma_f32_16x16x32_bf16 v[80:83], v[216:219], v[240:243], v[80:83]
	ds_read_b128 v[236:239], v168 offset:50176
	v_mfma_f32_16x16x32_bf16 v[52:55], v[220:223], v[240:243], v[52:55]
	global_load_lds_dwordx4 v[198:199], off nt
	v_mfma_f32_16x16x32_bf16 v[20:23], v[224:227], v[240:243], v[20:23]
	s_mov_b32 m0, s14
	v_mfma_f32_16x16x32_bf16 v[4:7], v[228:231], v[240:243], v[4:7]
	global_load_lds_dwordx4 v[128:129], off nt
	s_waitcnt lgkmcnt(6)
	v_mfma_f32_16x16x32_bf16 v[72:75], v[216:219], v[244:247], v[72:75]
	ds_read_b128 v[240:243], v168 offset:51200
	v_mfma_f32_16x16x32_bf16 v[48:51], v[220:223], v[244:247], v[48:51]
	v_mfma_f32_16x16x32_bf16 v[16:19], v[224:227], v[244:247], v[16:19]
	v_mfma_f32_16x16x32_bf16 v[0:3], v[228:231], v[244:247], v[0:3]
	ds_read_b128 v[244:247], v168 offset:52224
	s_waitcnt lgkmcnt(3)
	v_mfma_f32_16x16x32_bf16 v[124:127], v[186:189], v[232:235], v[124:127]
	v_mfma_f32_16x16x32_bf16 v[108:111], v[190:193], v[232:235], v[108:111]
	v_mfma_f32_16x16x32_bf16 v[88:91], v[194:197], v[232:235], v[88:91]
	v_mfma_f32_16x16x32_bf16 v[44:47], v[202:205], v[232:235], v[44:47]
	s_waitcnt vmcnt(4)
	s_barrier
	s_waitcnt lgkmcnt(2)
	v_mfma_f32_16x16x32_bf16 v[120:123], v[186:189], v[236:239], v[120:123]
	ds_read_b128 v[232:235], v168 offset:53248
	v_mfma_f32_16x16x32_bf16 v[104:107], v[190:193], v[236:239], v[104:107]
	v_mfma_f32_16x16x32_bf16 v[76:79], v[194:197], v[236:239], v[76:79]
	v_mfma_f32_16x16x32_bf16 v[40:43], v[202:205], v[236:239], v[40:43]
	s_waitcnt lgkmcnt(2)
	v_mfma_f32_16x16x32_bf16 v[116:119], v[186:189], v[240:243], v[116:119]
	ds_read_b128 v[236:239], v168 offset:54272
	v_mfma_f32_16x16x32_bf16 v[100:103], v[190:193], v[240:243], v[100:103]
	v_mfma_f32_16x16x32_bf16 v[68:71], v[194:197], v[240:243], v[68:71]
	v_mfma_f32_16x16x32_bf16 v[36:39], v[202:205], v[240:243], v[36:39]
	s_waitcnt lgkmcnt(2)
	v_mfma_f32_16x16x32_bf16 v[112:115], v[186:189], v[244:247], v[112:115]
	ds_read_b128 v[240:243], v168 offset:55296
	v_mfma_f32_16x16x32_bf16 v[96:99], v[190:193], v[244:247], v[96:99]
	v_mfma_f32_16x16x32_bf16 v[64:67], v[194:197], v[244:247], v[64:67]
	v_mfma_f32_16x16x32_bf16 v[32:35], v[202:205], v[244:247], v[32:35]
	s_waitcnt lgkmcnt(2)
	v_mfma_f32_16x16x32_bf16 v[92:95], v[186:189], v[232:235], v[92:95]
	ds_read_b128 v[244:247], v168 offset:56320
	v_mfma_f32_16x16x32_bf16 v[60:63], v[190:193], v[232:235], v[60:63]
	v_mfma_f32_16x16x32_bf16 v[28:31], v[194:197], v[232:235], v[28:31]
	v_mfma_f32_16x16x32_bf16 v[12:15], v[202:205], v[232:235], v[12:15]
	s_waitcnt lgkmcnt(2)
	v_mfma_f32_16x16x32_bf16 v[84:87], v[186:189], v[236:239], v[84:87]
	v_mfma_f32_16x16x32_bf16 v[56:59], v[190:193], v[236:239], v[56:59]
	v_mfma_f32_16x16x32_bf16 v[24:27], v[194:197], v[236:239], v[24:27]
	v_mfma_f32_16x16x32_bf16 v[8:11], v[202:205], v[236:239], v[8:11]
	s_waitcnt lgkmcnt(1)
	v_mfma_f32_16x16x32_bf16 v[80:83], v[186:189], v[240:243], v[80:83]
	v_mfma_f32_16x16x32_bf16 v[52:55], v[190:193], v[240:243], v[52:55]
	v_mfma_f32_16x16x32_bf16 v[20:23], v[194:197], v[240:243], v[20:23]
	v_mfma_f32_16x16x32_bf16 v[4:7], v[202:205], v[240:243], v[4:7]
	s_waitcnt lgkmcnt(0)
	v_mfma_f32_16x16x32_bf16 v[72:75], v[186:189], v[244:247], v[72:75]
	v_mfma_f32_16x16x32_bf16 v[48:51], v[190:193], v[244:247], v[48:51]
	v_mfma_f32_16x16x32_bf16 v[16:19], v[194:197], v[244:247], v[16:19]
	v_mfma_f32_16x16x32_bf16 v[0:3], v[202:205], v[244:247], v[0:3]
	v_mov_b32_e32 v186, 0xf149f2ca
	v_mov_b32_e32 v187, 0x3c0881c4
	v_mov_b32_e32 v188, 0xbab64f3b
	v_mov_b32_e32 v189, 0x24800
	v_mov_b32_e32 v190, 1
	v_mov_b32_e32 v191, 0x24804
	v_mov_b32_e32 v192, 0xfcf
	v_mov_b32_e32 v193, 0x7cf
	v_mov_b32_e32 v194, 0xfdf
	v_mov_b32_e32 v195, 0x7df
	v_mov_b32_e32 v196, 0xfef
	v_mov_b32_e32 v197, 0x7ef
	v_mov_b32_e32 v198, 0xfff
	v_mov_b32_e32 v199, 0x7ff
	v_mov_b32_e32 v200, 0x20000
	v_mov_b32_e32 v201, 0xf8f
	v_mov_b32_e32 v202, 0x78f
	v_mov_b32_e32 v203, 0xf9f
	v_mov_b32_e32 v204, 0x79f
	v_mov_b32_e32 v205, 0xfaf
	v_mov_b32_e32 v210, 0x7f800000
	v_not_b32_e32 v211, 63
	v_not_b32_e32 v212, 31
	v_mov_b32_e32 v213, 0x7fc00000
	s_waitcnt vmcnt(4)
	s_barrier
; template <int NK, bool BNT = false> ...
;     ...
;   auto kstep = [&](int T, int cur, int nxt, bool do_stage) {
;     const unsigned char* sa = smem + cur * BIG_STAGE;
;     bf16x8 af[4], bfr[4];
; #pragma unroll
;     for (int m = 0; m < 4; ++m) af[m] = *reinterpret_cast<const bf16x8*>(sa + aoff + m * 1024);
; #pragma unroll
;     for (int n = 0; n < 4; ++n) bfr[n] = *reinterpret_cast<const bf16x8*>(sa + boff + n * 1024);
;     __builtin_amdgcn_sched_barrier(0);
;     if (do_stage) stage(T + 3, nxt);
; #pragma unroll
;     for (int m = 0; m < 4; ++m)
; #pragma unroll
;       for (int n = 0; n < 4; ++n) acc[m][n] = __builtin_amdgcn_mfma_f32_16x16x32_bf16(af[m], bfr[n], acc[m][n], 0, 0, 0);
;     if (do_stage) {
; #pragma unroll
;       for (int q = 0; q < NG; ++q) {
;         __builtin_amdgcn_sched_group_barrier(0x008, 3, 0);
;         __builtin_amdgcn_sched_group_barrier(0x010, 1, 0);
;       }
;       __builtin_amdgcn_sched_group_barrier(0x008, 16 - 3 * NG, 0);
;     }
;     __builtin_amdgcn_sched_barrier(0);
; #pragma unroll
;     for (int n = 0; n < 4; ++n) bfr[n] = *reinterpret_cast<const bf16x8*>(sa + boff + (4 + n) * 1024);
; #pragma unroll
;     for (int m = 0; m < 4; ++m)
; #pragma unroll
;       for (int n = 0; n < 4; ++n)
;         acc[m][4 + n] = __builtin_amdgcn_mfma_f32_16x16x32_bf16(af[m], bfr[n], acc[m][4 + n], 0, 0, 0);
;     __builtin_amdgcn_sched_barrier(0);
	ds_read_b128 v[128:131], v162
	ds_read_b128 v[138:141], v162 offset:1024
	ds_read_b128 v[146:149], v162 offset:2048
	ds_read_b128 v[154:157], v162 offset:3072
	ds_read_b128 v[158:161], v163
	ds_read_b128 v[216:219], v164
	ds_read_b128 v[162:165], v165
	ds_read_b128 v[220:223], v172
	s_waitcnt lgkmcnt(0)
	v_mfma_f32_16x16x32_bf16 v[124:127], v[128:131], v[158:161], v[124:127]
	v_mfma_f32_16x16x32_bf16 v[116:119], v[128:131], v[162:165], v[116:119]
	v_mfma_f32_16x16x32_bf16 v[112:115], v[128:131], v[220:223], v[112:115]
	v_mfma_f32_16x16x32_bf16 v[104:107], v[138:141], v[216:219], v[104:107]
	v_mfma_f32_16x16x32_bf16 v[100:103], v[138:141], v[162:165], v[100:103]
	v_mfma_f32_16x16x32_bf16 v[96:99], v[138:141], v[220:223], v[96:99]
	v_mfma_f32_16x16x32_bf16 v[68:71], v[146:149], v[162:165], v[68:71]
	v_mfma_f32_16x16x32_bf16 v[64:67], v[146:149], v[220:223], v[64:67]
	v_mfma_f32_16x16x32_bf16 v[44:47], v[154:157], v[158:161], v[44:47]
	v_mfma_f32_16x16x32_bf16 v[40:43], v[154:157], v[216:219], v[40:43]
	v_mfma_f32_16x16x32_bf16 v[36:39], v[154:157], v[162:165], v[36:39]
	v_mfma_f32_16x16x32_bf16 v[32:35], v[154:157], v[220:223], v[32:35]
	v_mfma_f32_16x16x32_bf16 v[120:123], v[128:131], v[216:219], v[120:123]
	v_mfma_f32_16x16x32_bf16 v[224:227], v[138:141], v[158:161], v[108:111]
	v_mfma_f32_16x16x32_bf16 v[228:231], v[146:149], v[158:161], v[88:91]
	v_mfma_f32_16x16x32_bf16 v[232:235], v[146:149], v[216:219], v[76:79]
	s_nop 2
	ds_read_b128 v[76:79], v173
	ds_read_b128 v[88:91], v174
	s_waitcnt lgkmcnt(0)
	v_mfma_f32_16x16x32_bf16 v[158:161], v[128:131], v[76:79], v[92:95]
	s_nop 2
	ds_read_b128 v[92:95], v178
	v_mfma_f32_16x16x32_bf16 v[162:165], v[128:131], v[88:91], v[84:87]
	s_nop 2
	ds_read_b128 v[84:87], v175
	s_waitcnt lgkmcnt(0)
	v_mfma_f32_16x16x32_bf16 v[172:175], v[128:131], v[84:87], v[80:83]
	v_mfma_f32_16x16x32_bf16 v[128:131], v[128:131], v[92:95], v[72:75]
	v_mfma_f32_16x16x32_bf16 v[216:219], v[138:141], v[76:79], v[60:63]
	v_mfma_f32_16x16x32_bf16 v[220:223], v[138:141], v[88:91], v[56:59]
	v_mfma_f32_16x16x32_bf16 v[52:55], v[138:141], v[84:87], v[52:55]
	v_mfma_f32_16x16x32_bf16 v[48:51], v[138:141], v[92:95], v[48:51]
	v_mfma_f32_16x16x32_bf16 v[138:141], v[146:149], v[76:79], v[28:31]
	v_mfma_f32_16x16x32_bf16 v[236:239], v[146:149], v[88:91], v[24:27]
	v_mfma_f32_16x16x32_bf16 v[20:23], v[146:149], v[84:87], v[20:23]
	v_mfma_f32_16x16x32_bf16 v[16:19], v[146:149], v[92:95], v[16:19]
	v_mfma_f32_16x16x32_bf16 v[146:149], v[154:157], v[76:79], v[12:15]
	v_mfma_f32_16x16x32_bf16 v[0:3], v[154:157], v[92:95], v[0:3]
	v_mfma_f32_16x16x32_bf16 v[240:243], v[154:157], v[88:91], v[8:11]
	v_mfma_f32_16x16x32_bf16 v[244:247], v[154:157], v[84:87], v[4:7]
	s_waitcnt vmcnt(0)
	s_barrier
	s_nop 1
	ds_read_b128 v[4:7], v176
	ds_read_b128 v[8:11], v176 offset:1024
	ds_read_b128 v[154:157], v176 offset:2048
	ds_read_b128 v[12:15], v179
	ds_read_b128 v[24:27], v180
	ds_read_b128 v[28:31], v181
	ds_read_b128 v[56:59], v182
	ds_read_b128 v[248:251], v176 offset:3072
	s_waitcnt lgkmcnt(0)
	v_mfma_f32_16x16x32_bf16 v[108:111], v[4:7], v[24:27], v[120:123]
	v_mfma_f32_16x16x32_bf16 v[92:95], v[4:7], v[28:31], v[116:119]
	v_mfma_f32_16x16x32_bf16 v[76:79], v[4:7], v[56:59], v[112:115]
	v_mfma_f32_16x16x32_bf16 v[104:107], v[8:11], v[24:27], v[104:107]
	v_mfma_f32_16x16x32_bf16 v[88:91], v[8:11], v[28:31], v[100:103]
	v_mfma_f32_16x16x32_bf16 v[72:75], v[8:11], v[56:59], v[96:99]
	v_mfma_f32_16x16x32_bf16 v[100:103], v[154:157], v[24:27], v[232:235]
	v_mfma_f32_16x16x32_bf16 v[84:87], v[154:157], v[28:31], v[68:71]
	v_mfma_f32_16x16x32_bf16 v[68:71], v[154:157], v[56:59], v[64:67]
	v_mfma_f32_16x16x32_bf16 v[116:119], v[248:251], v[12:15], v[44:47]
	v_mfma_f32_16x16x32_bf16 v[96:99], v[248:251], v[24:27], v[40:43]
	v_mfma_f32_16x16x32_bf16 v[80:83], v[248:251], v[28:31], v[36:39]
	v_mfma_f32_16x16x32_bf16 v[64:67], v[248:251], v[56:59], v[32:35]
	v_mfma_f32_16x16x32_bf16 v[178:181], v[4:7], v[12:15], v[124:127]
	v_mfma_f32_16x16x32_bf16 v[224:227], v[8:11], v[12:15], v[224:227]
	v_mfma_f32_16x16x32_bf16 v[120:123], v[154:157], v[12:15], v[228:231]
	ds_read_b128 v[32:35], v142
	ds_read_b128 v[112:115], v143
	ds_read_b128 v[124:127], v144
	ds_read_b128 v[142:145], v145
	s_waitcnt lgkmcnt(0)
; __device__ __forceinline__ float bf2f(bf16_t b) { return __uint_as_float(((unsigned)b) << 16); }
; __device__ __forceinline__ int widen_off(int fq) { return ((fq & 1) << 4) + ((fq >> 1) << 3); }
; template <int MODE, int NSUB>
; __device__ __forceinline__ void epilogue(const Params& p, int layer, f32x4 (&acc)[4][NSUB], int tm, int tn, int g,
;                                          const float* s_rstd, const int tid_in) {
;     ...
;   } else if constexpr (MODE == EPI_RES) {
;     const int fb = tm * 128 + wr * 64 + fq * 4;
;     const int tb = tn * (NSUB * 32) + wc * (NSUB * 16) + fr;
;     const int fw = tm * 128 + wr * 64 + widen_off(fq);
;     u32x4 curw[2], nxtw[2];
; #pragma unroll
;     for (int mp = 0; mp < 2; ++mp) curw[mp] = *reinterpret_cast<const u32x4*>(p.xb + blk(tb, fw + mp * 32, 32));
; #pragma unroll
;     for (int n = 0; n < NSUB; ++n) {
;       if (n + 1 < NSUB) {
; #pragma unroll
;         for (int mp = 0; mp < 2; ++mp) nxtw[mp] = *reinterpret_cast<const u32x4*>(p.xb + blk(tb + (n + 1) * 16, fw + mp * 32, 32));
;       }
;       bf16x4 cur[4];
;       unwiden_pair(curw[0], cur[0], cur[1]);
;       unwiden_pair(curw[1], cur[2], cur[3]);
;       const int t = tb + n * 16;
;       float ss = 0.f;
; #pragma unroll
;       for (int mp = 0; mp < 2; ++mp) {
;         bf16x4 pk[2];
; #pragma unroll
;         for (int h2 = 0; h2 < 2; ++h2) {
;           const int m = mp * 2 + h2;
;           const float x0 = bf2f((bf16_t)cur[m][0]) + acc[m][n][0], x1 = bf2f((bf16_t)cur[m][1]) + acc[m][n][1];
;           const float x2 = bf2f((bf16_t)cur[m][2]) + acc[m][n][2], x3 = bf2f((bf16_t)cur[m][3]) + acc[m][n][3];
;           ss += x0 * x0 + x1 * x1 + x2 * x2 + x3 * x3;
;           pk[h2] = pack4(x0, x1, x2, x3);
;         }
;         const int f = tm * 128 + wr * 64 + mp * 32 + widen_off(fq);
;         *reinterpret_cast<u32x4*>(p.xb + blk(t, f, 32)) = widen_pair(pk[0], pk[1]);
;       }
;       ss = red_fq(ss);
;       if (fq == 0) p.part[(long)t * 16 + tm * 2 + wr] = ss;
;       curw[0] = nxtw[0];
;       curw[1] = nxtw[1];
;     }
	v_mfma_f32_16x16x32_bf16 v[60:63], v[4:7], v[32:35], v[158:161]
	v_mfma_f32_16x16x32_bf16 v[44:47], v[4:7], v[112:115], v[162:165]
	v_mfma_f32_16x16x32_bf16 v[28:31], v[4:7], v[124:127], v[172:175]
	v_mfma_f32_16x16x32_bf16 v[12:15], v[4:7], v[142:145], v[128:131]
	v_mfma_f32_16x16x32_bf16 v[56:59], v[8:11], v[32:35], v[216:219]
	v_mfma_f32_16x16x32_bf16 v[40:43], v[8:11], v[112:115], v[220:223]
	v_mfma_f32_16x16x32_bf16 v[24:27], v[8:11], v[124:127], v[52:55]
	v_mfma_f32_16x16x32_bf16 v[8:11], v[8:11], v[142:145], v[48:51]
	v_mfma_f32_16x16x32_bf16 v[52:55], v[154:157], v[32:35], v[138:141]
	v_mfma_f32_16x16x32_bf16 v[36:39], v[154:157], v[112:115], v[236:239]
	v_mfma_f32_16x16x32_bf16 v[20:23], v[154:157], v[124:127], v[20:23]
	v_mfma_f32_16x16x32_bf16 v[4:7], v[154:157], v[142:145], v[16:19]
	v_mfma_f32_16x16x32_bf16 v[48:51], v[248:251], v[32:35], v[146:149]
	v_mfma_f32_16x16x32_bf16 v[32:35], v[248:251], v[112:115], v[240:243]
	v_mfma_f32_16x16x32_bf16 v[16:19], v[248:251], v[124:127], v[244:247]
	v_mfma_f32_16x16x32_bf16 v[0:3], v[248:251], v[142:145], v[0:3]
	v_lshl_add_u32 v124, s13, 1, v170
	v_mov_b32_e32 v112, v215
	v_lshlrev_b32_e32 v113, 7, v124
	v_ashrrev_i32_e32 v138, 7, v112
	s_mul_i32 s13, s15, 0x140
	v_lshl_add_u32 v114, v138, 6, v113
	v_lshlrev_b32_e32 v113, 1, v112
	s_add_i32 s12, s12, s13
	v_and_b32_e32 v113, 0x80, v113
	v_lshl_or_b32 v127, s12, 8, v113
	v_lshrrev_b32_e32 v113, 2, v112
	v_and_b32_e32 v125, 15, v112
	v_and_b32_e32 v113, 8, v113
	v_ashrrev_i32_e32 v115, 2, v127
	v_readlane_b32 s80, v253, 25
	v_ashrrev_i32_e32 v114, 5, v114
	v_bfe_u32 v126, v112, 4, 2
	v_and_or_b32 v112, v112, 16, v113
	v_lshlrev_b32_e32 v156, 6, v125
	v_mov_b32_e32 v157, v153
	v_readlane_b32 s84, v253, 29
	v_readlane_b32 s85, v253, 30
	v_add_u32_e32 v114, v114, v115
	v_lshlrev_b32_e32 v152, 1, v112
	v_lshl_add_u64 v[144:145], s[84:85], 0, v[156:157]
	v_ashrrev_i32_e32 v115, 31, v114
	v_lshl_add_u64 v[112:113], v[144:145], 0, v[152:153]
	v_lshlrev_b64 v[146:147], 13, v[114:115]
	v_or_b32_e32 v114, 1, v114
	v_lshl_add_u64 v[150:151], v[112:113], 0, v[146:147]
	v_ashrrev_i32_e32 v115, 31, v114
	global_load_dwordx4 v[158:161], v[150:151], off
	v_lshlrev_b64 v[148:149], 13, v[114:115]
	v_lshl_add_u64 v[154:155], v[112:113], 0, v[148:149]
	global_load_dwordx4 v[128:131], v[154:155], off
	v_and_b32_e32 v113, 64, v185
	v_xor_b32_e32 v112, 16, v185
	v_add_u32_e32 v113, 64, v113
	v_cmp_lt_i32_e32 vcc, v112, v113
	v_or_b32_e32 v142, v127, v125
	v_lshlrev_b32_e32 v140, 1, v124
	v_cndmask_b32_e32 v112, v185, v112, vcc
	v_lshlrev_b32_e32 v172, 2, v112
	v_xor_b32_e32 v112, 32, v185
	v_cmp_lt_i32_e32 vcc, v112, v113
	v_ashrrev_i32_e32 v141, 31, v140
	v_ashrrev_i32_e32 v139, 31, v138
	v_cndmask_b32_e32 v112, v185, v112, vcc
	v_lshlrev_b32_e32 v173, 2, v112
	v_cmp_eq_u32_e32 vcc, 0, v126
	global_load_dwordx4 v[124:127], v[150:151], off offset:1024
	global_load_dwordx4 v[112:115], v[154:155], off offset:1024
	v_readlane_b32 s81, v253, 26
	v_readlane_b32 s82, v253, 27
	v_readlane_b32 s83, v253, 28
	v_readlane_b32 s86, v253, 31
	v_readlane_b32 s87, v253, 32
	v_readlane_b32 s88, v253, 33
	v_readlane_b32 s89, v253, 34
	v_readlane_b32 s90, v253, 35
	v_readlane_b32 s91, v253, 36
	v_readlane_b32 s92, v253, 37
	v_readlane_b32 s93, v253, 38
	v_readlane_b32 s94, v253, 39
	v_readlane_b32 s95, v253, 40
	s_waitcnt vmcnt(0)
	v_mov_b32_e32 v143, v160
	s_nop 1
	v_permlane16_swap_b32_e32 v158, v143
	v_mov_b32_e32 v164, v161
	s_nop 1
	v_permlane16_swap_b32_e32 v159, v164
	v_mov_b32_e32 v176, v130
	v_mov_b32_e32 v182, v131
	v_and_b32_e32 v131, 0xffff0000, v158
	v_lshlrev_b32_e32 v130, 16, v158
	v_pk_add_f32 v[130:131], v[178:179], v[130:131]
	v_and_b32_e32 v161, 0xffff0000, v159
	v_lshlrev_b32_e32 v160, 16, v159
	v_pk_add_f32 v[162:163], v[180:181], v[160:161]
	v_pk_mul_f32 v[160:161], v[130:131], v[130:131]
	v_cvt_pk_bf16_f32 v178, v130, v131
	v_and_b32_e32 v131, 0xffff0000, v143
	v_lshlrev_b32_e32 v130, 16, v143
	v_pk_mul_f32 v[158:159], v[162:163], v[162:163]
	v_cvt_pk_bf16_f32 v179, v162, v163
	v_pk_add_f32 v[130:131], v[224:225], v[130:131]
	v_and_b32_e32 v163, 0xffff0000, v164
	v_lshlrev_b32_e32 v162, 16, v164
	v_pk_add_f32 v[174:175], v[226:227], v[162:163]
	v_pk_mul_f32 v[164:165], v[130:131], v[130:131]
	v_cvt_pk_bf16_f32 v180, v130, v131
	v_lshl_add_u64 v[130:131], s[84:85], 0, v[146:147]
	v_pk_mul_f32 v[162:163], v[174:175], v[174:175]
	v_cvt_pk_bf16_f32 v181, v174, v175
	v_lshl_add_u64 v[174:175], v[130:131], 0, v[156:157]
	v_permlane16_swap_b32_e32 v128, v176
	v_permlane16_swap_b32_e32 v178, v180
	v_permlane16_swap_b32_e32 v179, v181
	v_lshl_add_u64 v[174:175], v[174:175], 0, v[152:153]
	v_permlane16_swap_b32_e32 v129, v182
	global_store_dwordx4 v[174:175], v[178:181], off
	v_and_b32_e32 v175, 0xffff0000, v128
	v_lshlrev_b32_e32 v174, 16, v128
	v_pk_add_f32 v[120:121], v[120:121], v[174:175]
	v_and_b32_e32 v175, 0xffff0000, v129
	v_lshlrev_b32_e32 v174, 16, v129
	v_pk_add_f32 v[122:123], v[122:123], v[174:175]
	v_pk_mul_f32 v[128:129], v[120:121], v[120:121]
	v_pk_mul_f32 v[174:175], v[122:123], v[122:123]
	v_cvt_pk_bf16_f32 v120, v120, v121
	v_cvt_pk_bf16_f32 v121, v122, v123
	v_and_b32_e32 v123, 0xffff0000, v176
	v_lshlrev_b32_e32 v122, 16, v176
	v_pk_add_f32 v[116:117], v[116:117], v[122:123]
	v_and_b32_e32 v123, 0xffff0000, v182
	v_lshlrev_b32_e32 v122, 16, v182
	v_add_f32_e32 v143, v164, v165
	v_add_f32_e32 v160, v160, v161
	v_pk_add_f32 v[118:119], v[118:119], v[122:123]
	v_pk_mul_f32 v[122:123], v[116:117], v[116:117]
	v_add_f32_e32 v143, v162, v143
	v_add_f32_e32 v158, v158, v160
	v_add_f32_e32 v128, v128, v129
	v_pk_mul_f32 v[178:179], v[118:119], v[118:119]
	v_add_f32_e32 v143, v163, v143
	v_add_f32_e32 v158, v159, v158
	v_add_f32_e32 v128, v174, v128
	v_add_f32_e32 v122, v122, v123
	v_add_f32_e32 v143, v158, v143
	v_add_f32_e32 v128, v175, v128
	v_add_f32_e32 v122, v178, v122
	v_add_f32_e32 v128, v143, v128
	v_add_f32_e32 v122, v179, v122
	v_add_f32_e32 v143, v122, v128
	v_lshl_add_u64 v[128:129], s[84:85], 0, v[148:149]
	v_cvt_pk_bf16_f32 v122, v116, v117
	v_cvt_pk_bf16_f32 v123, v118, v119
	v_lshl_add_u64 v[116:117], v[128:129], 0, v[156:157]
	v_permlane16_swap_b32_e32 v120, v122
	v_permlane16_swap_b32_e32 v121, v123
	v_lshl_add_u64 v[116:117], v[116:117], 0, v[152:153]
	global_store_dwordx4 v[116:117], v[120:123], off
	ds_bpermute_b32 v116, v172, v143
	s_waitcnt lgkmcnt(0)
	v_add_f32_e32 v116, v143, v116
	ds_bpermute_b32 v117, v173, v116
	s_and_saveexec_b64 s[12:13], vcc
	s_cbranch_execz .LBB0_267
; template <int MODE, int NSUB>
; __device__ __forceinline__ void epilogue(const Params& p, int layer, f32x4 (&acc)[4][NSUB], int tm, int tn, int g,
;                                          const float* s_rstd, const int tid_in) {
;     ...
;       ss = red_fq(ss);
;       if (fq == 0) p.part[(long)t * 16 + tm * 2 + wr] = ss;
	v_ashrrev_i32_e32 v143, 31, v142
	v_readlane_b32 s64, v253, 25
	v_lshlrev_b64 v[118:119], 6, v[142:143]
	v_readlane_b32 s70, v253, 31
	v_readlane_b32 s71, v253, 32
	s_waitcnt lgkmcnt(0)
	v_add_f32_e32 v116, v116, v117
	v_readlane_b32 s65, v253, 26
	v_lshl_add_u64 v[118:119], s[70:71], 0, v[118:119]
	v_lshl_add_u64 v[118:119], v[140:141], 2, v[118:119]
	v_lshl_add_u64 v[118:119], v[138:139], 2, v[118:119]
	v_readlane_b32 s66, v253, 27
	v_readlane_b32 s67, v253, 28
	v_readlane_b32 s68, v253, 29
	v_readlane_b32 s69, v253, 30
	v_readlane_b32 s72, v253, 33
	v_readlane_b32 s73, v253, 34
	v_readlane_b32 s74, v253, 35
	v_readlane_b32 s75, v253, 36
	v_readlane_b32 s76, v253, 37
	v_readlane_b32 s77, v253, 38
	v_readlane_b32 s78, v253, 39
	v_readlane_b32 s79, v253, 40
	global_store_dword v[118:119], v116, off

; #define BIG_SYNC(N)                                              \
;   asm volatile("s_waitcnt vmcnt(%0)" ::"n"(N) : "memory");       \
;   __builtin_amdgcn_s_barrier();                                  \
;   asm volatile("" ::: "memory");                                 \
;   __builtin_amdgcn_sched_barrier(0);
; template <int NK, bool BNT = false> ...
;     ...
;   auto stage = [&](int kt, int bufc) {
;     unsigned char* sa = smem + bufc * BIG_STAGE;
;     const unsigned char* Ab = Abase + (long)kt * 8192 + soff;
;     const unsigned char* Bb = Bbase + (long)kt * 8192 + soff;
;     glds16(Ab, sa + sb0);
;     glds16(Ab + astride * 2, sa + 8192 + sb0);
;     if constexpr (BNT) {
;       glds16_nt(Bb, sa + 16384 + sb0);
;       glds16_nt(Bb + bstride * 2, sa + 24576 + sb0);
;     } else {
;       glds16(Bb, sa + 16384 + sb0);
;       glds16(Bb + bstride * 2, sa + 24576 + sb0);
;     }
;   };
;   const int rd = fr * 64 + ((fq ^ (((fr >> 3) & 1) << 1)) * 16);
;   const int aoff = wr * 64 * 64 + rd;
;   const int boff = 16384 + wc * 128 * 64 + rd;
;   auto kstep = [&](int T, int cur, int nxt, bool do_stage) {
;     const unsigned char* sa = smem + cur * BIG_STAGE;
;     bf16x8 af[4], bfr[4];
; #pragma unroll
;     for (int m = 0; m < 4; ++m) af[m] = *reinterpret_cast<const bf16x8*>(sa + aoff + m * 1024);
; #pragma unroll
;     for (int n = 0; n < 4; ++n) bfr[n] = *reinterpret_cast<const bf16x8*>(sa + boff + n * 1024);
;     __builtin_amdgcn_sched_barrier(0);
;     if (do_stage) stage(T + 3, nxt);
; #pragma unroll
;     for (int m = 0; m < 4; ++m)
; #pragma unroll
;       for (int n = 0; n < 4; ++n) acc[m][n] = __builtin_amdgcn_mfma_f32_16x16x32_bf16(af[m], bfr[n], acc[m][n], 0, 0, 0);
;     if (do_stage) {
; #pragma unroll
;       for (int q = 0; q < NG; ++q) {
;         __builtin_amdgcn_sched_group_barrier(0x008, 3, 0);
;         __builtin_amdgcn_sched_group_barrier(0x010, 1, 0);
;       }
;       __builtin_amdgcn_sched_group_barrier(0x008, 16 - 3 * NG, 0);
;     }
;     __builtin_amdgcn_sched_barrier(0);
;     ...
;   for (int it = 0; it < NK / 4 - 1; ++it) {
;     const int t = it * 4;
;     BIG_SYNC(2 * NG); kstep(t, 0, 3, true);
;     BIG_SYNC(2 * NG); kstep(t + 1, 1, 0, true);
;     BIG_SYNC(2 * NG); kstep(t + 2, 2, 1, true);
;     BIG_SYNC(2 * NG); kstep(t + 3, 3, 2, true);
.Lmy_up_rsdone:
	s_or_b64 exec, exec, s[100:101]
	s_waitcnt vmcnt(8)
	s_barrier
	v_add_u32_e32 v167, 0x10000, v147
	v_or_b32_e32 v168, 0x10000, v149
	v_add_u32_e32 v176, 0x18000, v147
	v_or_b32_e32 v179, 0x18000, v149
	v_add_u32_e32 v210, 0x10000, v147
	v_or_b32_e32 v211, 0x10000, v149
	v_add_u32_e32 v212, 0x18000, v147
	v_or_b32_e32 v213, 0x18000, v149
	v_readfirstlane_b32 s100, v146
	ds_read_b128 v[216:219], v147
	ds_read_b128 v[220:223], v147 offset:1024
	ds_read_b128 v[224:227], v147 offset:2048
	ds_read_b128 v[228:231], v147 offset:3072
	ds_read_b128 v[232:235], v148 offset:16384
	ds_read_b128 v[236:239], v148 offset:17408
	ds_read_b128 v[240:243], v148 offset:18432
	ds_read_b128 v[244:247], v148 offset:19456
.LBB0_290:
	s_waitcnt lgkmcnt(3)
	v_mfma_f32_16x16x32_bf16 v[124:127], v[216:219], v[232:235], v[124:127]
	v_add_u32_e32 v163, 0x18000, v146
	v_mfma_f32_16x16x32_bf16 v[108:111], v[220:223], v[232:235], v[108:111]
	v_lshl_add_u64 v[144:145], v[138:139], 0, s[12:13]
	v_mfma_f32_16x16x32_bf16 v[88:91], v[224:227], v[232:235], v[88:91]
	s_waitcnt vmcnt(4)
	s_barrier
	v_lshl_add_u64 v[164:165], v[144:145], 0, s[60:61]
	v_mfma_f32_16x16x32_bf16 v[44:47], v[228:231], v[232:235], v[44:47]
	s_add_i32 m0, s100, 0x18000
	s_waitcnt lgkmcnt(2)
	v_mfma_f32_16x16x32_bf16 v[120:123], v[216:219], v[236:239], v[120:123]
	ds_read_b128 v[232:235], v148 offset:20480
	v_mfma_f32_16x16x32_bf16 v[104:107], v[220:223], v[236:239], v[104:107]
	v_lshl_add_u64 v[142:143], v[140:141], 0, s[12:13]
	v_mfma_f32_16x16x32_bf16 v[76:79], v[224:227], v[236:239], v[76:79]
	v_lshl_add_u64 v[168:169], v[144:145], 0, s[80:81]
	v_mfma_f32_16x16x32_bf16 v[40:43], v[228:231], v[236:239], v[40:43]
	v_lshl_add_u64 v[166:167], v[142:143], 0, s[60:61]
	s_waitcnt lgkmcnt(2)
	v_mfma_f32_16x16x32_bf16 v[116:119], v[216:219], v[240:243], v[116:119]
	ds_read_b128 v[236:239], v148 offset:21504
	v_mfma_f32_16x16x32_bf16 v[100:103], v[220:223], v[240:243], v[100:103]
	global_load_lds_dwordx4 v[164:165], off
	v_mfma_f32_16x16x32_bf16 v[68:71], v[224:227], v[240:243], v[68:71]
	v_add_u32_e32 v164, 0x1a000, v146
	v_mfma_f32_16x16x32_bf16 v[36:39], v[228:231], v[240:243], v[36:39]
	v_add_u32_e32 v165, 0x1c000, v146
	s_waitcnt lgkmcnt(2)
	v_mfma_f32_16x16x32_bf16 v[112:115], v[216:219], v[244:247], v[112:115]
	ds_read_b128 v[240:243], v148 offset:22528
	v_mfma_f32_16x16x32_bf16 v[96:99], v[220:223], v[244:247], v[96:99]
	s_add_i32 m0, s100, 0x1a000
	v_mfma_f32_16x16x32_bf16 v[64:67], v[224:227], v[244:247], v[64:67]
	global_load_lds_dwordx4 v[168:169], off
	v_mfma_f32_16x16x32_bf16 v[32:35], v[228:231], v[244:247], v[32:35]
	s_add_i32 m0, s100, 0x1c000
	s_waitcnt lgkmcnt(2)
	v_mfma_f32_16x16x32_bf16 v[92:95], v[216:219], v[232:235], v[92:95]
	ds_read_b128 v[244:247], v148 offset:23552
	v_mfma_f32_16x16x32_bf16 v[60:63], v[220:223], v[232:235], v[60:63]
	ds_read_b128 v[186:189], v147 offset:32768
	v_mfma_f32_16x16x32_bf16 v[28:31], v[224:227], v[232:235], v[28:31]
	ds_read_b128 v[190:193], v147 offset:33792
	v_mfma_f32_16x16x32_bf16 v[12:15], v[228:231], v[232:235], v[12:15]
	ds_read_b128 v[194:197], v147 offset:34816
	s_waitcnt lgkmcnt(5)
	v_mfma_f32_16x16x32_bf16 v[84:87], v[216:219], v[236:239], v[84:87]
	ds_read_b128 v[202:205], v147 offset:35840
	ds_read_b128 v[232:235], v148 offset:49152
	v_mfma_f32_16x16x32_bf16 v[56:59], v[220:223], v[236:239], v[56:59]
	v_lshl_add_u64 v[168:169], v[142:143], 0, s[80:81]
	v_mfma_f32_16x16x32_bf16 v[24:27], v[224:227], v[236:239], v[24:27]
	global_load_lds_dwordx4 v[166:167], off
	v_mfma_f32_16x16x32_bf16 v[8:11], v[228:231], v[236:239], v[8:11]
	v_add_u32_e32 v166, 0x1e000, v146
	s_waitcnt lgkmcnt(6)
	v_mfma_f32_16x16x32_bf16 v[80:83], v[216:219], v[240:243], v[80:83]
	ds_read_b128 v[236:239], v148 offset:50176
	v_mfma_f32_16x16x32_bf16 v[52:55], v[220:223], v[240:243], v[52:55]
	s_add_i32 m0, s100, 0x1e000
	v_mfma_f32_16x16x32_bf16 v[20:23], v[224:227], v[240:243], v[20:23]
	global_load_lds_dwordx4 v[168:169], off
	v_mfma_f32_16x16x32_bf16 v[4:7], v[228:231], v[240:243], v[4:7]
	s_waitcnt lgkmcnt(6)
	v_mfma_f32_16x16x32_bf16 v[72:75], v[216:219], v[244:247], v[72:75]
	ds_read_b128 v[240:243], v148 offset:51200
	v_mfma_f32_16x16x32_bf16 v[48:51], v[220:223], v[244:247], v[48:51]
	v_mfma_f32_16x16x32_bf16 v[16:19], v[224:227], v[244:247], v[16:19]
	v_mfma_f32_16x16x32_bf16 v[0:3], v[228:231], v[244:247], v[0:3]
	ds_read_b128 v[244:247], v148 offset:52224
	s_waitcnt lgkmcnt(3)
	v_mfma_f32_16x16x32_bf16 v[124:127], v[186:189], v[232:235], v[124:127]
	v_lshl_add_u64 v[168:169], v[144:145], 0, s[62:63]
	v_mfma_f32_16x16x32_bf16 v[108:111], v[190:193], v[232:235], v[108:111]
	s_mov_b32 m0, s100
	v_mfma_f32_16x16x32_bf16 v[88:91], v[194:197], v[232:235], v[88:91]
	s_waitcnt vmcnt(4)
	s_barrier
; #define BIG_SYNC(N)                                              \
;   asm volatile("s_waitcnt vmcnt(%0)" ::"n"(N) : "memory");       \
;   __builtin_amdgcn_s_barrier();                                  \
;   asm volatile("" ::: "memory");                                 \
;   __builtin_amdgcn_sched_barrier(0);
; template <int NK, bool BNT = false> ...
;     ...
;   auto kstep = [&](int T, int cur, int nxt, bool do_stage) {
;     const unsigned char* sa = smem + cur * BIG_STAGE;
;     bf16x8 af[4], bfr[4];
; #pragma unroll
;     for (int m = 0; m < 4; ++m) af[m] = *reinterpret_cast<const bf16x8*>(sa + aoff + m * 1024);
; #pragma unroll
;     for (int n = 0; n < 4; ++n) bfr[n] = *reinterpret_cast<const bf16x8*>(sa + boff + n * 1024);
;     __builtin_amdgcn_sched_barrier(0);
;     if (do_stage) stage(T + 3, nxt);
; #pragma unroll
;     for (int m = 0; m < 4; ++m)
; #pragma unroll
;       for (int n = 0; n < 4; ++n) acc[m][n] = __builtin_amdgcn_mfma_f32_16x16x32_bf16(af[m], bfr[n], acc[m][n], 0, 0, 0);
;     if (do_stage) {
; #pragma unroll
;       for (int q = 0; q < NG; ++q) {
;         __builtin_amdgcn_sched_group_barrier(0x008, 3, 0);
;         __builtin_amdgcn_sched_group_barrier(0x010, 1, 0);
;       }
;       __builtin_amdgcn_sched_group_barrier(0x008, 16 - 3 * NG, 0);
;     }
;     __builtin_amdgcn_sched_barrier(0);
; #pragma unroll
;     for (int n = 0; n < 4; ++n) bfr[n] = *reinterpret_cast<const bf16x8*>(sa + boff + (4 + n) * 1024);
; #pragma unroll
;     for (int m = 0; m < 4; ++m)
; #pragma unroll
;       for (int n = 0; n < 4; ++n)
;         acc[m][4 + n] = __builtin_amdgcn_mfma_f32_16x16x32_bf16(af[m], bfr[n], acc[m][4 + n], 0, 0, 0);
;     __builtin_amdgcn_sched_barrier(0);
;     ...
;   for (int it = 0; it < NK / 4 - 1; ++it) {
;     const int t = it * 4;
;     BIG_SYNC(2 * NG); kstep(t, 0, 3, true);
;     BIG_SYNC(2 * NG); kstep(t + 1, 1, 0, true);
;     BIG_SYNC(2 * NG); kstep(t + 2, 2, 1, true);
;     BIG_SYNC(2 * NG); kstep(t + 3, 3, 2, true);
	v_lshl_add_u64 v[182:183], v[142:143], 0, s[62:63]
	v_mfma_f32_16x16x32_bf16 v[44:47], v[202:205], v[232:235], v[44:47]
	global_load_lds_dwordx4 v[168:169], off
	s_waitcnt lgkmcnt(2)
	v_mfma_f32_16x16x32_bf16 v[120:123], v[186:189], v[236:239], v[120:123]
	ds_read_b128 v[232:235], v148 offset:53248
	v_mfma_f32_16x16x32_bf16 v[104:107], v[190:193], v[236:239], v[104:107]
	v_lshl_add_u64 v[168:169], v[144:145], 0, s[0:1]
	v_mfma_f32_16x16x32_bf16 v[76:79], v[194:197], v[236:239], v[76:79]
	s_add_i32 m0, s100, 0x2000
	v_mfma_f32_16x16x32_bf16 v[40:43], v[202:205], v[236:239], v[40:43]
	global_load_lds_dwordx4 v[168:169], off
	s_waitcnt lgkmcnt(2)
	v_mfma_f32_16x16x32_bf16 v[116:119], v[186:189], v[240:243], v[116:119]
	ds_read_b128 v[236:239], v148 offset:54272
	v_mfma_f32_16x16x32_bf16 v[100:103], v[190:193], v[240:243], v[100:103]
	s_add_i32 m0, s100, 0x4000
	v_mfma_f32_16x16x32_bf16 v[68:71], v[194:197], v[240:243], v[68:71]
	v_lshl_add_u64 v[168:169], v[142:143], 0, s[0:1]
	v_mfma_f32_16x16x32_bf16 v[36:39], v[202:205], v[240:243], v[36:39]
	global_load_lds_dwordx4 v[182:183], off
	s_waitcnt lgkmcnt(2)
	v_mfma_f32_16x16x32_bf16 v[112:115], v[186:189], v[244:247], v[112:115]
	ds_read_b128 v[240:243], v148 offset:55296
	v_mfma_f32_16x16x32_bf16 v[96:99], v[190:193], v[244:247], v[96:99]
	s_add_i32 m0, s100, 0x6000
	v_mfma_f32_16x16x32_bf16 v[64:67], v[194:197], v[244:247], v[64:67]
	global_load_lds_dwordx4 v[168:169], off
	v_mfma_f32_16x16x32_bf16 v[32:35], v[202:205], v[244:247], v[32:35]
	s_waitcnt lgkmcnt(2)
	v_mfma_f32_16x16x32_bf16 v[92:95], v[186:189], v[232:235], v[92:95]
	ds_read_b128 v[244:247], v148 offset:56320
	v_mfma_f32_16x16x32_bf16 v[60:63], v[190:193], v[232:235], v[60:63]
	ds_read_b128 v[216:219], v210
	v_mfma_f32_16x16x32_bf16 v[28:31], v[194:197], v[232:235], v[28:31]
	ds_read_b128 v[220:223], v210 offset:1024
	v_mfma_f32_16x16x32_bf16 v[12:15], v[202:205], v[232:235], v[12:15]
	ds_read_b128 v[224:227], v210 offset:2048
	s_waitcnt lgkmcnt(5)
	v_mfma_f32_16x16x32_bf16 v[84:87], v[186:189], v[236:239], v[84:87]
	ds_read_b128 v[228:231], v210 offset:3072
	ds_read_b128 v[232:235], v211
	v_mfma_f32_16x16x32_bf16 v[56:59], v[190:193], v[236:239], v[56:59]
	v_mfma_f32_16x16x32_bf16 v[24:27], v[194:197], v[236:239], v[24:27]
	v_mfma_f32_16x16x32_bf16 v[8:11], v[202:205], v[236:239], v[8:11]
	s_waitcnt lgkmcnt(6)
	v_mfma_f32_16x16x32_bf16 v[80:83], v[186:189], v[240:243], v[80:83]
	ds_read_b128 v[236:239], v211 offset:1024
	v_mfma_f32_16x16x32_bf16 v[52:55], v[190:193], v[240:243], v[52:55]
	v_mfma_f32_16x16x32_bf16 v[20:23], v[194:197], v[240:243], v[20:23]
	v_mfma_f32_16x16x32_bf16 v[4:7], v[202:205], v[240:243], v[4:7]
	s_waitcnt lgkmcnt(6)
	v_mfma_f32_16x16x32_bf16 v[72:75], v[186:189], v[244:247], v[72:75]
	ds_read_b128 v[240:243], v211 offset:2048
	v_mfma_f32_16x16x32_bf16 v[48:51], v[190:193], v[244:247], v[48:51]
	v_mfma_f32_16x16x32_bf16 v[16:19], v[194:197], v[244:247], v[16:19]
	v_mfma_f32_16x16x32_bf16 v[0:3], v[202:205], v[244:247], v[0:3]
	ds_read_b128 v[244:247], v211 offset:3072
	s_waitcnt lgkmcnt(3)
	v_mfma_f32_16x16x32_bf16 v[124:127], v[216:219], v[232:235], v[124:127]
	v_lshl_add_u64 v[174:175], v[144:145], 0, s[2:3]
	v_mfma_f32_16x16x32_bf16 v[108:111], v[220:223], v[232:235], v[108:111]
	s_add_i32 m0, s100, 0x8000
	v_mfma_f32_16x16x32_bf16 v[88:91], v[224:227], v[232:235], v[88:91]
	s_waitcnt vmcnt(4)
	s_barrier
	v_lshl_add_u64 v[178:179], v[142:143], 0, s[2:3]
	v_mfma_f32_16x16x32_bf16 v[44:47], v[228:231], v[232:235], v[44:47]
	global_load_lds_dwordx4 v[174:175], off
	s_waitcnt lgkmcnt(2)
	v_mfma_f32_16x16x32_bf16 v[120:123], v[216:219], v[236:239], v[120:123]
	ds_read_b128 v[232:235], v211 offset:4096
	v_mfma_f32_16x16x32_bf16 v[104:107], v[220:223], v[236:239], v[104:107]
	v_lshl_add_u64 v[174:175], v[144:145], 0, s[52:53]
	v_mfma_f32_16x16x32_bf16 v[76:79], v[224:227], v[236:239], v[76:79]
	s_add_i32 m0, s100, 0xa000
	v_mfma_f32_16x16x32_bf16 v[40:43], v[228:231], v[236:239], v[40:43]
	global_load_lds_dwordx4 v[174:175], off
	s_waitcnt lgkmcnt(2)
	v_mfma_f32_16x16x32_bf16 v[116:119], v[216:219], v[240:243], v[116:119]
	ds_read_b128 v[236:239], v211 offset:5120
	v_mfma_f32_16x16x32_bf16 v[100:103], v[220:223], v[240:243], v[100:103]
	s_add_i32 m0, s100, 0xc000
	v_mfma_f32_16x16x32_bf16 v[68:71], v[224:227], v[240:243], v[68:71]
	v_lshl_add_u64 v[174:175], v[142:143], 0, s[52:53]
	v_mfma_f32_16x16x32_bf16 v[36:39], v[228:231], v[240:243], v[36:39]
	global_load_lds_dwordx4 v[178:179], off
	s_waitcnt lgkmcnt(2)
	v_mfma_f32_16x16x32_bf16 v[112:115], v[216:219], v[244:247], v[112:115]
	ds_read_b128 v[240:243], v211 offset:6144
	v_mfma_f32_16x16x32_bf16 v[96:99], v[220:223], v[244:247], v[96:99]
	s_add_i32 m0, s100, 0xe000
	v_mfma_f32_16x16x32_bf16 v[64:67], v[224:227], v[244:247], v[64:67]
	global_load_lds_dwordx4 v[174:175], off
	v_mfma_f32_16x16x32_bf16 v[32:35], v[228:231], v[244:247], v[32:35]
	s_waitcnt lgkmcnt(2)
	v_mfma_f32_16x16x32_bf16 v[92:95], v[216:219], v[232:235], v[92:95]
	ds_read_b128 v[244:247], v211 offset:7168
	v_mfma_f32_16x16x32_bf16 v[60:63], v[220:223], v[232:235], v[60:63]
	ds_read_b128 v[186:189], v210 offset:32768
	v_mfma_f32_16x16x32_bf16 v[28:31], v[224:227], v[232:235], v[28:31]
	ds_read_b128 v[190:193], v210 offset:33792
	v_mfma_f32_16x16x32_bf16 v[12:15], v[228:231], v[232:235], v[12:15]
	ds_read_b128 v[194:197], v210 offset:34816
	s_waitcnt lgkmcnt(5)
	v_mfma_f32_16x16x32_bf16 v[84:87], v[216:219], v[236:239], v[84:87]
	ds_read_b128 v[202:205], v210 offset:35840
	ds_read_b128 v[232:235], v211 offset:32768
	v_mfma_f32_16x16x32_bf16 v[56:59], v[220:223], v[236:239], v[56:59]
	v_mfma_f32_16x16x32_bf16 v[24:27], v[224:227], v[236:239], v[24:27]
	v_mfma_f32_16x16x32_bf16 v[8:11], v[228:231], v[236:239], v[8:11]
	s_waitcnt lgkmcnt(6)
	v_mfma_f32_16x16x32_bf16 v[80:83], v[216:219], v[240:243], v[80:83]
	ds_read_b128 v[236:239], v211 offset:33792
	v_mfma_f32_16x16x32_bf16 v[52:55], v[220:223], v[240:243], v[52:55]
	v_mfma_f32_16x16x32_bf16 v[20:23], v[224:227], v[240:243], v[20:23]
	v_mfma_f32_16x16x32_bf16 v[4:7], v[228:231], v[240:243], v[4:7]
	s_waitcnt lgkmcnt(6)
	v_mfma_f32_16x16x32_bf16 v[72:75], v[216:219], v[244:247], v[72:75]
	ds_read_b128 v[240:243], v211 offset:34816
	v_mfma_f32_16x16x32_bf16 v[48:51], v[220:223], v[244:247], v[48:51]
	v_mfma_f32_16x16x32_bf16 v[16:19], v[224:227], v[244:247], v[16:19]
	v_mfma_f32_16x16x32_bf16 v[0:3], v[228:231], v[244:247], v[0:3]
	ds_read_b128 v[244:247], v211 offset:35840
	s_waitcnt lgkmcnt(3)
	v_mfma_f32_16x16x32_bf16 v[124:127], v[186:189], v[232:235], v[124:127]
	v_lshl_add_u64 v[248:249], v[144:145], 0, s[54:55]
	v_mfma_f32_16x16x32_bf16 v[108:111], v[190:193], v[232:235], v[108:111]
	s_add_i32 m0, s100, 0x10000
	v_mfma_f32_16x16x32_bf16 v[88:91], v[194:197], v[232:235], v[88:91]
	s_waitcnt vmcnt(4)
	s_barrier
; #define BIG_SYNC(N)                                              \
;   asm volatile("s_waitcnt vmcnt(%0)" ::"n"(N) : "memory");       \
;   __builtin_amdgcn_s_barrier();                                  \
;   asm volatile("" ::: "memory");                                 \
;   __builtin_amdgcn_sched_barrier(0);
; template <int NK, bool BNT = false> ...
;     ...
;   auto kstep = [&](int T, int cur, int nxt, bool do_stage) {
;     const unsigned char* sa = smem + cur * BIG_STAGE;
;     bf16x8 af[4], bfr[4];
; #pragma unroll
;     for (int m = 0; m < 4; ++m) af[m] = *reinterpret_cast<const bf16x8*>(sa + aoff + m * 1024);
; #pragma unroll
;     for (int n = 0; n < 4; ++n) bfr[n] = *reinterpret_cast<const bf16x8*>(sa + boff + n * 1024);
;     __builtin_amdgcn_sched_barrier(0);
;     if (do_stage) stage(T + 3, nxt);
; #pragma unroll
;     for (int m = 0; m < 4; ++m)
; #pragma unroll
;       for (int n = 0; n < 4; ++n) acc[m][n] = __builtin_amdgcn_mfma_f32_16x16x32_bf16(af[m], bfr[n], acc[m][n], 0, 0, 0);
;     if (do_stage) {
; #pragma unroll
;       for (int q = 0; q < NG; ++q) {
;         __builtin_amdgcn_sched_group_barrier(0x008, 3, 0);
;         __builtin_amdgcn_sched_group_barrier(0x010, 1, 0);
;       }
;       __builtin_amdgcn_sched_group_barrier(0x008, 16 - 3 * NG, 0);
;     }
;     __builtin_amdgcn_sched_barrier(0);
; #pragma unroll
;     for (int n = 0; n < 4; ++n) bfr[n] = *reinterpret_cast<const bf16x8*>(sa + boff + (4 + n) * 1024);
; #pragma unroll
;     for (int m = 0; m < 4; ++m)
; #pragma unroll
;       for (int n = 0; n < 4; ++n)
;         acc[m][4 + n] = __builtin_amdgcn_mfma_f32_16x16x32_bf16(af[m], bfr[n], acc[m][4 + n], 0, 0, 0);
;     __builtin_amdgcn_sched_barrier(0);
;     ...
;   for (int it = 0; it < NK / 4 - 1; ++it) {
;     const int t = it * 4;
;     BIG_SYNC(2 * NG); kstep(t, 0, 3, true);
;     BIG_SYNC(2 * NG); kstep(t + 1, 1, 0, true);
;     BIG_SYNC(2 * NG); kstep(t + 2, 2, 1, true);
;     BIG_SYNC(2 * NG); kstep(t + 3, 3, 2, true);
;   }
;   BIG_SYNC(2 * NG); kstep(NK - 4, 0, 3, true);
	v_lshl_add_u64 v[144:145], v[144:145], 0, s[56:57]
	v_mfma_f32_16x16x32_bf16 v[44:47], v[202:205], v[232:235], v[44:47]
	v_lshl_add_u64 v[250:251], v[142:143], 0, s[54:55]
	s_waitcnt lgkmcnt(2)
	v_mfma_f32_16x16x32_bf16 v[120:123], v[186:189], v[236:239], v[120:123]
	ds_read_b128 v[232:235], v211 offset:36864
	v_mfma_f32_16x16x32_bf16 v[104:107], v[190:193], v[236:239], v[104:107]
	v_lshl_add_u64 v[142:143], v[142:143], 0, s[56:57]
	v_mfma_f32_16x16x32_bf16 v[76:79], v[194:197], v[236:239], v[76:79]
	global_load_lds_dwordx4 v[248:249], off
	v_mfma_f32_16x16x32_bf16 v[40:43], v[202:205], v[236:239], v[40:43]
	s_add_i32 m0, s100, 0x12000
	s_waitcnt lgkmcnt(2)
	v_mfma_f32_16x16x32_bf16 v[116:119], v[186:189], v[240:243], v[116:119]
	ds_read_b128 v[236:239], v211 offset:37888
	v_mfma_f32_16x16x32_bf16 v[100:103], v[190:193], v[240:243], v[100:103]
	global_load_lds_dwordx4 v[144:145], off
	v_mfma_f32_16x16x32_bf16 v[68:71], v[194:197], v[240:243], v[68:71]
	s_add_i32 m0, s100, 0x14000
	v_mfma_f32_16x16x32_bf16 v[36:39], v[202:205], v[240:243], v[36:39]
	global_load_lds_dwordx4 v[250:251], off
	s_waitcnt lgkmcnt(2)
	v_mfma_f32_16x16x32_bf16 v[112:115], v[186:189], v[244:247], v[112:115]
	ds_read_b128 v[240:243], v211 offset:38912
	v_mfma_f32_16x16x32_bf16 v[96:99], v[190:193], v[244:247], v[96:99]
	s_add_i32 m0, s100, 0x16000
	v_mfma_f32_16x16x32_bf16 v[64:67], v[194:197], v[244:247], v[64:67]
	global_load_lds_dwordx4 v[142:143], off
	v_mfma_f32_16x16x32_bf16 v[32:35], v[202:205], v[244:247], v[32:35]
	s_waitcnt lgkmcnt(2)
	v_mfma_f32_16x16x32_bf16 v[92:95], v[186:189], v[232:235], v[92:95]
	ds_read_b128 v[244:247], v211 offset:39936
	v_mfma_f32_16x16x32_bf16 v[60:63], v[190:193], v[232:235], v[60:63]
	ds_read_b128 v[216:219], v147
	v_mfma_f32_16x16x32_bf16 v[28:31], v[194:197], v[232:235], v[28:31]
	ds_read_b128 v[220:223], v147 offset:1024
	v_mfma_f32_16x16x32_bf16 v[12:15], v[202:205], v[232:235], v[12:15]
	ds_read_b128 v[224:227], v147 offset:2048
	s_waitcnt lgkmcnt(5)
	v_mfma_f32_16x16x32_bf16 v[84:87], v[186:189], v[236:239], v[84:87]
	ds_read_b128 v[228:231], v147 offset:3072
	ds_read_b128 v[232:235], v148 offset:16384
	v_mfma_f32_16x16x32_bf16 v[56:59], v[190:193], v[236:239], v[56:59]
	v_mfma_f32_16x16x32_bf16 v[24:27], v[194:197], v[236:239], v[24:27]
	v_mfma_f32_16x16x32_bf16 v[8:11], v[202:205], v[236:239], v[8:11]
	s_waitcnt lgkmcnt(6)
	v_mfma_f32_16x16x32_bf16 v[80:83], v[186:189], v[240:243], v[80:83]
	ds_read_b128 v[236:239], v148 offset:17408
	v_mfma_f32_16x16x32_bf16 v[52:55], v[190:193], v[240:243], v[52:55]
	v_mfma_f32_16x16x32_bf16 v[20:23], v[194:197], v[240:243], v[20:23]
	v_mfma_f32_16x16x32_bf16 v[4:7], v[202:205], v[240:243], v[4:7]
	s_waitcnt lgkmcnt(6)
	v_mfma_f32_16x16x32_bf16 v[72:75], v[186:189], v[244:247], v[72:75]
	ds_read_b128 v[240:243], v148 offset:18432
	v_mfma_f32_16x16x32_bf16 v[48:51], v[190:193], v[244:247], v[48:51]
	v_mfma_f32_16x16x32_bf16 v[16:19], v[194:197], v[244:247], v[16:19]
	v_mfma_f32_16x16x32_bf16 v[0:3], v[202:205], v[244:247], v[0:3]
	ds_read_b128 v[244:247], v148 offset:19456
	s_add_u32 s12, s12, 0x8000
	s_addc_u32 s13, s13, 0
	s_cmp_lg_u32 s12, 0x38000
	s_cbranch_scc1 .LBB0_290
	v_add_u32_e32 v167, 0x10000, v147
	v_or_b32_e32 v168, 0x10000, v149
	v_add_u32_e32 v169, 0x10400, v149
	v_add_u32_e32 v170, 0x10800, v149
	v_add_u32_e32 v172, 0x10c00, v149
	v_add_u32_e32 v173, 0x11000, v149
	v_add_u32_e32 v174, 0x11400, v149
	v_add_u32_e32 v175, 0x11800, v149
	v_add_u32_e32 v178, 0x11c00, v149
	v_add_u32_e32 v176, 0x18000, v147
	v_or_b32_e32 v179, 0x18000, v149
	v_add_u32_e32 v180, 0x18400, v149
	v_add_u32_e32 v181, 0x18800, v149
	v_add_u32_e32 v182, 0x18c00, v149
	v_add_u32_e32 v142, 0x19000, v149
	v_add_u32_e32 v143, 0x19400, v149
	v_add_u32_e32 v144, 0x19800, v149
	v_add_u32_e32 v145, 0x19c00, v149
	s_waitcnt lgkmcnt(3)
	v_mfma_f32_16x16x32_bf16 v[124:127], v[216:219], v[232:235], v[124:127]
	s_mov_b64 s[12:13], 0x3e000
	v_mfma_f32_16x16x32_bf16 v[108:111], v[220:223], v[232:235], v[108:111]
	v_readfirstlane_b32 s11, v163
	v_mfma_f32_16x16x32_bf16 v[88:91], v[224:227], v[232:235], v[88:91]
	s_waitcnt vmcnt(4)
	s_barrier
	v_lshl_add_u64 v[198:199], v[136:137], 0, s[12:13]
	v_mfma_f32_16x16x32_bf16 v[44:47], v[228:231], v[232:235], v[44:47]
	v_lshl_add_u64 v[200:201], v[134:135], 0, s[12:13]
	s_waitcnt lgkmcnt(2)
	v_mfma_f32_16x16x32_bf16 v[120:123], v[216:219], v[236:239], v[120:123]
	ds_read_b128 v[232:235], v148 offset:20480
	v_mfma_f32_16x16x32_bf16 v[104:107], v[220:223], v[236:239], v[104:107]
	s_mov_b32 m0, s11
	v_mfma_f32_16x16x32_bf16 v[76:79], v[224:227], v[236:239], v[76:79]
	s_mov_b64 s[12:13], 0x7e000
	v_mfma_f32_16x16x32_bf16 v[40:43], v[228:231], v[236:239], v[40:43]
	v_readfirstlane_b32 s11, v164
	s_waitcnt lgkmcnt(2)
	v_mfma_f32_16x16x32_bf16 v[116:119], v[216:219], v[240:243], v[116:119]
	ds_read_b128 v[236:239], v148 offset:21504
	v_mfma_f32_16x16x32_bf16 v[100:103], v[220:223], v[240:243], v[100:103]
	v_lshl_add_u64 v[136:137], v[136:137], 0, s[12:13]
	v_mfma_f32_16x16x32_bf16 v[68:71], v[224:227], v[240:243], v[68:71]
	v_lshl_add_u64 v[134:135], v[134:135], 0, s[12:13]
	v_mfma_f32_16x16x32_bf16 v[36:39], v[228:231], v[240:243], v[36:39]
	global_load_lds_dwordx4 v[198:199], off
	s_waitcnt lgkmcnt(2)
	v_mfma_f32_16x16x32_bf16 v[112:115], v[216:219], v[244:247], v[112:115]
	ds_read_b128 v[240:243], v148 offset:22528
	v_mfma_f32_16x16x32_bf16 v[96:99], v[220:223], v[244:247], v[96:99]
	s_mov_b32 m0, s11
	v_mfma_f32_16x16x32_bf16 v[64:67], v[224:227], v[244:247], v[64:67]
	v_readfirstlane_b32 s11, v165
	v_mfma_f32_16x16x32_bf16 v[32:35], v[228:231], v[244:247], v[32:35]
	global_load_lds_dwordx4 v[136:137], off
	s_waitcnt lgkmcnt(2)
; #define BIG_SYNC(N)                                              \
;   asm volatile("s_waitcnt vmcnt(%0)" ::"n"(N) : "memory");       \
;   __builtin_amdgcn_s_barrier();                                  \
;   asm volatile("" ::: "memory");                                 \
;   __builtin_amdgcn_sched_barrier(0);
; template <int NK, bool BNT = false> ...
;     ...
;   auto kstep = [&](int T, int cur, int nxt, bool do_stage) {
;     const unsigned char* sa = smem + cur * BIG_STAGE;
;     bf16x8 af[4], bfr[4];
; #pragma unroll
;     for (int m = 0; m < 4; ++m) af[m] = *reinterpret_cast<const bf16x8*>(sa + aoff + m * 1024);
; #pragma unroll
;     for (int n = 0; n < 4; ++n) bfr[n] = *reinterpret_cast<const bf16x8*>(sa + boff + n * 1024);
;     __builtin_amdgcn_sched_barrier(0);
;     if (do_stage) stage(T + 3, nxt);
; #pragma unroll
;     for (int m = 0; m < 4; ++m)
; #pragma unroll
;       for (int n = 0; n < 4; ++n) acc[m][n] = __builtin_amdgcn_mfma_f32_16x16x32_bf16(af[m], bfr[n], acc[m][n], 0, 0, 0);
;     if (do_stage) {
; #pragma unroll
;       for (int q = 0; q < NG; ++q) {
;         __builtin_amdgcn_sched_group_barrier(0x008, 3, 0);
;         __builtin_amdgcn_sched_group_barrier(0x010, 1, 0);
;       }
;       __builtin_amdgcn_sched_group_barrier(0x008, 16 - 3 * NG, 0);
;     }
;     __builtin_amdgcn_sched_barrier(0);
; #pragma unroll
;     for (int n = 0; n < 4; ++n) bfr[n] = *reinterpret_cast<const bf16x8*>(sa + boff + (4 + n) * 1024);
; #pragma unroll
;     for (int m = 0; m < 4; ++m)
; #pragma unroll
;       for (int n = 0; n < 4; ++n)
;         acc[m][4 + n] = __builtin_amdgcn_mfma_f32_16x16x32_bf16(af[m], bfr[n], acc[m][4 + n], 0, 0, 0);
;     __builtin_amdgcn_sched_barrier(0);
;     ...
;   BIG_SYNC(2 * NG); kstep(NK - 4, 0, 3, true);
;   BIG_SYNC(2 * NG); kstep(NK - 3, 1, 0, false);
;   BIG_SYNC(NG);     kstep(NK - 2, 2, 0, false);
	v_mfma_f32_16x16x32_bf16 v[92:95], v[216:219], v[232:235], v[92:95]
	ds_read_b128 v[244:247], v148 offset:23552
	v_mfma_f32_16x16x32_bf16 v[60:63], v[220:223], v[232:235], v[60:63]
	ds_read_b128 v[186:189], v147 offset:32768
	v_mfma_f32_16x16x32_bf16 v[28:31], v[224:227], v[232:235], v[28:31]
	ds_read_b128 v[190:193], v147 offset:33792
	v_mfma_f32_16x16x32_bf16 v[12:15], v[228:231], v[232:235], v[12:15]
	ds_read_b128 v[194:197], v147 offset:34816
	s_waitcnt lgkmcnt(5)
	v_mfma_f32_16x16x32_bf16 v[84:87], v[216:219], v[236:239], v[84:87]
	ds_read_b128 v[202:205], v147 offset:35840
	ds_read_b128 v[232:235], v148 offset:49152
	v_mfma_f32_16x16x32_bf16 v[56:59], v[220:223], v[236:239], v[56:59]
	s_mov_b32 m0, s11
	v_mfma_f32_16x16x32_bf16 v[24:27], v[224:227], v[236:239], v[24:27]
	v_readfirstlane_b32 s11, v166
	v_mfma_f32_16x16x32_bf16 v[8:11], v[228:231], v[236:239], v[8:11]
	global_load_lds_dwordx4 v[200:201], off
	s_waitcnt lgkmcnt(6)
	v_mfma_f32_16x16x32_bf16 v[80:83], v[216:219], v[240:243], v[80:83]
	ds_read_b128 v[236:239], v148 offset:50176
	v_mfma_f32_16x16x32_bf16 v[52:55], v[220:223], v[240:243], v[52:55]
	s_mov_b32 m0, s11
	v_mfma_f32_16x16x32_bf16 v[20:23], v[224:227], v[240:243], v[20:23]
	global_load_lds_dwordx4 v[134:135], off
	v_mfma_f32_16x16x32_bf16 v[4:7], v[228:231], v[240:243], v[4:7]
	s_waitcnt lgkmcnt(6)
	v_mfma_f32_16x16x32_bf16 v[72:75], v[216:219], v[244:247], v[72:75]
	ds_read_b128 v[240:243], v148 offset:51200
	v_mfma_f32_16x16x32_bf16 v[48:51], v[220:223], v[244:247], v[48:51]
	v_mfma_f32_16x16x32_bf16 v[16:19], v[224:227], v[244:247], v[16:19]
	v_mfma_f32_16x16x32_bf16 v[0:3], v[228:231], v[244:247], v[0:3]
	ds_read_b128 v[244:247], v148 offset:52224
	s_waitcnt lgkmcnt(3)
	v_mfma_f32_16x16x32_bf16 v[124:127], v[186:189], v[232:235], v[124:127]
	v_mfma_f32_16x16x32_bf16 v[108:111], v[190:193], v[232:235], v[108:111]
	v_mfma_f32_16x16x32_bf16 v[88:91], v[194:197], v[232:235], v[88:91]
	v_mfma_f32_16x16x32_bf16 v[44:47], v[202:205], v[232:235], v[44:47]
	s_waitcnt vmcnt(4)
	s_barrier
	s_waitcnt lgkmcnt(2)
	v_mfma_f32_16x16x32_bf16 v[120:123], v[186:189], v[236:239], v[120:123]
	ds_read_b128 v[232:235], v148 offset:53248
	v_mfma_f32_16x16x32_bf16 v[104:107], v[190:193], v[236:239], v[104:107]
	v_mfma_f32_16x16x32_bf16 v[76:79], v[194:197], v[236:239], v[76:79]
	v_mfma_f32_16x16x32_bf16 v[40:43], v[202:205], v[236:239], v[40:43]
	s_waitcnt lgkmcnt(2)
	v_mfma_f32_16x16x32_bf16 v[116:119], v[186:189], v[240:243], v[116:119]
	ds_read_b128 v[236:239], v148 offset:54272
	v_mfma_f32_16x16x32_bf16 v[100:103], v[190:193], v[240:243], v[100:103]
	v_mfma_f32_16x16x32_bf16 v[68:71], v[194:197], v[240:243], v[68:71]
	v_mfma_f32_16x16x32_bf16 v[36:39], v[202:205], v[240:243], v[36:39]
	s_waitcnt lgkmcnt(2)
	v_mfma_f32_16x16x32_bf16 v[112:115], v[186:189], v[244:247], v[112:115]
	ds_read_b128 v[240:243], v148 offset:55296
	v_mfma_f32_16x16x32_bf16 v[96:99], v[190:193], v[244:247], v[96:99]
	v_mfma_f32_16x16x32_bf16 v[64:67], v[194:197], v[244:247], v[64:67]
	v_mfma_f32_16x16x32_bf16 v[32:35], v[202:205], v[244:247], v[32:35]
	s_waitcnt lgkmcnt(2)
	v_mfma_f32_16x16x32_bf16 v[92:95], v[186:189], v[232:235], v[92:95]
	ds_read_b128 v[244:247], v148 offset:56320
	v_mfma_f32_16x16x32_bf16 v[60:63], v[190:193], v[232:235], v[60:63]
	v_mfma_f32_16x16x32_bf16 v[28:31], v[194:197], v[232:235], v[28:31]
	v_mfma_f32_16x16x32_bf16 v[12:15], v[202:205], v[232:235], v[12:15]
	s_waitcnt lgkmcnt(2)
	v_mfma_f32_16x16x32_bf16 v[84:87], v[186:189], v[236:239], v[84:87]
	v_mfma_f32_16x16x32_bf16 v[56:59], v[190:193], v[236:239], v[56:59]
	v_mfma_f32_16x16x32_bf16 v[24:27], v[194:197], v[236:239], v[24:27]
	v_mfma_f32_16x16x32_bf16 v[8:11], v[202:205], v[236:239], v[8:11]
	s_waitcnt lgkmcnt(1)
	v_mfma_f32_16x16x32_bf16 v[80:83], v[186:189], v[240:243], v[80:83]
	v_mfma_f32_16x16x32_bf16 v[52:55], v[190:193], v[240:243], v[52:55]
	v_mfma_f32_16x16x32_bf16 v[20:23], v[194:197], v[240:243], v[20:23]
	v_mfma_f32_16x16x32_bf16 v[4:7], v[202:205], v[240:243], v[4:7]
	s_waitcnt lgkmcnt(0)
	v_mfma_f32_16x16x32_bf16 v[72:75], v[186:189], v[244:247], v[72:75]
	v_mfma_f32_16x16x32_bf16 v[48:51], v[190:193], v[244:247], v[48:51]
	v_mfma_f32_16x16x32_bf16 v[16:19], v[194:197], v[244:247], v[16:19]
	v_mfma_f32_16x16x32_bf16 v[0:3], v[202:205], v[244:247], v[0:3]
	v_mov_b32_e32 v186, 0xf149f2ca
	v_mov_b32_e32 v187, 0x3c0881c4
	v_mov_b32_e32 v188, 0xbab64f3b
	v_mov_b32_e32 v189, 0x24800
	v_mov_b32_e32 v190, 1
	v_mov_b32_e32 v191, 0x24804
	v_mov_b32_e32 v192, 0xfcf
	v_mov_b32_e32 v193, 0x7cf
	v_mov_b32_e32 v194, 0xfdf
	v_mov_b32_e32 v195, 0x7df
	v_mov_b32_e32 v196, 0xfef
	v_mov_b32_e32 v197, 0x7ef
	v_mov_b32_e32 v198, 0xfff
	v_mov_b32_e32 v199, 0x7ff
	v_mov_b32_e32 v200, 0x20000
	v_mov_b32_e32 v201, 0xf8f
	v_mov_b32_e32 v202, 0x78f
	v_mov_b32_e32 v203, 0xf9f
	v_mov_b32_e32 v204, 0x79f
	v_mov_b32_e32 v205, 0xfaf
	v_mov_b32_e32 v210, 0x7f800000
	v_not_b32_e32 v211, 63
	v_not_b32_e32 v212, 31
	v_mov_b32_e32 v213, 0x7fc00000
	s_waitcnt vmcnt(4)
	s_barrier
; __device__ __forceinline__ int widen_off(int fq) { return ((fq & 1) << 4) + ((fq >> 1) << 3); }
; template <int NK, bool BNT = false> ...
;     ...
;   auto kstep = [&](int T, int cur, int nxt, bool do_stage) {
;     const unsigned char* sa = smem + cur * BIG_STAGE;
;     bf16x8 af[4], bfr[4];
; #pragma unroll
;     for (int m = 0; m < 4; ++m) af[m] = *reinterpret_cast<const bf16x8*>(sa + aoff + m * 1024);
; #pragma unroll
;     for (int n = 0; n < 4; ++n) bfr[n] = *reinterpret_cast<const bf16x8*>(sa + boff + n * 1024);
;     __builtin_amdgcn_sched_barrier(0);
;     if (do_stage) stage(T + 3, nxt);
; #pragma unroll
;     for (int m = 0; m < 4; ++m)
; #pragma unroll
;       for (int n = 0; n < 4; ++n) acc[m][n] = __builtin_amdgcn_mfma_f32_16x16x32_bf16(af[m], bfr[n], acc[m][n], 0, 0, 0);
;     if (do_stage) {
; #pragma unroll
;       for (int q = 0; q < NG; ++q) {
;         __builtin_amdgcn_sched_group_barrier(0x008, 3, 0);
;         __builtin_amdgcn_sched_group_barrier(0x010, 1, 0);
;       }
;       __builtin_amdgcn_sched_group_barrier(0x008, 16 - 3 * NG, 0);
;     }
;     __builtin_amdgcn_sched_barrier(0);
; #pragma unroll
;     for (int n = 0; n < 4; ++n) bfr[n] = *reinterpret_cast<const bf16x8*>(sa + boff + (4 + n) * 1024);
; #pragma unroll
;     for (int m = 0; m < 4; ++m)
; #pragma unroll
;       for (int n = 0; n < 4; ++n)
;         acc[m][4 + n] = __builtin_amdgcn_mfma_f32_16x16x32_bf16(af[m], bfr[n], acc[m][4 + n], 0, 0, 0);
;     __builtin_amdgcn_sched_barrier(0);
; template <int MODE, int NSUB>
; __device__ __forceinline__ void epilogue(const Params& p, int layer, f32x4 (&acc)[4][NSUB], int tm, int tn, int g,
;                                          const float* s_rstd, const int tid_in) {
;     ...
;   } else if constexpr (MODE == EPI_UP) {
;     const int woff = widen_off(fq);
; #pragma unroll
;     for (int n = 0; n < NSUB; ++n) {
;       const int nl = wc * (NSUB * 16) + n * 16 + fr;
;       const int t = tn * (NSUB * 32) + nl;
;       const float rs = s_rstd[nl];
; #pragma unroll
	ds_read_b128 v[134:137], v167
	ds_read_b128 v[138:141], v167 offset:1024
	ds_read_b128 v[154:157], v167 offset:2048
	ds_read_b128 v[158:161], v167 offset:3072
	ds_read_b128 v[162:165], v168
	ds_read_b128 v[166:169], v169
	ds_read_b128 v[216:219], v170
	ds_read_b128 v[220:223], v172
	s_waitcnt lgkmcnt(0)
	v_mfma_f32_16x16x32_bf16 v[124:127], v[134:137], v[162:165], v[124:127]
	v_mfma_f32_16x16x32_bf16 v[120:123], v[134:137], v[166:169], v[120:123]
	v_mfma_f32_16x16x32_bf16 v[116:119], v[134:137], v[216:219], v[116:119]
	v_mfma_f32_16x16x32_bf16 v[112:115], v[134:137], v[220:223], v[112:115]
	v_mfma_f32_16x16x32_bf16 v[224:227], v[138:141], v[162:165], v[108:111]
	v_mfma_f32_16x16x32_bf16 v[104:107], v[138:141], v[166:169], v[104:107]
	v_mfma_f32_16x16x32_bf16 v[100:103], v[138:141], v[216:219], v[100:103]
	v_mfma_f32_16x16x32_bf16 v[96:99], v[138:141], v[220:223], v[96:99]
	v_mfma_f32_16x16x32_bf16 v[228:231], v[154:157], v[162:165], v[88:91]
	v_mfma_f32_16x16x32_bf16 v[232:235], v[154:157], v[166:169], v[76:79]
	v_mfma_f32_16x16x32_bf16 v[68:71], v[154:157], v[216:219], v[68:71]
	v_mfma_f32_16x16x32_bf16 v[64:67], v[154:157], v[220:223], v[64:67]
	v_mfma_f32_16x16x32_bf16 v[44:47], v[158:161], v[162:165], v[44:47]
	v_mfma_f32_16x16x32_bf16 v[40:43], v[158:161], v[166:169], v[40:43]
	v_mfma_f32_16x16x32_bf16 v[36:39], v[158:161], v[216:219], v[36:39]
	v_mfma_f32_16x16x32_bf16 v[32:35], v[158:161], v[220:223], v[32:35]
	ds_read_b128 v[76:79], v173
	ds_read_b128 v[88:91], v174
	s_waitcnt lgkmcnt(0)
	v_mfma_f32_16x16x32_bf16 v[162:165], v[134:137], v[76:79], v[92:95]
	s_nop 2
	ds_read_b128 v[92:95], v178
	v_mfma_f32_16x16x32_bf16 v[166:169], v[134:137], v[88:91], v[84:87]
	s_nop 2
	ds_read_b128 v[84:87], v175
	s_waitcnt lgkmcnt(0)
	v_mfma_f32_16x16x32_bf16 v[172:175], v[134:137], v[84:87], v[80:83]
	v_mfma_f32_16x16x32_bf16 v[134:137], v[134:137], v[92:95], v[72:75]
	v_mfma_f32_16x16x32_bf16 v[216:219], v[138:141], v[76:79], v[60:63]
	v_mfma_f32_16x16x32_bf16 v[220:223], v[138:141], v[88:91], v[56:59]
	v_mfma_f32_16x16x32_bf16 v[52:55], v[138:141], v[84:87], v[52:55]
	v_mfma_f32_16x16x32_bf16 v[48:51], v[138:141], v[92:95], v[48:51]
	v_mfma_f32_16x16x32_bf16 v[138:141], v[154:157], v[76:79], v[28:31]
	v_mfma_f32_16x16x32_bf16 v[236:239], v[154:157], v[88:91], v[24:27]
	v_mfma_f32_16x16x32_bf16 v[20:23], v[154:157], v[84:87], v[20:23]
	v_mfma_f32_16x16x32_bf16 v[16:19], v[154:157], v[92:95], v[16:19]
	v_mfma_f32_16x16x32_bf16 v[154:157], v[158:161], v[76:79], v[12:15]
	v_mfma_f32_16x16x32_bf16 v[240:243], v[158:161], v[88:91], v[8:11]
	v_mfma_f32_16x16x32_bf16 v[244:247], v[158:161], v[84:87], v[4:7]
	v_mfma_f32_16x16x32_bf16 v[0:3], v[158:161], v[92:95], v[0:3]
	s_waitcnt vmcnt(0)
	s_barrier
	s_nop 0
	ds_read_b128 v[4:7], v176
	ds_read_b128 v[8:11], v176 offset:1024
	ds_read_b128 v[158:161], v176 offset:2048
	ds_read_b128 v[248:251], v176 offset:3072
	ds_read_b128 v[12:15], v179
	ds_read_b128 v[24:27], v180
	ds_read_b128 v[28:31], v181
	ds_read_b128 v[56:59], v182
	s_waitcnt lgkmcnt(0)
	v_mfma_f32_16x16x32_bf16 v[124:127], v[4:7], v[12:15], v[124:127]
	v_mfma_f32_16x16x32_bf16 v[108:111], v[4:7], v[24:27], v[120:123]
	v_mfma_f32_16x16x32_bf16 v[92:95], v[4:7], v[28:31], v[116:119]
	v_mfma_f32_16x16x32_bf16 v[76:79], v[4:7], v[56:59], v[112:115]
	v_mfma_f32_16x16x32_bf16 v[112:115], v[8:11], v[12:15], v[224:227]
	v_mfma_f32_16x16x32_bf16 v[104:107], v[8:11], v[24:27], v[104:107]
	v_mfma_f32_16x16x32_bf16 v[88:91], v[8:11], v[28:31], v[100:103]
	v_mfma_f32_16x16x32_bf16 v[72:75], v[8:11], v[56:59], v[96:99]
	v_mfma_f32_16x16x32_bf16 v[120:123], v[158:161], v[12:15], v[228:231]
	v_mfma_f32_16x16x32_bf16 v[100:103], v[158:161], v[24:27], v[232:235]
	v_mfma_f32_16x16x32_bf16 v[84:87], v[158:161], v[28:31], v[68:71]
	v_mfma_f32_16x16x32_bf16 v[68:71], v[158:161], v[56:59], v[64:67]
	v_mfma_f32_16x16x32_bf16 v[178:181], v[248:251], v[12:15], v[44:47]
	v_mfma_f32_16x16x32_bf16 v[96:99], v[248:251], v[24:27], v[40:43]
	v_mfma_f32_16x16x32_bf16 v[80:83], v[248:251], v[28:31], v[36:39]
	v_mfma_f32_16x16x32_bf16 v[64:67], v[248:251], v[56:59], v[32:35]
	s_nop 2
	ds_read_b128 v[32:35], v142
	ds_read_b128 v[116:119], v143
	s_waitcnt lgkmcnt(0)
	v_mfma_f32_16x16x32_bf16 v[60:63], v[4:7], v[32:35], v[162:165]
	s_nop 2
	ds_read_b128 v[162:165], v144
	ds_read_b128 v[142:145], v145
	v_mfma_f32_16x16x32_bf16 v[44:47], v[4:7], v[116:119], v[166:169]
	s_waitcnt lgkmcnt(0)
	v_mfma_f32_16x16x32_bf16 v[28:31], v[4:7], v[162:165], v[172:175]
	v_mfma_f32_16x16x32_bf16 v[12:15], v[4:7], v[142:145], v[134:137]
	v_mfma_f32_16x16x32_bf16 v[56:59], v[8:11], v[32:35], v[216:219]
	v_mfma_f32_16x16x32_bf16 v[40:43], v[8:11], v[116:119], v[220:223]
	v_mfma_f32_16x16x32_bf16 v[24:27], v[8:11], v[162:165], v[52:55]
	v_mfma_f32_16x16x32_bf16 v[8:11], v[8:11], v[142:145], v[48:51]
	v_mfma_f32_16x16x32_bf16 v[52:55], v[158:161], v[32:35], v[138:141]
	v_mfma_f32_16x16x32_bf16 v[36:39], v[158:161], v[116:119], v[236:239]
	v_mfma_f32_16x16x32_bf16 v[20:23], v[158:161], v[162:165], v[20:23]
	v_mfma_f32_16x16x32_bf16 v[4:7], v[158:161], v[142:145], v[16:19]
	v_mfma_f32_16x16x32_bf16 v[48:51], v[248:251], v[32:35], v[154:157]
	v_mfma_f32_16x16x32_bf16 v[32:35], v[248:251], v[116:119], v[240:243]
	v_mfma_f32_16x16x32_bf16 v[16:19], v[248:251], v[162:165], v[244:247]
	v_mfma_f32_16x16x32_bf16 v[0:3], v[248:251], v[142:145], v[0:3]
	v_mov_b32_e32 v116, v215
	s_lshl_b32 s10, s10, 8
	v_and_b32_e32 v117, 16, v116
	v_lshrrev_b32_e32 v118, 2, v116
	v_and_or_b32 v136, v118, 8, v117
	v_lshlrev_b32_e32 v117, 1, v116
	v_and_b32_e32 v119, 15, v116
	v_and_b32_e32 v117, 0x80, v117
	v_lshl_or_b32 v134, s15, 8, v117
	v_or_b32_e32 v117, v117, v119
	v_ashrrev_i32_e32 v116, 1, v116
	v_lshlrev_b32_e32 v118, 2, v117
	v_and_b32_e32 v116, 0xffffffc0, v116
	v_add3_u32 v135, s10, v150, v116
	v_or_b32_e32 v116, 0x20000, v118
	ds_read_b32 v137, v116
	v_lshlrev_b32_e32 v152, 6, v119
	v_or_b32_e32 v119, 0x20040, v118
	v_readlane_b32 s64, v252, 4
	ds_read_b32 v119, v119
	s_waitcnt lgkmcnt(0)
; template <int MODE, int NSUB>
; __device__ __forceinline__ void epilogue(const Params& p, int layer, f32x4 (&acc)[4][NSUB], int tm, int tn, int g,
;                                          const float* s_rstd, const int tid_in) {
;     ...
;       for (int mp = 0; mp < 2; ++mp) {
;         bf16x4 pk[2];
; #pragma unroll
;         for (int h2 = 0; h2 < 2; ++h2) {
;           const int m = mp * 2 + h2;
;           float v[4];
; #pragma unroll
;           for (int j = 0; j < 4; ++j) {
;             float a = fmaxf(acc[m][n][j] * rs, 0.f);
;             v[j] = a * a;
;           }
;           pk[h2] = pack4(v[0], v[1], v[2], v[3]);
;         }
;         const int f = tm * 128 + wr * 64 + mp * 32 + woff;
;         __builtin_nontemporal_store(widen_pair(pk[0], pk[1]), reinterpret_cast<u32x4*>(p.hm + blk(t, f, 128)));
;       }
	v_mul_f32_e32 v116, v124, v137
	v_mul_f32_e32 v117, v125, v137
	v_mul_f32_e32 v124, v126, v137
	v_mul_f32_e32 v125, v127, v137
	v_mul_f32_e32 v112, v112, v137
	v_mul_f32_e32 v113, v113, v137
	v_max_f32_e32 v124, 0, v124
	v_max_f32_e32 v125, 0, v125
	v_max_f32_e32 v112, 0, v112
	v_max_f32_e32 v113, 0, v113
	v_mul_f32_e32 v114, v114, v137
	v_mul_f32_e32 v115, v115, v137
	v_pk_mul_f32 v[126:127], v[124:125], v[124:125]
	v_pk_mul_f32 v[112:113], v[112:113], v[112:113]
	v_max_f32_e32 v114, 0, v114
	v_max_f32_e32 v115, 0, v115
	v_cvt_pk_bf16_f32 v125, v126, v127
	v_pk_mul_f32 v[114:115], v[114:115], v[114:115]
	v_cvt_pk_bf16_f32 v126, v112, v113
	v_ashrrev_i32_e32 v112, 5, v135
	v_cvt_pk_bf16_f32 v127, v114, v115
	v_add_u32_e32 v114, v112, v134
	v_ashrrev_i32_e32 v115, 31, v114
	v_lshlrev_b64 v[112:113], 13, v[114:115]
	v_mul_f32_e32 v115, v120, v137
	v_max_f32_e32 v120, 0, v115
	v_mul_f32_e32 v115, v121, v137
	v_max_f32_e32 v121, 0, v115
	v_mul_f32_e32 v115, v122, v137
	v_max_f32_e32 v116, 0, v116
	v_max_f32_e32 v117, 0, v117
	v_max_f32_e32 v122, 0, v115
	v_mul_f32_e32 v115, v123, v137
	v_pk_mul_f32 v[116:117], v[116:117], v[116:117]
	v_readlane_b32 s78, v252, 18
	v_readlane_b32 s79, v252, 19
	v_max_f32_e32 v123, 0, v115
	v_cvt_pk_bf16_f32 v124, v116, v117
	v_lshl_add_u64 v[116:117], s[78:79], 0, v[112:113]
	v_pk_mul_f32 v[120:121], v[120:121], v[120:121]
	v_pk_mul_f32 v[122:123], v[122:123], v[122:123]
	v_mul_f32_e32 v115, v178, v137
	v_lshl_add_u64 v[134:135], v[116:117], 0, v[152:153]
	v_lshlrev_b32_e32 v112, 1, v136
	v_mov_b32_e32 v113, v153
	v_cvt_pk_bf16_f32 v120, v120, v121
	v_cvt_pk_bf16_f32 v121, v122, v123
	v_max_f32_e32 v122, 0, v115
	v_mul_f32_e32 v115, v179, v137
	v_permlane16_swap_b32_e32 v124, v126
	v_permlane16_swap_b32_e32 v125, v127
	v_lshl_add_u64 v[134:135], v[134:135], 0, v[112:113]
	v_max_f32_e32 v123, 0, v115
	v_mul_f32_e32 v115, v180, v137
	global_store_dwordx4 v[134:135], v[124:127], off nt
	v_add_u32_e32 v114, 1, v114
	v_mul_f32_e32 v108, v108, v119
	v_max_f32_e32 v124, 0, v115
	v_mul_f32_e32 v115, v181, v137
	v_mul_f32_e32 v109, v109, v119
	v_mul_f32_e32 v110, v110, v119
	v_mul_f32_e32 v111, v111, v119
	v_mul_f32_e32 v104, v104, v119
	v_mul_f32_e32 v105, v105, v119
	v_max_f32_e32 v125, 0, v115
	v_ashrrev_i32_e32 v115, 31, v114
	v_max_f32_e32 v108, 0, v108
	v_max_f32_e32 v109, 0, v109
	v_max_f32_e32 v110, 0, v110
	v_max_f32_e32 v111, 0, v111
	v_max_f32_e32 v104, 0, v104
	v_max_f32_e32 v105, 0, v105
	v_mul_f32_e32 v100, v100, v119
	v_mul_f32_e32 v101, v101, v119
	v_mul_f32_e32 v102, v102, v119
	v_mul_f32_e32 v103, v103, v119
	v_mul_f32_e32 v96, v96, v119
	v_mul_f32_e32 v97, v97, v119
	v_mul_f32_e32 v98, v98, v119
	v_mul_f32_e32 v99, v99, v119
	v_lshlrev_b64 v[114:115], 13, v[114:115]
	v_pk_mul_f32 v[108:109], v[108:109], v[108:109]
	v_pk_mul_f32 v[110:111], v[110:111], v[110:111]
	v_pk_mul_f32 v[104:105], v[104:105], v[104:105]
	v_max_f32_e32 v100, 0, v100
	v_max_f32_e32 v101, 0, v101
	v_max_f32_e32 v102, 0, v102
	v_max_f32_e32 v103, 0, v103
	v_max_f32_e32 v96, 0, v96
	v_max_f32_e32 v97, 0, v97
	v_max_f32_e32 v98, 0, v98
	v_max_f32_e32 v99, 0, v99
	v_lshl_add_u64 v[114:115], s[78:79], 0, v[114:115]
	v_cvt_pk_bf16_f32 v108, v108, v109
	v_cvt_pk_bf16_f32 v109, v110, v111
	v_cvt_pk_bf16_f32 v110, v104, v105
	v_or_b32_e32 v104, 0x400, v152
	v_mov_b32_e32 v105, v153
	v_pk_mul_f32 v[100:101], v[100:101], v[100:101]
	v_pk_mul_f32 v[102:103], v[102:103], v[102:103]
	v_pk_mul_f32 v[96:97], v[96:97], v[96:97]
	v_pk_mul_f32 v[98:99], v[98:99], v[98:99]
	v_cvt_pk_bf16_f32 v100, v100, v101
	v_cvt_pk_bf16_f32 v101, v102, v103
	v_cvt_pk_bf16_f32 v102, v96, v97
	v_cvt_pk_bf16_f32 v103, v98, v99
	v_lshl_add_u64 v[96:97], v[114:115], 0, v[104:105]
	v_permlane16_swap_b32_e32 v100, v102
	v_permlane16_swap_b32_e32 v101, v103
	v_lshl_add_u64 v[96:97], v[96:97], 0, v[112:113]
	global_store_dwordx4 v[96:97], v[100:103], off nt
	v_or_b32_e32 v96, 0x20080, v118
	ds_read_b32 v96, v96
	v_mul_f32_e32 v106, v106, v119
	v_mul_f32_e32 v107, v107, v119
	v_pk_mul_f32 v[122:123], v[122:123], v[122:123]
	v_pk_mul_f32 v[124:125], v[124:125], v[124:125]
	s_waitcnt lgkmcnt(0)
	v_mul_f32_e32 v92, v92, v96
	v_mul_f32_e32 v93, v93, v96
	v_mul_f32_e32 v94, v94, v96
	v_mul_f32_e32 v95, v95, v96
	v_mul_f32_e32 v88, v88, v96
	v_mul_f32_e32 v89, v89, v96
	v_max_f32_e32 v92, 0, v92
	v_max_f32_e32 v93, 0, v93
	v_max_f32_e32 v94, 0, v94
	v_max_f32_e32 v95, 0, v95
	v_max_f32_e32 v88, 0, v88
	v_max_f32_e32 v89, 0, v89
	v_mul_f32_e32 v84, v84, v96
	v_mul_f32_e32 v85, v85, v96
	v_mul_f32_e32 v86, v86, v96
	v_mul_f32_e32 v87, v87, v96
	v_mul_f32_e32 v80, v80, v96
	v_mul_f32_e32 v81, v81, v96
	v_mul_f32_e32 v82, v82, v96
	v_mul_f32_e32 v83, v83, v96
	v_pk_mul_f32 v[92:93], v[92:93], v[92:93]
	v_pk_mul_f32 v[94:95], v[94:95], v[94:95]
	v_pk_mul_f32 v[88:89], v[88:89], v[88:89]
	v_max_f32_e32 v84, 0, v84
	v_max_f32_e32 v85, 0, v85
	v_max_f32_e32 v86, 0, v86
	v_max_f32_e32 v87, 0, v87
	v_max_f32_e32 v80, 0, v80
	v_max_f32_e32 v81, 0, v81
	v_max_f32_e32 v82, 0, v82
	v_max_f32_e32 v83, 0, v83
	v_cvt_pk_bf16_f32 v92, v92, v93
	v_cvt_pk_bf16_f32 v93, v94, v95
	v_cvt_pk_bf16_f32 v94, v88, v89
	v_or_b32_e32 v88, 0x800, v152
	v_mov_b32_e32 v89, v153
	v_pk_mul_f32 v[84:85], v[84:85], v[84:85]
	v_pk_mul_f32 v[86:87], v[86:87], v[86:87]
	v_pk_mul_f32 v[80:81], v[80:81], v[80:81]
	v_pk_mul_f32 v[82:83], v[82:83], v[82:83]
	v_cvt_pk_bf16_f32 v84, v84, v85
	v_cvt_pk_bf16_f32 v85, v86, v87
	v_cvt_pk_bf16_f32 v86, v80, v81
	v_cvt_pk_bf16_f32 v87, v82, v83
	v_lshl_add_u64 v[80:81], v[114:115], 0, v[88:89]
	v_permlane16_swap_b32_e32 v84, v86
	v_permlane16_swap_b32_e32 v85, v87
	v_lshl_add_u64 v[80:81], v[80:81], 0, v[112:113]
	global_store_dwordx4 v[80:81], v[84:87], off nt
	v_or_b32_e32 v80, 0x200c0, v118
	ds_read_b32 v80, v80
	v_mul_f32_e32 v90, v90, v96
	v_mul_f32_e32 v91, v91, v96
	v_max_f32_e32 v106, 0, v106
	v_max_f32_e32 v107, 0, v107
	s_waitcnt lgkmcnt(0)
; template <int MODE, int NSUB>
; __device__ __forceinline__ void epilogue(const Params& p, int layer, f32x4 (&acc)[4][NSUB], int tm, int tn, int g,
;                                          const float* s_rstd, const int tid_in) {
;     ...
;       for (int mp = 0; mp < 2; ++mp) {
;         bf16x4 pk[2];
; #pragma unroll
;         for (int h2 = 0; h2 < 2; ++h2) {
;           const int m = mp * 2 + h2;
;           float v[4];
; #pragma unroll
;           for (int j = 0; j < 4; ++j) {
;             float a = fmaxf(acc[m][n][j] * rs, 0.f);
;             v[j] = a * a;
;           }
;           pk[h2] = pack4(v[0], v[1], v[2], v[3]);
;         }
;         const int f = tm * 128 + wr * 64 + mp * 32 + woff;
;         __builtin_nontemporal_store(widen_pair(pk[0], pk[1]), reinterpret_cast<u32x4*>(p.hm + blk(t, f, 128)));
;       }
	v_mul_f32_e32 v76, v76, v80
	v_mul_f32_e32 v77, v77, v80
	v_mul_f32_e32 v78, v78, v80
	v_mul_f32_e32 v79, v79, v80
	v_mul_f32_e32 v72, v72, v80
	v_mul_f32_e32 v73, v73, v80
	v_max_f32_e32 v76, 0, v76
	v_max_f32_e32 v77, 0, v77
	v_max_f32_e32 v78, 0, v78
	v_max_f32_e32 v79, 0, v79
	v_max_f32_e32 v72, 0, v72
	v_max_f32_e32 v73, 0, v73
	v_mul_f32_e32 v68, v68, v80
	v_mul_f32_e32 v69, v69, v80
	v_mul_f32_e32 v70, v70, v80
	v_mul_f32_e32 v71, v71, v80
	v_mul_f32_e32 v64, v64, v80
	v_mul_f32_e32 v65, v65, v80
	v_mul_f32_e32 v66, v66, v80
	v_mul_f32_e32 v67, v67, v80
	v_pk_mul_f32 v[76:77], v[76:77], v[76:77]
	v_pk_mul_f32 v[78:79], v[78:79], v[78:79]
	v_pk_mul_f32 v[72:73], v[72:73], v[72:73]
	v_max_f32_e32 v68, 0, v68
	v_max_f32_e32 v69, 0, v69
	v_max_f32_e32 v70, 0, v70
	v_max_f32_e32 v71, 0, v71
	v_max_f32_e32 v64, 0, v64
	v_max_f32_e32 v65, 0, v65
	v_max_f32_e32 v66, 0, v66
	v_max_f32_e32 v67, 0, v67
	v_cvt_pk_bf16_f32 v76, v76, v77
	v_cvt_pk_bf16_f32 v77, v78, v79
	v_cvt_pk_bf16_f32 v78, v72, v73
	v_or_b32_e32 v72, 0xc00, v152
	v_mov_b32_e32 v73, v153
	v_pk_mul_f32 v[68:69], v[68:69], v[68:69]
	v_pk_mul_f32 v[70:71], v[70:71], v[70:71]
	v_pk_mul_f32 v[64:65], v[64:65], v[64:65]
	v_pk_mul_f32 v[66:67], v[66:67], v[66:67]
	v_cvt_pk_bf16_f32 v68, v68, v69
	v_cvt_pk_bf16_f32 v69, v70, v71
	v_cvt_pk_bf16_f32 v70, v64, v65
	v_cvt_pk_bf16_f32 v71, v66, v67
	v_lshl_add_u64 v[64:65], v[114:115], 0, v[72:73]
	v_permlane16_swap_b32_e32 v68, v70
	v_permlane16_swap_b32_e32 v69, v71
	v_lshl_add_u64 v[64:65], v[64:65], 0, v[112:113]
	global_store_dwordx4 v[64:65], v[68:71], off nt
	v_or_b32_e32 v64, 0x20100, v118
	ds_read_b32 v64, v64
	v_mul_f32_e32 v74, v74, v80
	v_mul_f32_e32 v75, v75, v80
	v_max_f32_e32 v90, 0, v90
	v_max_f32_e32 v91, 0, v91
	s_waitcnt lgkmcnt(0)
	v_mul_f32_e32 v60, v60, v64
	v_mul_f32_e32 v61, v61, v64
	v_mul_f32_e32 v62, v62, v64
	v_mul_f32_e32 v63, v63, v64
	v_mul_f32_e32 v56, v56, v64
	v_mul_f32_e32 v57, v57, v64
	v_max_f32_e32 v60, 0, v60
	v_max_f32_e32 v61, 0, v61
	v_max_f32_e32 v62, 0, v62
	v_max_f32_e32 v63, 0, v63
	v_max_f32_e32 v56, 0, v56
	v_max_f32_e32 v57, 0, v57
	v_mul_f32_e32 v52, v52, v64
	v_mul_f32_e32 v53, v53, v64
	v_mul_f32_e32 v54, v54, v64
	v_mul_f32_e32 v55, v55, v64
	v_mul_f32_e32 v48, v48, v64
	v_mul_f32_e32 v49, v49, v64
	v_mul_f32_e32 v50, v50, v64
	v_mul_f32_e32 v51, v51, v64
	v_pk_mul_f32 v[60:61], v[60:61], v[60:61]
	v_pk_mul_f32 v[62:63], v[62:63], v[62:63]
	v_pk_mul_f32 v[56:57], v[56:57], v[56:57]
	v_max_f32_e32 v52, 0, v52
	v_max_f32_e32 v53, 0, v53
	v_max_f32_e32 v54, 0, v54
	v_max_f32_e32 v55, 0, v55
	v_max_f32_e32 v48, 0, v48
	v_max_f32_e32 v49, 0, v49
	v_max_f32_e32 v50, 0, v50
	v_max_f32_e32 v51, 0, v51
	v_cvt_pk_bf16_f32 v60, v60, v61
	v_cvt_pk_bf16_f32 v61, v62, v63
	v_cvt_pk_bf16_f32 v62, v56, v57
	v_or_b32_e32 v56, 0x1000, v152
	v_mov_b32_e32 v57, v153
	v_pk_mul_f32 v[52:53], v[52:53], v[52:53]
	v_pk_mul_f32 v[54:55], v[54:55], v[54:55]
	v_pk_mul_f32 v[48:49], v[48:49], v[48:49]
	v_pk_mul_f32 v[50:51], v[50:51], v[50:51]
	v_cvt_pk_bf16_f32 v52, v52, v53
	v_cvt_pk_bf16_f32 v53, v54, v55
	v_cvt_pk_bf16_f32 v54, v48, v49
	v_cvt_pk_bf16_f32 v55, v50, v51
	v_lshl_add_u64 v[48:49], v[114:115], 0, v[56:57]
	v_permlane16_swap_b32_e32 v52, v54
	v_permlane16_swap_b32_e32 v53, v55
	v_lshl_add_u64 v[48:49], v[48:49], 0, v[112:113]
	global_store_dwordx4 v[48:49], v[52:55], off nt
	v_or_b32_e32 v48, 0x20140, v118
	ds_read_b32 v48, v48
	v_mul_f32_e32 v58, v58, v64
	v_mul_f32_e32 v59, v59, v64
	v_max_f32_e32 v74, 0, v74
	v_max_f32_e32 v75, 0, v75
	s_waitcnt lgkmcnt(0)
	v_mul_f32_e32 v44, v44, v48
	v_mul_f32_e32 v45, v45, v48
	v_mul_f32_e32 v46, v46, v48
	v_mul_f32_e32 v47, v47, v48
	v_mul_f32_e32 v40, v40, v48
	v_mul_f32_e32 v41, v41, v48
	v_max_f32_e32 v44, 0, v44
	v_max_f32_e32 v45, 0, v45
	v_max_f32_e32 v46, 0, v46
	v_max_f32_e32 v47, 0, v47
	v_max_f32_e32 v40, 0, v40
	v_max_f32_e32 v41, 0, v41
	v_mul_f32_e32 v36, v36, v48
	v_mul_f32_e32 v37, v37, v48
	v_mul_f32_e32 v38, v38, v48
	v_mul_f32_e32 v39, v39, v48
	v_mul_f32_e32 v32, v32, v48
	v_mul_f32_e32 v33, v33, v48
	v_mul_f32_e32 v34, v34, v48
	v_mul_f32_e32 v35, v35, v48
	v_pk_mul_f32 v[44:45], v[44:45], v[44:45]
	v_pk_mul_f32 v[46:47], v[46:47], v[46:47]
	v_pk_mul_f32 v[40:41], v[40:41], v[40:41]
	v_max_f32_e32 v36, 0, v36
	v_max_f32_e32 v37, 0, v37
	v_max_f32_e32 v38, 0, v38
	v_max_f32_e32 v39, 0, v39
	v_max_f32_e32 v32, 0, v32
	v_max_f32_e32 v33, 0, v33
	v_max_f32_e32 v34, 0, v34
	v_max_f32_e32 v35, 0, v35
	v_cvt_pk_bf16_f32 v44, v44, v45
	v_cvt_pk_bf16_f32 v45, v46, v47
	v_cvt_pk_bf16_f32 v46, v40, v41
	v_or_b32_e32 v40, 0x1400, v152
	v_mov_b32_e32 v41, v153
	v_pk_mul_f32 v[36:37], v[36:37], v[36:37]
	v_pk_mul_f32 v[38:39], v[38:39], v[38:39]
	v_pk_mul_f32 v[32:33], v[32:33], v[32:33]
	v_pk_mul_f32 v[34:35], v[34:35], v[34:35]
	v_cvt_pk_bf16_f32 v36, v36, v37
	v_cvt_pk_bf16_f32 v37, v38, v39
	v_cvt_pk_bf16_f32 v38, v32, v33
	v_cvt_pk_bf16_f32 v39, v34, v35
	v_lshl_add_u64 v[32:33], v[114:115], 0, v[40:41]
	v_permlane16_swap_b32_e32 v36, v38
	v_permlane16_swap_b32_e32 v37, v39
	v_lshl_add_u64 v[32:33], v[32:33], 0, v[112:113]
	global_store_dwordx4 v[32:33], v[36:39], off nt
	v_or_b32_e32 v32, 0x20180, v118
	ds_read_b32 v32, v32
	v_mul_f32_e32 v42, v42, v48
	v_mul_f32_e32 v43, v43, v48
	v_max_f32_e32 v58, 0, v58
	v_max_f32_e32 v59, 0, v59
	s_waitcnt lgkmcnt(0)
; template <int MODE, int NSUB>
; __device__ __forceinline__ void epilogue(const Params& p, int layer, f32x4 (&acc)[4][NSUB], int tm, int tn, int g,
;                                          const float* s_rstd, const int tid_in) {
;     ...
;       for (int mp = 0; mp < 2; ++mp) {
;         bf16x4 pk[2];
; #pragma unroll
;         for (int h2 = 0; h2 < 2; ++h2) {
;           const int m = mp * 2 + h2;
;           float v[4];
; #pragma unroll
;           for (int j = 0; j < 4; ++j) {
;             float a = fmaxf(acc[m][n][j] * rs, 0.f);
;             v[j] = a * a;
;           }
;           pk[h2] = pack4(v[0], v[1], v[2], v[3]);
;         }
;         const int f = tm * 128 + wr * 64 + mp * 32 + woff;
;         __builtin_nontemporal_store(widen_pair(pk[0], pk[1]), reinterpret_cast<u32x4*>(p.hm + blk(t, f, 128)));
;       }
; __global__ void __launch_bounds__(NTHREADS) fwd_megakernel(Params p) {
;     ...
;           for (int id = rvid; id < 16 * CHUNK_TT; id += Greal) {
;             int ftb, ttl;
;             tile_decode_fb(id, 16, 4, ftb, ttl);
;             compute_rstd(p.part, 16, 1.0f / 1024.f, (chunk * CHUNK_TT + ttl) * 256, 256, s_rstd_b, tid_full);
;             f32x4 acc[4][8];
;             gemm_big<32>(acc, W + (long)ftb * 256 * 1024, 128 * 1024, p.xb + (long)(chunk * CHUNK_TT + ttl) * 256 * 1024, 128 * 1024, smem_all, tid_full);
;             const int ft = ftb * 2 + (widf >> 2);
;             epilogue<EPI_UP, 8>(p, l, acc, ft, ttl, 0, s_rstd_b, tid_e);
;             __syncthreads();
;           }
	v_mul_f32_e32 v28, v28, v32
	v_mul_f32_e32 v29, v29, v32
	v_mul_f32_e32 v30, v30, v32
	v_mul_f32_e32 v31, v31, v32
	v_mul_f32_e32 v24, v24, v32
	v_mul_f32_e32 v25, v25, v32
	v_max_f32_e32 v28, 0, v28
	v_max_f32_e32 v29, 0, v29
	v_max_f32_e32 v30, 0, v30
	v_max_f32_e32 v31, 0, v31
	v_max_f32_e32 v24, 0, v24
	v_max_f32_e32 v25, 0, v25
	v_mul_f32_e32 v20, v20, v32
	v_mul_f32_e32 v21, v21, v32
	v_mul_f32_e32 v22, v22, v32
	v_mul_f32_e32 v23, v23, v32
	v_mul_f32_e32 v16, v16, v32
	v_mul_f32_e32 v17, v17, v32
	v_mul_f32_e32 v18, v18, v32
	v_mul_f32_e32 v19, v19, v32
	v_pk_mul_f32 v[28:29], v[28:29], v[28:29]
	v_pk_mul_f32 v[30:31], v[30:31], v[30:31]
	v_pk_mul_f32 v[24:25], v[24:25], v[24:25]
	v_max_f32_e32 v20, 0, v20
	v_max_f32_e32 v21, 0, v21
	v_max_f32_e32 v22, 0, v22
	v_max_f32_e32 v23, 0, v23
	v_max_f32_e32 v16, 0, v16
	v_max_f32_e32 v17, 0, v17
	v_max_f32_e32 v18, 0, v18
	v_max_f32_e32 v19, 0, v19
	v_cvt_pk_bf16_f32 v28, v28, v29
	v_cvt_pk_bf16_f32 v29, v30, v31
	v_cvt_pk_bf16_f32 v30, v24, v25
	v_or_b32_e32 v24, 0x1800, v152
	v_mov_b32_e32 v25, v153
	v_pk_mul_f32 v[20:21], v[20:21], v[20:21]
	v_pk_mul_f32 v[22:23], v[22:23], v[22:23]
	v_pk_mul_f32 v[16:17], v[16:17], v[16:17]
	v_pk_mul_f32 v[18:19], v[18:19], v[18:19]
	v_cvt_pk_bf16_f32 v20, v20, v21
	v_cvt_pk_bf16_f32 v21, v22, v23
	v_cvt_pk_bf16_f32 v22, v16, v17
	v_cvt_pk_bf16_f32 v23, v18, v19
	v_lshl_add_u64 v[16:17], v[114:115], 0, v[24:25]
	v_permlane16_swap_b32_e32 v20, v22
	v_permlane16_swap_b32_e32 v21, v23
	v_lshl_add_u64 v[16:17], v[16:17], 0, v[112:113]
	global_store_dwordx4 v[16:17], v[20:23], off nt
	v_or_b32_e32 v16, 0x201c0, v118
	ds_read_b32 v16, v16
	v_mul_f32_e32 v26, v26, v32
	v_mul_f32_e32 v27, v27, v32
	v_max_f32_e32 v42, 0, v42
	v_max_f32_e32 v43, 0, v43
	s_waitcnt lgkmcnt(0)
	v_mul_f32_e32 v12, v12, v16
	v_mul_f32_e32 v13, v13, v16
	v_mul_f32_e32 v14, v14, v16
	v_mul_f32_e32 v15, v15, v16
	v_mul_f32_e32 v8, v8, v16
	v_mul_f32_e32 v9, v9, v16
	v_mul_f32_e32 v10, v10, v16
	v_mul_f32_e32 v11, v11, v16
	v_mul_f32_e32 v4, v4, v16
	v_mul_f32_e32 v5, v5, v16
	v_mul_f32_e32 v6, v6, v16
	v_mul_f32_e32 v7, v7, v16
	v_mul_f32_e32 v0, v0, v16
	v_mul_f32_e32 v1, v1, v16
	v_mul_f32_e32 v2, v2, v16
	v_mul_f32_e32 v3, v3, v16
	v_max_f32_e32 v26, 0, v26
	v_max_f32_e32 v27, 0, v27
	v_max_f32_e32 v12, 0, v12
	v_max_f32_e32 v13, 0, v13
	v_max_f32_e32 v14, 0, v14
	v_max_f32_e32 v15, 0, v15
	v_max_f32_e32 v8, 0, v8
	v_max_f32_e32 v9, 0, v9
	v_max_f32_e32 v10, 0, v10
	v_max_f32_e32 v11, 0, v11
	v_max_f32_e32 v4, 0, v4
	v_max_f32_e32 v5, 0, v5
	v_max_f32_e32 v6, 0, v6
	v_max_f32_e32 v7, 0, v7
	v_max_f32_e32 v0, 0, v0
	v_max_f32_e32 v1, 0, v1
	v_max_f32_e32 v2, 0, v2
	v_max_f32_e32 v3, 0, v3
	v_cvt_pk_bf16_f32 v122, v122, v123
	v_cvt_pk_bf16_f32 v123, v124, v125
	v_lshl_add_u64 v[124:125], v[114:115], 0, v[152:153]
	v_pk_mul_f32 v[106:107], v[106:107], v[106:107]
	v_pk_mul_f32 v[90:91], v[90:91], v[90:91]
	v_pk_mul_f32 v[74:75], v[74:75], v[74:75]
	v_pk_mul_f32 v[58:59], v[58:59], v[58:59]
	v_pk_mul_f32 v[42:43], v[42:43], v[42:43]
	v_pk_mul_f32 v[26:27], v[26:27], v[26:27]
	v_pk_mul_f32 v[12:13], v[12:13], v[12:13]
	v_pk_mul_f32 v[14:15], v[14:15], v[14:15]
	v_pk_mul_f32 v[8:9], v[8:9], v[8:9]
	v_pk_mul_f32 v[10:11], v[10:11], v[10:11]
	v_or_b32_e32 v152, 0x1c00, v152
	v_pk_mul_f32 v[4:5], v[4:5], v[4:5]
	v_pk_mul_f32 v[6:7], v[6:7], v[6:7]
	v_pk_mul_f32 v[0:1], v[0:1], v[0:1]
	v_pk_mul_f32 v[2:3], v[2:3], v[2:3]
	v_cvt_pk_bf16_f32 v111, v106, v107
	v_lshl_add_u64 v[106:107], v[116:117], 0, v[104:105]
	v_cvt_pk_bf16_f32 v95, v90, v91
	v_lshl_add_u64 v[90:91], v[116:117], 0, v[88:89]
	v_cvt_pk_bf16_f32 v79, v74, v75
	v_lshl_add_u64 v[74:75], v[116:117], 0, v[72:73]
	v_cvt_pk_bf16_f32 v63, v58, v59
	v_lshl_add_u64 v[58:59], v[116:117], 0, v[56:57]
	v_cvt_pk_bf16_f32 v47, v42, v43
	v_lshl_add_u64 v[42:43], v[116:117], 0, v[40:41]
	v_cvt_pk_bf16_f32 v31, v26, v27
	v_lshl_add_u64 v[26:27], v[116:117], 0, v[24:25]
	v_cvt_pk_bf16_f32 v12, v12, v13
	v_cvt_pk_bf16_f32 v13, v14, v15
	v_cvt_pk_bf16_f32 v14, v8, v9
	v_cvt_pk_bf16_f32 v15, v10, v11
	v_lshl_add_u64 v[8:9], v[116:117], 0, v[152:153]
	v_cvt_pk_bf16_f32 v4, v4, v5
	v_cvt_pk_bf16_f32 v5, v6, v7
	v_cvt_pk_bf16_f32 v6, v0, v1
	v_cvt_pk_bf16_f32 v7, v2, v3
	v_lshl_add_u64 v[0:1], v[114:115], 0, v[152:153]
	s_add_i32 s9, s9, s26
	v_permlane16_swap_b32_e32 v120, v122
	v_permlane16_swap_b32_e32 v121, v123
	v_lshl_add_u64 v[124:125], v[124:125], 0, v[112:113]
	v_permlane16_swap_b32_e32 v108, v110
	v_permlane16_swap_b32_e32 v109, v111
	v_lshl_add_u64 v[106:107], v[106:107], 0, v[112:113]
	v_permlane16_swap_b32_e32 v92, v94
	v_permlane16_swap_b32_e32 v93, v95
	v_lshl_add_u64 v[90:91], v[90:91], 0, v[112:113]
	v_permlane16_swap_b32_e32 v76, v78
	v_permlane16_swap_b32_e32 v77, v79
	v_lshl_add_u64 v[74:75], v[74:75], 0, v[112:113]
	v_permlane16_swap_b32_e32 v60, v62
	v_permlane16_swap_b32_e32 v61, v63
	v_lshl_add_u64 v[58:59], v[58:59], 0, v[112:113]
	v_permlane16_swap_b32_e32 v44, v46
	v_permlane16_swap_b32_e32 v45, v47
	v_lshl_add_u64 v[42:43], v[42:43], 0, v[112:113]
	v_permlane16_swap_b32_e32 v28, v30
	v_permlane16_swap_b32_e32 v29, v31
	v_lshl_add_u64 v[26:27], v[26:27], 0, v[112:113]
	v_permlane16_swap_b32_e32 v12, v14
	v_permlane16_swap_b32_e32 v13, v15
	v_lshl_add_u64 v[8:9], v[8:9], 0, v[112:113]
	v_permlane16_swap_b32_e32 v4, v6
	v_permlane16_swap_b32_e32 v5, v7
	v_lshl_add_u64 v[0:1], v[0:1], 0, v[112:113]
	s_cmpk_gt_i32 s9, 0x13ff
	v_readlane_b32 s65, v252, 5
	v_readlane_b32 s66, v252, 6
	v_readlane_b32 s67, v252, 7
	v_readlane_b32 s68, v252, 8
	v_readlane_b32 s69, v252, 9
	v_readlane_b32 s70, v252, 10
	v_readlane_b32 s71, v252, 11
	v_readlane_b32 s72, v252, 12
	v_readlane_b32 s73, v252, 13
	v_readlane_b32 s74, v252, 14
	v_readlane_b32 s75, v252, 15
	v_readlane_b32 s76, v252, 16
	v_readlane_b32 s77, v252, 17
	global_store_dwordx4 v[124:125], v[120:123], off nt
	global_store_dwordx4 v[106:107], v[108:111], off nt
	global_store_dwordx4 v[90:91], v[92:95], off nt
	global_store_dwordx4 v[74:75], v[76:79], off nt
	global_store_dwordx4 v[58:59], v[60:63], off nt
	global_store_dwordx4 v[42:43], v[44:47], off nt
	global_store_dwordx4 v[26:27], v[28:31], off nt
	global_store_dwordx4 v[8:9], v[12:15], off nt
	global_store_dwordx4 v[0:1], v[4:7], off nt
	s_barrier
	s_cbranch_scc0 .LBB0_287

; #define BIG_SYNC(N)                                              \
;   asm volatile("s_waitcnt vmcnt(%0)" ::"n"(N) : "memory");       \
;   __builtin_amdgcn_s_barrier();                                  \
;   asm volatile("" ::: "memory");                                 \
;   __builtin_amdgcn_sched_barrier(0);
; template <int NK, bool BNT = false> ...
;     ...
;   auto stage = [&](int kt, int bufc) {
;     unsigned char* sa = smem + bufc * BIG_STAGE;
;     const unsigned char* Ab = Abase + (long)kt * 8192 + soff;
;     const unsigned char* Bb = Bbase + (long)kt * 8192 + soff;
;     glds16(Ab, sa + sb0);
;     glds16(Ab + astride * 2, sa + 8192 + sb0);
;     if constexpr (BNT) {
;       glds16_nt(Bb, sa + 16384 + sb0);
;       glds16_nt(Bb + bstride * 2, sa + 24576 + sb0);
;     } else {
;       glds16(Bb, sa + 16384 + sb0);
;       glds16(Bb + bstride * 2, sa + 24576 + sb0);
;     }
;   };
;   const int rd = fr * 64 + ((fq ^ (((fr >> 3) & 1) << 1)) * 16);
;   const int aoff = wr * 64 * 64 + rd;
;   const int boff = 16384 + wc * 128 * 64 + rd;
;   auto kstep = [&](int T, int cur, int nxt, bool do_stage) {
;     const unsigned char* sa = smem + cur * BIG_STAGE;
;     bf16x8 af[4], bfr[4];
; #pragma unroll
;     for (int m = 0; m < 4; ++m) af[m] = *reinterpret_cast<const bf16x8*>(sa + aoff + m * 1024);
; #pragma unroll
;     for (int n = 0; n < 4; ++n) bfr[n] = *reinterpret_cast<const bf16x8*>(sa + boff + n * 1024);
;     __builtin_amdgcn_sched_barrier(0);
;     if (do_stage) stage(T + 3, nxt);
; #pragma unroll
;     for (int m = 0; m < 4; ++m)
; #pragma unroll
;       for (int n = 0; n < 4; ++n) acc[m][n] = __builtin_amdgcn_mfma_f32_16x16x32_bf16(af[m], bfr[n], acc[m][n], 0, 0, 0);
;     if (do_stage) {
; #pragma unroll
;       for (int q = 0; q < NG; ++q) {
;         __builtin_amdgcn_sched_group_barrier(0x008, 3, 0);
;         __builtin_amdgcn_sched_group_barrier(0x010, 1, 0);
;       }
;       __builtin_amdgcn_sched_group_barrier(0x008, 16 - 3 * NG, 0);
;     }
;     __builtin_amdgcn_sched_barrier(0);
;     ...
;   for (int it = 0; it < NK / 4 - 1; ++it) {
;     const int t = it * 4;
;     BIG_SYNC(2 * NG); kstep(t, 0, 3, true);
;     BIG_SYNC(2 * NG); kstep(t + 1, 1, 0, true);
;     BIG_SYNC(2 * NG); kstep(t + 2, 2, 1, true);
;     BIG_SYNC(2 * NG); kstep(t + 3, 3, 2, true);
.Lmy_g1_rsdone:
	s_or_b64 exec, exec, s[100:101]
	s_waitcnt vmcnt(8)
	s_barrier
	v_add_u32_e32 v167, 0x10000, v148
	v_or_b32_e32 v168, 0x10000, v150
	v_add_u32_e32 v176, 0x18000, v148
	v_or_b32_e32 v179, 0x18000, v150
	v_add_u32_e32 v210, 0x10000, v148
	v_or_b32_e32 v211, 0x10000, v150
	v_add_u32_e32 v212, 0x18000, v148
	v_or_b32_e32 v213, 0x18000, v150
	v_readfirstlane_b32 s100, v147
	ds_read_b128 v[216:219], v148
	ds_read_b128 v[220:223], v148 offset:1024
	ds_read_b128 v[224:227], v148 offset:2048
	ds_read_b128 v[228:231], v148 offset:3072
	ds_read_b128 v[232:235], v149 offset:16384
	ds_read_b128 v[236:239], v149 offset:17408
	ds_read_b128 v[240:243], v149 offset:18432
	ds_read_b128 v[244:247], v149 offset:19456
.LBB0_302:
	s_waitcnt lgkmcnt(3)
	v_mfma_f32_16x16x32_bf16 v[56:59], v[216:219], v[232:235], v[56:59]
	v_add_u32_e32 v163, 0x18000, v147
	v_mfma_f32_16x16x32_bf16 v[100:103], v[220:223], v[232:235], v[100:103]
	v_lshl_add_u64 v[144:145], v[138:139], 0, s[6:7]
	v_mfma_f32_16x16x32_bf16 v[104:107], v[224:227], v[232:235], v[104:107]
	s_waitcnt vmcnt(4)
	s_barrier
	v_lshl_add_u64 v[164:165], v[144:145], 0, s[60:61]
	v_mfma_f32_16x16x32_bf16 v[112:115], v[228:231], v[232:235], v[112:115]
	s_add_i32 m0, s100, 0x18000
	s_waitcnt lgkmcnt(2)
	v_mfma_f32_16x16x32_bf16 v[64:67], v[216:219], v[236:239], v[64:67]
	ds_read_b128 v[232:235], v149 offset:20480
	v_mfma_f32_16x16x32_bf16 v[80:83], v[220:223], v[236:239], v[80:83]
	v_lshl_add_u64 v[142:143], v[140:141], 0, s[6:7]
	v_mfma_f32_16x16x32_bf16 v[96:99], v[224:227], v[236:239], v[96:99]
	v_lshl_add_u64 v[168:169], v[144:145], 0, s[80:81]
	v_mfma_f32_16x16x32_bf16 v[116:119], v[228:231], v[236:239], v[116:119]
	v_lshl_add_u64 v[166:167], v[142:143], 0, s[60:61]
	s_waitcnt lgkmcnt(2)
	v_mfma_f32_16x16x32_bf16 v[52:55], v[216:219], v[240:243], v[52:55]
	ds_read_b128 v[236:239], v149 offset:21504
	v_mfma_f32_16x16x32_bf16 v[68:71], v[220:223], v[240:243], v[68:71]
	global_load_lds_dwordx4 v[164:165], off
	v_mfma_f32_16x16x32_bf16 v[108:111], v[224:227], v[240:243], v[108:111]
	v_add_u32_e32 v164, 0x1a000, v147
	v_mfma_f32_16x16x32_bf16 v[120:123], v[228:231], v[240:243], v[120:123]
	v_add_u32_e32 v165, 0x1c000, v147
	s_waitcnt lgkmcnt(2)
	v_mfma_f32_16x16x32_bf16 v[48:51], v[216:219], v[244:247], v[48:51]
	ds_read_b128 v[240:243], v149 offset:22528
	v_mfma_f32_16x16x32_bf16 v[72:75], v[220:223], v[244:247], v[72:75]
	s_add_i32 m0, s100, 0x1a000
	v_mfma_f32_16x16x32_bf16 v[88:91], v[224:227], v[244:247], v[88:91]
	global_load_lds_dwordx4 v[168:169], off
	v_mfma_f32_16x16x32_bf16 v[124:127], v[228:231], v[244:247], v[124:127]
	s_add_i32 m0, s100, 0x1c000
	s_waitcnt lgkmcnt(2)
	v_mfma_f32_16x16x32_bf16 v[0:3], v[216:219], v[232:235], v[0:3]
	ds_read_b128 v[244:247], v149 offset:23552
	v_mfma_f32_16x16x32_bf16 v[16:19], v[220:223], v[232:235], v[16:19]
	ds_read_b128 v[186:189], v148 offset:32768
	v_mfma_f32_16x16x32_bf16 v[32:35], v[224:227], v[232:235], v[32:35]
	ds_read_b128 v[190:193], v148 offset:33792
	v_mfma_f32_16x16x32_bf16 v[60:63], v[228:231], v[232:235], v[60:63]
	ds_read_b128 v[194:197], v148 offset:34816
	s_waitcnt lgkmcnt(5)
	v_mfma_f32_16x16x32_bf16 v[4:7], v[216:219], v[236:239], v[4:7]
	ds_read_b128 v[202:205], v148 offset:35840
	ds_read_b128 v[232:235], v149 offset:49152
	v_mfma_f32_16x16x32_bf16 v[20:23], v[220:223], v[236:239], v[20:23]
	v_lshl_add_u64 v[168:169], v[142:143], 0, s[80:81]
	v_mfma_f32_16x16x32_bf16 v[36:39], v[224:227], v[236:239], v[36:39]
	global_load_lds_dwordx4 v[166:167], off
	v_mfma_f32_16x16x32_bf16 v[76:79], v[228:231], v[236:239], v[76:79]
	v_add_u32_e32 v166, 0x1e000, v147
	s_waitcnt lgkmcnt(6)
	v_mfma_f32_16x16x32_bf16 v[8:11], v[216:219], v[240:243], v[8:11]
	ds_read_b128 v[236:239], v149 offset:50176
	v_mfma_f32_16x16x32_bf16 v[24:27], v[220:223], v[240:243], v[24:27]
	s_add_i32 m0, s100, 0x1e000
	v_mfma_f32_16x16x32_bf16 v[40:43], v[224:227], v[240:243], v[40:43]
	global_load_lds_dwordx4 v[168:169], off
	v_mfma_f32_16x16x32_bf16 v[84:87], v[228:231], v[240:243], v[84:87]
	s_waitcnt lgkmcnt(6)
	v_mfma_f32_16x16x32_bf16 v[12:15], v[216:219], v[244:247], v[12:15]
	ds_read_b128 v[240:243], v149 offset:51200
	v_mfma_f32_16x16x32_bf16 v[28:31], v[220:223], v[244:247], v[28:31]
	v_mfma_f32_16x16x32_bf16 v[44:47], v[224:227], v[244:247], v[44:47]
	v_mfma_f32_16x16x32_bf16 v[92:95], v[228:231], v[244:247], v[92:95]
	ds_read_b128 v[244:247], v149 offset:52224
	s_waitcnt lgkmcnt(3)
	v_mfma_f32_16x16x32_bf16 v[56:59], v[186:189], v[232:235], v[56:59]
	v_lshl_add_u64 v[168:169], v[144:145], 0, s[62:63]
	v_mfma_f32_16x16x32_bf16 v[100:103], v[190:193], v[232:235], v[100:103]
	s_mov_b32 m0, s100
	v_mfma_f32_16x16x32_bf16 v[104:107], v[194:197], v[232:235], v[104:107]
	s_waitcnt vmcnt(4)
	s_barrier
; #define BIG_SYNC(N)                                              \
;   asm volatile("s_waitcnt vmcnt(%0)" ::"n"(N) : "memory");       \
;   __builtin_amdgcn_s_barrier();                                  \
;   asm volatile("" ::: "memory");                                 \
;   __builtin_amdgcn_sched_barrier(0);
; template <int NK, bool BNT = false> ...
;     ...
;   auto kstep = [&](int T, int cur, int nxt, bool do_stage) {
;     const unsigned char* sa = smem + cur * BIG_STAGE;
;     bf16x8 af[4], bfr[4];
; #pragma unroll
;     for (int m = 0; m < 4; ++m) af[m] = *reinterpret_cast<const bf16x8*>(sa + aoff + m * 1024);
; #pragma unroll
;     for (int n = 0; n < 4; ++n) bfr[n] = *reinterpret_cast<const bf16x8*>(sa + boff + n * 1024);
;     __builtin_amdgcn_sched_barrier(0);
;     if (do_stage) stage(T + 3, nxt);
; #pragma unroll
;     for (int m = 0; m < 4; ++m)
; #pragma unroll
;       for (int n = 0; n < 4; ++n) acc[m][n] = __builtin_amdgcn_mfma_f32_16x16x32_bf16(af[m], bfr[n], acc[m][n], 0, 0, 0);
;     if (do_stage) {
; #pragma unroll
;       for (int q = 0; q < NG; ++q) {
;         __builtin_amdgcn_sched_group_barrier(0x008, 3, 0);
;         __builtin_amdgcn_sched_group_barrier(0x010, 1, 0);
;       }
;       __builtin_amdgcn_sched_group_barrier(0x008, 16 - 3 * NG, 0);
;     }
;     __builtin_amdgcn_sched_barrier(0);
; #pragma unroll
;     for (int n = 0; n < 4; ++n) bfr[n] = *reinterpret_cast<const bf16x8*>(sa + boff + (4 + n) * 1024);
; #pragma unroll
;     for (int m = 0; m < 4; ++m)
; #pragma unroll
;       for (int n = 0; n < 4; ++n)
;         acc[m][4 + n] = __builtin_amdgcn_mfma_f32_16x16x32_bf16(af[m], bfr[n], acc[m][4 + n], 0, 0, 0);
;     __builtin_amdgcn_sched_barrier(0);
;     ...
;   for (int it = 0; it < NK / 4 - 1; ++it) {
;     const int t = it * 4;
;     BIG_SYNC(2 * NG); kstep(t, 0, 3, true);
;     BIG_SYNC(2 * NG); kstep(t + 1, 1, 0, true);
;     BIG_SYNC(2 * NG); kstep(t + 2, 2, 1, true);
;     BIG_SYNC(2 * NG); kstep(t + 3, 3, 2, true);
	v_lshl_add_u64 v[182:183], v[142:143], 0, s[62:63]
	v_mfma_f32_16x16x32_bf16 v[112:115], v[202:205], v[232:235], v[112:115]
	global_load_lds_dwordx4 v[168:169], off
	s_waitcnt lgkmcnt(2)
	v_mfma_f32_16x16x32_bf16 v[64:67], v[186:189], v[236:239], v[64:67]
	ds_read_b128 v[232:235], v149 offset:53248
	v_mfma_f32_16x16x32_bf16 v[80:83], v[190:193], v[236:239], v[80:83]
	v_lshl_add_u64 v[168:169], v[144:145], 0, s[0:1]
	v_mfma_f32_16x16x32_bf16 v[96:99], v[194:197], v[236:239], v[96:99]
	s_add_i32 m0, s100, 0x2000
	v_mfma_f32_16x16x32_bf16 v[116:119], v[202:205], v[236:239], v[116:119]
	global_load_lds_dwordx4 v[168:169], off
	s_waitcnt lgkmcnt(2)
	v_mfma_f32_16x16x32_bf16 v[52:55], v[186:189], v[240:243], v[52:55]
	ds_read_b128 v[236:239], v149 offset:54272
	v_mfma_f32_16x16x32_bf16 v[68:71], v[190:193], v[240:243], v[68:71]
	s_add_i32 m0, s100, 0x4000
	v_mfma_f32_16x16x32_bf16 v[108:111], v[194:197], v[240:243], v[108:111]
	v_lshl_add_u64 v[168:169], v[142:143], 0, s[0:1]
	v_mfma_f32_16x16x32_bf16 v[120:123], v[202:205], v[240:243], v[120:123]
	global_load_lds_dwordx4 v[182:183], off
	s_waitcnt lgkmcnt(2)
	v_mfma_f32_16x16x32_bf16 v[48:51], v[186:189], v[244:247], v[48:51]
	ds_read_b128 v[240:243], v149 offset:55296
	v_mfma_f32_16x16x32_bf16 v[72:75], v[190:193], v[244:247], v[72:75]
	s_add_i32 m0, s100, 0x6000
	v_mfma_f32_16x16x32_bf16 v[88:91], v[194:197], v[244:247], v[88:91]
	global_load_lds_dwordx4 v[168:169], off
	v_mfma_f32_16x16x32_bf16 v[124:127], v[202:205], v[244:247], v[124:127]
	s_waitcnt lgkmcnt(2)
	v_mfma_f32_16x16x32_bf16 v[0:3], v[186:189], v[232:235], v[0:3]
	ds_read_b128 v[244:247], v149 offset:56320
	v_mfma_f32_16x16x32_bf16 v[16:19], v[190:193], v[232:235], v[16:19]
	ds_read_b128 v[216:219], v210
	v_mfma_f32_16x16x32_bf16 v[32:35], v[194:197], v[232:235], v[32:35]
	ds_read_b128 v[220:223], v210 offset:1024
	v_mfma_f32_16x16x32_bf16 v[60:63], v[202:205], v[232:235], v[60:63]
	ds_read_b128 v[224:227], v210 offset:2048
	s_waitcnt lgkmcnt(5)
	v_mfma_f32_16x16x32_bf16 v[4:7], v[186:189], v[236:239], v[4:7]
	ds_read_b128 v[228:231], v210 offset:3072
	ds_read_b128 v[232:235], v211
	v_mfma_f32_16x16x32_bf16 v[20:23], v[190:193], v[236:239], v[20:23]
	v_mfma_f32_16x16x32_bf16 v[36:39], v[194:197], v[236:239], v[36:39]
	v_mfma_f32_16x16x32_bf16 v[76:79], v[202:205], v[236:239], v[76:79]
	s_waitcnt lgkmcnt(6)
	v_mfma_f32_16x16x32_bf16 v[8:11], v[186:189], v[240:243], v[8:11]
	ds_read_b128 v[236:239], v211 offset:1024
	v_mfma_f32_16x16x32_bf16 v[24:27], v[190:193], v[240:243], v[24:27]
	v_mfma_f32_16x16x32_bf16 v[40:43], v[194:197], v[240:243], v[40:43]
	v_mfma_f32_16x16x32_bf16 v[84:87], v[202:205], v[240:243], v[84:87]
	s_waitcnt lgkmcnt(6)
	v_mfma_f32_16x16x32_bf16 v[12:15], v[186:189], v[244:247], v[12:15]
	ds_read_b128 v[240:243], v211 offset:2048
	v_mfma_f32_16x16x32_bf16 v[28:31], v[190:193], v[244:247], v[28:31]
	v_mfma_f32_16x16x32_bf16 v[44:47], v[194:197], v[244:247], v[44:47]
	v_mfma_f32_16x16x32_bf16 v[92:95], v[202:205], v[244:247], v[92:95]
	ds_read_b128 v[244:247], v211 offset:3072
	s_waitcnt lgkmcnt(3)
	v_mfma_f32_16x16x32_bf16 v[56:59], v[216:219], v[232:235], v[56:59]
	v_lshl_add_u64 v[174:175], v[144:145], 0, s[2:3]
	v_mfma_f32_16x16x32_bf16 v[100:103], v[220:223], v[232:235], v[100:103]
	s_add_i32 m0, s100, 0x8000
	v_mfma_f32_16x16x32_bf16 v[104:107], v[224:227], v[232:235], v[104:107]
	s_waitcnt vmcnt(4)
	s_barrier
	v_lshl_add_u64 v[178:179], v[142:143], 0, s[2:3]
	v_mfma_f32_16x16x32_bf16 v[112:115], v[228:231], v[232:235], v[112:115]
	global_load_lds_dwordx4 v[174:175], off
	s_waitcnt lgkmcnt(2)
	v_mfma_f32_16x16x32_bf16 v[64:67], v[216:219], v[236:239], v[64:67]
	ds_read_b128 v[232:235], v211 offset:4096
	v_mfma_f32_16x16x32_bf16 v[80:83], v[220:223], v[236:239], v[80:83]
	v_lshl_add_u64 v[174:175], v[144:145], 0, s[52:53]
	v_mfma_f32_16x16x32_bf16 v[96:99], v[224:227], v[236:239], v[96:99]
	s_add_i32 m0, s100, 0xa000
	v_mfma_f32_16x16x32_bf16 v[116:119], v[228:231], v[236:239], v[116:119]
	global_load_lds_dwordx4 v[174:175], off
	s_waitcnt lgkmcnt(2)
	v_mfma_f32_16x16x32_bf16 v[52:55], v[216:219], v[240:243], v[52:55]
	ds_read_b128 v[236:239], v211 offset:5120
	v_mfma_f32_16x16x32_bf16 v[68:71], v[220:223], v[240:243], v[68:71]
	s_add_i32 m0, s100, 0xc000
	v_mfma_f32_16x16x32_bf16 v[108:111], v[224:227], v[240:243], v[108:111]
	v_lshl_add_u64 v[174:175], v[142:143], 0, s[52:53]
	v_mfma_f32_16x16x32_bf16 v[120:123], v[228:231], v[240:243], v[120:123]
	global_load_lds_dwordx4 v[178:179], off
	s_waitcnt lgkmcnt(2)
	v_mfma_f32_16x16x32_bf16 v[48:51], v[216:219], v[244:247], v[48:51]
	ds_read_b128 v[240:243], v211 offset:6144
	v_mfma_f32_16x16x32_bf16 v[72:75], v[220:223], v[244:247], v[72:75]
	s_add_i32 m0, s100, 0xe000
	v_mfma_f32_16x16x32_bf16 v[88:91], v[224:227], v[244:247], v[88:91]
	global_load_lds_dwordx4 v[174:175], off
	v_mfma_f32_16x16x32_bf16 v[124:127], v[228:231], v[244:247], v[124:127]
	s_waitcnt lgkmcnt(2)
	v_mfma_f32_16x16x32_bf16 v[0:3], v[216:219], v[232:235], v[0:3]
	ds_read_b128 v[244:247], v211 offset:7168
	v_mfma_f32_16x16x32_bf16 v[16:19], v[220:223], v[232:235], v[16:19]
	ds_read_b128 v[186:189], v210 offset:32768
	v_mfma_f32_16x16x32_bf16 v[32:35], v[224:227], v[232:235], v[32:35]
	ds_read_b128 v[190:193], v210 offset:33792
	v_mfma_f32_16x16x32_bf16 v[60:63], v[228:231], v[232:235], v[60:63]
	ds_read_b128 v[194:197], v210 offset:34816
	s_waitcnt lgkmcnt(5)
	v_mfma_f32_16x16x32_bf16 v[4:7], v[216:219], v[236:239], v[4:7]
	ds_read_b128 v[202:205], v210 offset:35840
	ds_read_b128 v[232:235], v211 offset:32768
	v_mfma_f32_16x16x32_bf16 v[20:23], v[220:223], v[236:239], v[20:23]
	v_mfma_f32_16x16x32_bf16 v[36:39], v[224:227], v[236:239], v[36:39]
	v_mfma_f32_16x16x32_bf16 v[76:79], v[228:231], v[236:239], v[76:79]
	s_waitcnt lgkmcnt(6)
	v_mfma_f32_16x16x32_bf16 v[8:11], v[216:219], v[240:243], v[8:11]
	ds_read_b128 v[236:239], v211 offset:33792
	v_mfma_f32_16x16x32_bf16 v[24:27], v[220:223], v[240:243], v[24:27]
	v_mfma_f32_16x16x32_bf16 v[40:43], v[224:227], v[240:243], v[40:43]
	v_mfma_f32_16x16x32_bf16 v[84:87], v[228:231], v[240:243], v[84:87]
	s_waitcnt lgkmcnt(6)
	v_mfma_f32_16x16x32_bf16 v[12:15], v[216:219], v[244:247], v[12:15]
	ds_read_b128 v[240:243], v211 offset:34816
	v_mfma_f32_16x16x32_bf16 v[28:31], v[220:223], v[244:247], v[28:31]
	v_mfma_f32_16x16x32_bf16 v[44:47], v[224:227], v[244:247], v[44:47]
	v_mfma_f32_16x16x32_bf16 v[92:95], v[228:231], v[244:247], v[92:95]
	ds_read_b128 v[244:247], v211 offset:35840
	s_waitcnt lgkmcnt(3)
	v_mfma_f32_16x16x32_bf16 v[56:59], v[186:189], v[232:235], v[56:59]
	v_lshl_add_u64 v[248:249], v[144:145], 0, s[54:55]
	v_mfma_f32_16x16x32_bf16 v[100:103], v[190:193], v[232:235], v[100:103]
	s_add_i32 m0, s100, 0x10000
	v_mfma_f32_16x16x32_bf16 v[104:107], v[194:197], v[232:235], v[104:107]
	s_waitcnt vmcnt(4)
	s_barrier
; #define BIG_SYNC(N)                                              \
;   asm volatile("s_waitcnt vmcnt(%0)" ::"n"(N) : "memory");       \
;   __builtin_amdgcn_s_barrier();                                  \
;   asm volatile("" ::: "memory");                                 \
;   __builtin_amdgcn_sched_barrier(0);
; template <int NK, bool BNT = false> ...
;     ...
;   auto kstep = [&](int T, int cur, int nxt, bool do_stage) {
;     const unsigned char* sa = smem + cur * BIG_STAGE;
;     bf16x8 af[4], bfr[4];
; #pragma unroll
;     for (int m = 0; m < 4; ++m) af[m] = *reinterpret_cast<const bf16x8*>(sa + aoff + m * 1024);
; #pragma unroll
;     for (int n = 0; n < 4; ++n) bfr[n] = *reinterpret_cast<const bf16x8*>(sa + boff + n * 1024);
;     __builtin_amdgcn_sched_barrier(0);
;     if (do_stage) stage(T + 3, nxt);
; #pragma unroll
;     for (int m = 0; m < 4; ++m)
; #pragma unroll
;       for (int n = 0; n < 4; ++n) acc[m][n] = __builtin_amdgcn_mfma_f32_16x16x32_bf16(af[m], bfr[n], acc[m][n], 0, 0, 0);
;     if (do_stage) {
; #pragma unroll
;       for (int q = 0; q < NG; ++q) {
;         __builtin_amdgcn_sched_group_barrier(0x008, 3, 0);
;         __builtin_amdgcn_sched_group_barrier(0x010, 1, 0);
;       }
;       __builtin_amdgcn_sched_group_barrier(0x008, 16 - 3 * NG, 0);
;     }
;     __builtin_amdgcn_sched_barrier(0);
; #pragma unroll
;     for (int n = 0; n < 4; ++n) bfr[n] = *reinterpret_cast<const bf16x8*>(sa + boff + (4 + n) * 1024);
; #pragma unroll
;     for (int m = 0; m < 4; ++m)
; #pragma unroll
;       for (int n = 0; n < 4; ++n)
;         acc[m][4 + n] = __builtin_amdgcn_mfma_f32_16x16x32_bf16(af[m], bfr[n], acc[m][4 + n], 0, 0, 0);
;     __builtin_amdgcn_sched_barrier(0);
;     ...
;   for (int it = 0; it < NK / 4 - 1; ++it) {
;     const int t = it * 4;
;     BIG_SYNC(2 * NG); kstep(t, 0, 3, true);
;     BIG_SYNC(2 * NG); kstep(t + 1, 1, 0, true);
;     BIG_SYNC(2 * NG); kstep(t + 2, 2, 1, true);
;     BIG_SYNC(2 * NG); kstep(t + 3, 3, 2, true);
;   }
;   BIG_SYNC(2 * NG); kstep(NK - 4, 0, 3, true);
	v_lshl_add_u64 v[144:145], v[144:145], 0, s[56:57]
	v_mfma_f32_16x16x32_bf16 v[112:115], v[202:205], v[232:235], v[112:115]
	v_lshl_add_u64 v[250:251], v[142:143], 0, s[54:55]
	s_waitcnt lgkmcnt(2)
	v_mfma_f32_16x16x32_bf16 v[64:67], v[186:189], v[236:239], v[64:67]
	ds_read_b128 v[232:235], v211 offset:36864
	v_mfma_f32_16x16x32_bf16 v[80:83], v[190:193], v[236:239], v[80:83]
	v_lshl_add_u64 v[142:143], v[142:143], 0, s[56:57]
	v_mfma_f32_16x16x32_bf16 v[96:99], v[194:197], v[236:239], v[96:99]
	global_load_lds_dwordx4 v[248:249], off
	v_mfma_f32_16x16x32_bf16 v[116:119], v[202:205], v[236:239], v[116:119]
	s_add_i32 m0, s100, 0x12000
	s_waitcnt lgkmcnt(2)
	v_mfma_f32_16x16x32_bf16 v[52:55], v[186:189], v[240:243], v[52:55]
	ds_read_b128 v[236:239], v211 offset:37888
	v_mfma_f32_16x16x32_bf16 v[68:71], v[190:193], v[240:243], v[68:71]
	global_load_lds_dwordx4 v[144:145], off
	v_mfma_f32_16x16x32_bf16 v[108:111], v[194:197], v[240:243], v[108:111]
	s_add_i32 m0, s100, 0x14000
	v_mfma_f32_16x16x32_bf16 v[120:123], v[202:205], v[240:243], v[120:123]
	global_load_lds_dwordx4 v[250:251], off
	s_waitcnt lgkmcnt(2)
	v_mfma_f32_16x16x32_bf16 v[48:51], v[186:189], v[244:247], v[48:51]
	ds_read_b128 v[240:243], v211 offset:38912
	v_mfma_f32_16x16x32_bf16 v[72:75], v[190:193], v[244:247], v[72:75]
	s_add_i32 m0, s100, 0x16000
	v_mfma_f32_16x16x32_bf16 v[88:91], v[194:197], v[244:247], v[88:91]
	global_load_lds_dwordx4 v[142:143], off
	v_mfma_f32_16x16x32_bf16 v[124:127], v[202:205], v[244:247], v[124:127]
	s_waitcnt lgkmcnt(2)
	v_mfma_f32_16x16x32_bf16 v[0:3], v[186:189], v[232:235], v[0:3]
	ds_read_b128 v[244:247], v211 offset:39936
	v_mfma_f32_16x16x32_bf16 v[16:19], v[190:193], v[232:235], v[16:19]
	ds_read_b128 v[216:219], v148
	v_mfma_f32_16x16x32_bf16 v[32:35], v[194:197], v[232:235], v[32:35]
	ds_read_b128 v[220:223], v148 offset:1024
	v_mfma_f32_16x16x32_bf16 v[60:63], v[202:205], v[232:235], v[60:63]
	ds_read_b128 v[224:227], v148 offset:2048
	s_waitcnt lgkmcnt(5)
	v_mfma_f32_16x16x32_bf16 v[4:7], v[186:189], v[236:239], v[4:7]
	ds_read_b128 v[228:231], v148 offset:3072
	ds_read_b128 v[232:235], v149 offset:16384
	v_mfma_f32_16x16x32_bf16 v[20:23], v[190:193], v[236:239], v[20:23]
	v_mfma_f32_16x16x32_bf16 v[36:39], v[194:197], v[236:239], v[36:39]
	v_mfma_f32_16x16x32_bf16 v[76:79], v[202:205], v[236:239], v[76:79]
	s_waitcnt lgkmcnt(6)
	v_mfma_f32_16x16x32_bf16 v[8:11], v[186:189], v[240:243], v[8:11]
	ds_read_b128 v[236:239], v149 offset:17408
	v_mfma_f32_16x16x32_bf16 v[24:27], v[190:193], v[240:243], v[24:27]
	v_mfma_f32_16x16x32_bf16 v[40:43], v[194:197], v[240:243], v[40:43]
	v_mfma_f32_16x16x32_bf16 v[84:87], v[202:205], v[240:243], v[84:87]
	s_waitcnt lgkmcnt(6)
	v_mfma_f32_16x16x32_bf16 v[12:15], v[186:189], v[244:247], v[12:15]
	ds_read_b128 v[240:243], v149 offset:18432
	v_mfma_f32_16x16x32_bf16 v[28:31], v[190:193], v[244:247], v[28:31]
	v_mfma_f32_16x16x32_bf16 v[44:47], v[194:197], v[244:247], v[44:47]
	v_mfma_f32_16x16x32_bf16 v[92:95], v[202:205], v[244:247], v[92:95]
	ds_read_b128 v[244:247], v149 offset:19456
	s_add_u32 s6, s6, 0x8000
	s_addc_u32 s7, s7, 0
	s_cmp_lg_u32 s6, 0x38000
	s_cbranch_scc1 .LBB0_302
	v_add_u32_e32 v167, 0x10000, v148
	v_or_b32_e32 v168, 0x10000, v150
	v_add_u32_e32 v169, 0x10400, v150
	v_add_u32_e32 v170, 0x10800, v150
	v_add_u32_e32 v172, 0x10c00, v150
	v_add_u32_e32 v173, 0x11000, v150
	v_add_u32_e32 v174, 0x11400, v150
	v_add_u32_e32 v175, 0x11800, v150
	v_add_u32_e32 v178, 0x11c00, v150
	v_add_u32_e32 v176, 0x18000, v148
	v_or_b32_e32 v179, 0x18000, v150
	v_add_u32_e32 v180, 0x18400, v150
	v_add_u32_e32 v181, 0x18800, v150
	v_add_u32_e32 v182, 0x18c00, v150
	v_add_u32_e32 v142, 0x19000, v150
	v_add_u32_e32 v143, 0x19400, v150
	v_add_u32_e32 v144, 0x19800, v150
	v_add_u32_e32 v145, 0x19c00, v150
	s_waitcnt lgkmcnt(3)
	v_mfma_f32_16x16x32_bf16 v[56:59], v[216:219], v[232:235], v[56:59]
	s_sext_i32_i8 s4, s4
	v_mfma_f32_16x16x32_bf16 v[100:103], v[220:223], v[232:235], v[100:103]
	s_mov_b64 s[6:7], 0x3e000
	v_mfma_f32_16x16x32_bf16 v[104:107], v[224:227], v[232:235], v[104:107]
	s_waitcnt vmcnt(4)
	s_barrier
	v_readfirstlane_b32 s5, v163
	v_mfma_f32_16x16x32_bf16 v[112:115], v[228:231], v[232:235], v[112:115]
	v_lshl_add_u64 v[198:199], v[136:137], 0, s[6:7]
	s_waitcnt lgkmcnt(2)
	v_mfma_f32_16x16x32_bf16 v[64:67], v[216:219], v[236:239], v[64:67]
	ds_read_b128 v[232:235], v149 offset:20480
	v_mfma_f32_16x16x32_bf16 v[80:83], v[220:223], v[236:239], v[80:83]
	v_lshl_add_u64 v[200:201], v[134:135], 0, s[6:7]
	v_mfma_f32_16x16x32_bf16 v[96:99], v[224:227], v[236:239], v[96:99]
	s_mov_b32 m0, s5
	v_mfma_f32_16x16x32_bf16 v[116:119], v[228:231], v[236:239], v[116:119]
	s_mov_b64 s[6:7], 0x7e000
	s_waitcnt lgkmcnt(2)
	v_mfma_f32_16x16x32_bf16 v[52:55], v[216:219], v[240:243], v[52:55]
	ds_read_b128 v[236:239], v149 offset:21504
	v_mfma_f32_16x16x32_bf16 v[68:71], v[220:223], v[240:243], v[68:71]
	v_readfirstlane_b32 s5, v164
	v_mfma_f32_16x16x32_bf16 v[108:111], v[224:227], v[240:243], v[108:111]
	v_lshl_add_u64 v[136:137], v[136:137], 0, s[6:7]
	v_mfma_f32_16x16x32_bf16 v[120:123], v[228:231], v[240:243], v[120:123]
	v_lshl_add_u64 v[134:135], v[134:135], 0, s[6:7]
	s_waitcnt lgkmcnt(2)
	v_mfma_f32_16x16x32_bf16 v[48:51], v[216:219], v[244:247], v[48:51]
	ds_read_b128 v[240:243], v149 offset:22528
	v_mfma_f32_16x16x32_bf16 v[72:75], v[220:223], v[244:247], v[72:75]
	global_load_lds_dwordx4 v[198:199], off
	v_mfma_f32_16x16x32_bf16 v[88:91], v[224:227], v[244:247], v[88:91]
	s_mov_b32 m0, s5
	v_mfma_f32_16x16x32_bf16 v[124:127], v[228:231], v[244:247], v[124:127]
	v_readfirstlane_b32 s5, v165
	s_waitcnt lgkmcnt(2)
; #define BIG_SYNC(N)                                              \
;   asm volatile("s_waitcnt vmcnt(%0)" ::"n"(N) : "memory");       \
;   __builtin_amdgcn_s_barrier();                                  \
;   asm volatile("" ::: "memory");                                 \
;   __builtin_amdgcn_sched_barrier(0);
; template <int NK, bool BNT = false> ...
;     ...
;   auto kstep = [&](int T, int cur, int nxt, bool do_stage) {
;     const unsigned char* sa = smem + cur * BIG_STAGE;
;     bf16x8 af[4], bfr[4];
; #pragma unroll
;     for (int m = 0; m < 4; ++m) af[m] = *reinterpret_cast<const bf16x8*>(sa + aoff + m * 1024);
; #pragma unroll
;     for (int n = 0; n < 4; ++n) bfr[n] = *reinterpret_cast<const bf16x8*>(sa + boff + n * 1024);
;     __builtin_amdgcn_sched_barrier(0);
;     if (do_stage) stage(T + 3, nxt);
; #pragma unroll
;     for (int m = 0; m < 4; ++m)
; #pragma unroll
;       for (int n = 0; n < 4; ++n) acc[m][n] = __builtin_amdgcn_mfma_f32_16x16x32_bf16(af[m], bfr[n], acc[m][n], 0, 0, 0);
;     if (do_stage) {
; #pragma unroll
;       for (int q = 0; q < NG; ++q) {
;         __builtin_amdgcn_sched_group_barrier(0x008, 3, 0);
;         __builtin_amdgcn_sched_group_barrier(0x010, 1, 0);
;       }
;       __builtin_amdgcn_sched_group_barrier(0x008, 16 - 3 * NG, 0);
;     }
;     __builtin_amdgcn_sched_barrier(0);
; #pragma unroll
;     for (int n = 0; n < 4; ++n) bfr[n] = *reinterpret_cast<const bf16x8*>(sa + boff + (4 + n) * 1024);
; #pragma unroll
;     for (int m = 0; m < 4; ++m)
; #pragma unroll
;       for (int n = 0; n < 4; ++n)
;         acc[m][4 + n] = __builtin_amdgcn_mfma_f32_16x16x32_bf16(af[m], bfr[n], acc[m][4 + n], 0, 0, 0);
;     __builtin_amdgcn_sched_barrier(0);
;     ...
;   BIG_SYNC(2 * NG); kstep(NK - 4, 0, 3, true);
;   BIG_SYNC(2 * NG); kstep(NK - 3, 1, 0, false);
;   BIG_SYNC(NG);     kstep(NK - 2, 2, 0, false);
;   BIG_SYNC(0);      kstep(NK - 1, 3, 0, false);
	v_mfma_f32_16x16x32_bf16 v[0:3], v[216:219], v[232:235], v[0:3]
	ds_read_b128 v[244:247], v149 offset:23552
	v_mfma_f32_16x16x32_bf16 v[16:19], v[220:223], v[232:235], v[16:19]
	ds_read_b128 v[186:189], v148 offset:32768
	v_mfma_f32_16x16x32_bf16 v[32:35], v[224:227], v[232:235], v[32:35]
	ds_read_b128 v[190:193], v148 offset:33792
	v_mfma_f32_16x16x32_bf16 v[60:63], v[228:231], v[232:235], v[60:63]
	ds_read_b128 v[194:197], v148 offset:34816
	s_waitcnt lgkmcnt(5)
	v_mfma_f32_16x16x32_bf16 v[4:7], v[216:219], v[236:239], v[4:7]
	ds_read_b128 v[202:205], v148 offset:35840
	ds_read_b128 v[232:235], v149 offset:49152
	v_mfma_f32_16x16x32_bf16 v[20:23], v[220:223], v[236:239], v[20:23]
	global_load_lds_dwordx4 v[136:137], off
	v_mfma_f32_16x16x32_bf16 v[36:39], v[224:227], v[236:239], v[36:39]
	s_mov_b32 m0, s5
	v_mfma_f32_16x16x32_bf16 v[76:79], v[228:231], v[236:239], v[76:79]
	v_readfirstlane_b32 s5, v166
	s_waitcnt lgkmcnt(6)
	v_mfma_f32_16x16x32_bf16 v[8:11], v[216:219], v[240:243], v[8:11]
	ds_read_b128 v[236:239], v149 offset:50176
	v_mfma_f32_16x16x32_bf16 v[24:27], v[220:223], v[240:243], v[24:27]
	global_load_lds_dwordx4 v[200:201], off
	v_mfma_f32_16x16x32_bf16 v[40:43], v[224:227], v[240:243], v[40:43]
	s_mov_b32 m0, s5
	v_mfma_f32_16x16x32_bf16 v[84:87], v[228:231], v[240:243], v[84:87]
	global_load_lds_dwordx4 v[134:135], off
	s_waitcnt lgkmcnt(6)
	v_mfma_f32_16x16x32_bf16 v[12:15], v[216:219], v[244:247], v[12:15]
	ds_read_b128 v[240:243], v149 offset:51200
	v_mfma_f32_16x16x32_bf16 v[28:31], v[220:223], v[244:247], v[28:31]
	v_mfma_f32_16x16x32_bf16 v[44:47], v[224:227], v[244:247], v[44:47]
	v_mfma_f32_16x16x32_bf16 v[92:95], v[228:231], v[244:247], v[92:95]
	ds_read_b128 v[244:247], v149 offset:52224
	s_waitcnt lgkmcnt(3)
	v_mfma_f32_16x16x32_bf16 v[56:59], v[186:189], v[232:235], v[56:59]
	v_mfma_f32_16x16x32_bf16 v[100:103], v[190:193], v[232:235], v[100:103]
	v_mfma_f32_16x16x32_bf16 v[104:107], v[194:197], v[232:235], v[104:107]
	v_mfma_f32_16x16x32_bf16 v[112:115], v[202:205], v[232:235], v[112:115]
	s_waitcnt vmcnt(4)
	s_barrier
	s_waitcnt lgkmcnt(2)
	v_mfma_f32_16x16x32_bf16 v[64:67], v[186:189], v[236:239], v[64:67]
	ds_read_b128 v[232:235], v149 offset:53248
	v_mfma_f32_16x16x32_bf16 v[80:83], v[190:193], v[236:239], v[80:83]
	v_mfma_f32_16x16x32_bf16 v[96:99], v[194:197], v[236:239], v[96:99]
	v_mfma_f32_16x16x32_bf16 v[116:119], v[202:205], v[236:239], v[116:119]
	s_waitcnt lgkmcnt(2)
	v_mfma_f32_16x16x32_bf16 v[52:55], v[186:189], v[240:243], v[52:55]
	ds_read_b128 v[236:239], v149 offset:54272
	v_mfma_f32_16x16x32_bf16 v[68:71], v[190:193], v[240:243], v[68:71]
	v_mfma_f32_16x16x32_bf16 v[108:111], v[194:197], v[240:243], v[108:111]
	v_mfma_f32_16x16x32_bf16 v[120:123], v[202:205], v[240:243], v[120:123]
	s_waitcnt lgkmcnt(2)
	v_mfma_f32_16x16x32_bf16 v[48:51], v[186:189], v[244:247], v[48:51]
	ds_read_b128 v[240:243], v149 offset:55296
	v_mfma_f32_16x16x32_bf16 v[72:75], v[190:193], v[244:247], v[72:75]
	v_mfma_f32_16x16x32_bf16 v[88:91], v[194:197], v[244:247], v[88:91]
	v_mfma_f32_16x16x32_bf16 v[124:127], v[202:205], v[244:247], v[124:127]
	s_waitcnt lgkmcnt(2)
	v_mfma_f32_16x16x32_bf16 v[0:3], v[186:189], v[232:235], v[0:3]
	ds_read_b128 v[244:247], v149 offset:56320
	v_mfma_f32_16x16x32_bf16 v[16:19], v[190:193], v[232:235], v[16:19]
	v_mfma_f32_16x16x32_bf16 v[32:35], v[194:197], v[232:235], v[32:35]
	v_mfma_f32_16x16x32_bf16 v[60:63], v[202:205], v[232:235], v[60:63]
	s_waitcnt lgkmcnt(2)
	v_mfma_f32_16x16x32_bf16 v[4:7], v[186:189], v[236:239], v[4:7]
	v_mfma_f32_16x16x32_bf16 v[20:23], v[190:193], v[236:239], v[20:23]
	v_mfma_f32_16x16x32_bf16 v[36:39], v[194:197], v[236:239], v[36:39]
	v_mfma_f32_16x16x32_bf16 v[76:79], v[202:205], v[236:239], v[76:79]
	s_waitcnt lgkmcnt(1)
	v_mfma_f32_16x16x32_bf16 v[8:11], v[186:189], v[240:243], v[8:11]
	v_mfma_f32_16x16x32_bf16 v[24:27], v[190:193], v[240:243], v[24:27]
	v_mfma_f32_16x16x32_bf16 v[40:43], v[194:197], v[240:243], v[40:43]
	v_mfma_f32_16x16x32_bf16 v[84:87], v[202:205], v[240:243], v[84:87]
	s_waitcnt lgkmcnt(0)
	v_mfma_f32_16x16x32_bf16 v[12:15], v[186:189], v[244:247], v[12:15]
	v_mfma_f32_16x16x32_bf16 v[28:31], v[190:193], v[244:247], v[28:31]
	v_mfma_f32_16x16x32_bf16 v[44:47], v[194:197], v[244:247], v[44:47]
	v_mfma_f32_16x16x32_bf16 v[92:95], v[202:205], v[244:247], v[92:95]
	v_mov_b32_e32 v186, 0xf149f2ca
	v_mov_b32_e32 v187, 0x3c0881c4
	v_mov_b32_e32 v188, 0xbab64f3b
	v_mov_b32_e32 v189, 0x24800
	v_mov_b32_e32 v190, 1
	v_mov_b32_e32 v191, 0x24804
	v_mov_b32_e32 v192, 0xfcf
	v_mov_b32_e32 v193, 0x7cf
	v_mov_b32_e32 v194, 0xfdf
	v_mov_b32_e32 v195, 0x7df
	v_mov_b32_e32 v196, 0xfef
	v_mov_b32_e32 v197, 0x7ef
	v_mov_b32_e32 v198, 0xfff
	v_mov_b32_e32 v199, 0x7ff
	v_mov_b32_e32 v200, 0x20000
	v_mov_b32_e32 v201, 0xf8f
	v_mov_b32_e32 v202, 0x78f
	v_mov_b32_e32 v203, 0xf9f
	v_mov_b32_e32 v204, 0x79f
	v_mov_b32_e32 v205, 0xfaf
	v_mov_b32_e32 v210, 0x7f800000
	v_not_b32_e32 v211, 63
	v_not_b32_e32 v212, 31
	v_mov_b32_e32 v213, 0x7fc00000
	s_waitcnt vmcnt(4)
	s_barrier
; template <int NK, bool BNT = false> ...
;     ...
;   auto kstep = [&](int T, int cur, int nxt, bool do_stage) {
;     const unsigned char* sa = smem + cur * BIG_STAGE;
;     bf16x8 af[4], bfr[4];
; #pragma unroll
;     for (int m = 0; m < 4; ++m) af[m] = *reinterpret_cast<const bf16x8*>(sa + aoff + m * 1024);
; #pragma unroll
;     for (int n = 0; n < 4; ++n) bfr[n] = *reinterpret_cast<const bf16x8*>(sa + boff + n * 1024);
;     __builtin_amdgcn_sched_barrier(0);
;     if (do_stage) stage(T + 3, nxt);
; #pragma unroll
;     for (int m = 0; m < 4; ++m)
; #pragma unroll
;       for (int n = 0; n < 4; ++n) acc[m][n] = __builtin_amdgcn_mfma_f32_16x16x32_bf16(af[m], bfr[n], acc[m][n], 0, 0, 0);
;     if (do_stage) {
; #pragma unroll
;       for (int q = 0; q < NG; ++q) {
;         __builtin_amdgcn_sched_group_barrier(0x008, 3, 0);
;         __builtin_amdgcn_sched_group_barrier(0x010, 1, 0);
;       }
;       __builtin_amdgcn_sched_group_barrier(0x008, 16 - 3 * NG, 0);
;     }
;     __builtin_amdgcn_sched_barrier(0);
; #pragma unroll
;     for (int n = 0; n < 4; ++n) bfr[n] = *reinterpret_cast<const bf16x8*>(sa + boff + (4 + n) * 1024);
; #pragma unroll
;     for (int m = 0; m < 4; ++m)
; #pragma unroll
;       for (int n = 0; n < 4; ++n)
;         acc[m][4 + n] = __builtin_amdgcn_mfma_f32_16x16x32_bf16(af[m], bfr[n], acc[m][4 + n], 0, 0, 0);
;     __builtin_amdgcn_sched_barrier(0);
; template <int MODE, int NSUB>
; __device__ __forceinline__ void epilogue(const Params& p, int layer, f32x4 (&acc)[4][NSUB], int tm, int tn, int g,
;                                          const float* s_rstd, const int tid_in) {
;     ...
;   if constexpr (MODE == EPI_G1) {
;     const int ft = tm;
; #pragma unroll
;     for (int n = 0; n < NSUB; ++n) {
;       const int nl = wc * (NSUB * 16) + n * 16 + fr;
;       const int t = tn * (NSUB * 32) + nl;
;       const float rs = s_rstd[nl];
;       if (ft < 2) {
; #pragma unroll
;         for (int m = 0; m < 4; ++m) {
;           int gg = ft * 8 + wr * 4 + m;
;           bf16x4 v = pack4(acc[m][n][0] * rs, acc[m][n][1] * rs, acc[m][n][2] * rs, acc[m][n][3] * rs);
;           *reinterpret_cast<bf16x4*>(p.ug + (long)gg * NT * 16 + blk(t >> 5, (t & 31) * 16 + fq * 4, 16)) = v;
;         }
;       } else if (ft < 4) {
; #pragma unroll
;         for (int mp = 0; mp < 2; ++mp) {
;           const int f = (ft - 2) * 128 + wr * 64 + mp * 32 + widen_off(fq);
	ds_read_b128 v[134:137], v167
	ds_read_b128 v[138:141], v167 offset:1024
	ds_read_b128 v[154:157], v167 offset:2048
	ds_read_b128 v[158:161], v167 offset:3072
	ds_read_b128 v[162:165], v168
	ds_read_b128 v[166:169], v169
	ds_read_b128 v[216:219], v170
	ds_read_b128 v[220:223], v172
	s_waitcnt lgkmcnt(0)
	v_mfma_f32_16x16x32_bf16 v[56:59], v[134:137], v[162:165], v[56:59]
	v_mfma_f32_16x16x32_bf16 v[64:67], v[134:137], v[166:169], v[64:67]
	v_mfma_f32_16x16x32_bf16 v[52:55], v[134:137], v[216:219], v[52:55]
	v_mfma_f32_16x16x32_bf16 v[48:51], v[134:137], v[220:223], v[48:51]
	v_mfma_f32_16x16x32_bf16 v[100:103], v[138:141], v[162:165], v[100:103]
	v_mfma_f32_16x16x32_bf16 v[80:83], v[138:141], v[166:169], v[80:83]
	v_mfma_f32_16x16x32_bf16 v[68:71], v[138:141], v[216:219], v[68:71]
	v_mfma_f32_16x16x32_bf16 v[72:75], v[138:141], v[220:223], v[72:75]
	v_mfma_f32_16x16x32_bf16 v[96:99], v[154:157], v[166:169], v[96:99]
	v_mfma_f32_16x16x32_bf16 v[112:115], v[158:161], v[162:165], v[112:115]
	v_mfma_f32_16x16x32_bf16 v[224:227], v[154:157], v[162:165], v[104:107]
	v_mfma_f32_16x16x32_bf16 v[228:231], v[154:157], v[216:219], v[108:111]
	v_mfma_f32_16x16x32_bf16 v[232:235], v[154:157], v[220:223], v[88:91]
	v_mfma_f32_16x16x32_bf16 v[162:165], v[158:161], v[166:169], v[116:119]
	v_mfma_f32_16x16x32_bf16 v[166:169], v[158:161], v[216:219], v[120:123]
	v_mfma_f32_16x16x32_bf16 v[216:219], v[158:161], v[220:223], v[124:127]
	ds_read_b128 v[88:91], v173
	ds_read_b128 v[104:107], v174
	ds_read_b128 v[108:111], v175
	ds_read_b128 v[116:119], v178
	s_waitcnt lgkmcnt(0)
	v_mfma_f32_16x16x32_bf16 v[0:3], v[134:137], v[88:91], v[0:3]
	v_mfma_f32_16x16x32_bf16 v[4:7], v[134:137], v[104:107], v[4:7]
	v_mfma_f32_16x16x32_bf16 v[8:11], v[134:137], v[108:111], v[8:11]
	v_mfma_f32_16x16x32_bf16 v[12:15], v[134:137], v[116:119], v[12:15]
	v_mfma_f32_16x16x32_bf16 v[16:19], v[138:141], v[88:91], v[16:19]
	v_mfma_f32_16x16x32_bf16 v[20:23], v[138:141], v[104:107], v[20:23]
	v_mfma_f32_16x16x32_bf16 v[24:27], v[138:141], v[108:111], v[24:27]
	v_mfma_f32_16x16x32_bf16 v[134:137], v[138:141], v[116:119], v[28:31]
	v_mfma_f32_16x16x32_bf16 v[32:35], v[154:157], v[88:91], v[32:35]
	v_mfma_f32_16x16x32_bf16 v[36:39], v[154:157], v[104:107], v[36:39]
	v_mfma_f32_16x16x32_bf16 v[138:141], v[154:157], v[108:111], v[40:43]
	v_mfma_f32_16x16x32_bf16 v[154:157], v[154:157], v[116:119], v[44:47]
	v_mfma_f32_16x16x32_bf16 v[172:175], v[158:161], v[88:91], v[60:63]
	v_mfma_f32_16x16x32_bf16 v[220:223], v[158:161], v[104:107], v[76:79]
	v_mfma_f32_16x16x32_bf16 v[236:239], v[158:161], v[108:111], v[84:87]
	v_mfma_f32_16x16x32_bf16 v[158:161], v[158:161], v[116:119], v[92:95]
	s_waitcnt vmcnt(0)
	s_barrier
	ds_read_b128 v[40:43], v176
	ds_read_b128 v[28:31], v179
	ds_read_b128 v[44:47], v180
	ds_read_b128 v[60:63], v181
	ds_read_b128 v[240:243], v176 offset:1024
	ds_read_b128 v[244:247], v176 offset:2048
	ds_read_b128 v[248:251], v176 offset:3072
	ds_read_b128 v[178:181], v182
	s_waitcnt lgkmcnt(0)
	v_mfma_f32_16x16x32_bf16 v[124:127], v[40:43], v[28:31], v[56:59]
	v_mfma_f32_16x16x32_bf16 v[108:111], v[40:43], v[44:47], v[64:67]
	v_mfma_f32_16x16x32_bf16 v[92:95], v[40:43], v[60:63], v[52:55]
	v_mfma_f32_16x16x32_bf16 v[76:79], v[40:43], v[178:181], v[48:51]
	v_mfma_f32_16x16x32_bf16 v[120:123], v[240:243], v[28:31], v[100:103]
	v_mfma_f32_16x16x32_bf16 v[104:107], v[240:243], v[44:47], v[80:83]
	v_mfma_f32_16x16x32_bf16 v[88:91], v[240:243], v[60:63], v[68:71]
	v_mfma_f32_16x16x32_bf16 v[72:75], v[240:243], v[178:181], v[72:75]
	v_mfma_f32_16x16x32_bf16 v[116:119], v[244:247], v[28:31], v[224:227]
	v_mfma_f32_16x16x32_bf16 v[100:103], v[244:247], v[44:47], v[96:99]
	v_mfma_f32_16x16x32_bf16 v[84:87], v[244:247], v[60:63], v[228:231]
	v_mfma_f32_16x16x32_bf16 v[68:71], v[244:247], v[178:181], v[232:235]
	v_mfma_f32_16x16x32_bf16 v[112:115], v[248:251], v[28:31], v[112:115]
	v_mfma_f32_16x16x32_bf16 v[96:99], v[248:251], v[44:47], v[162:165]
	v_mfma_f32_16x16x32_bf16 v[80:83], v[248:251], v[60:63], v[166:169]
	v_mfma_f32_16x16x32_bf16 v[64:67], v[248:251], v[178:181], v[216:219]
	ds_read_b128 v[48:51], v142
	ds_read_b128 v[162:165], v143
	s_waitcnt lgkmcnt(0)
	v_mfma_f32_16x16x32_bf16 v[60:63], v[40:43], v[48:51], v[0:3]
	s_nop 2
	ds_read_b128 v[0:3], v144
	ds_read_b128 v[142:145], v145
	v_mfma_f32_16x16x32_bf16 v[44:47], v[40:43], v[162:165], v[4:7]
	s_waitcnt lgkmcnt(0)
	v_mfma_f32_16x16x32_bf16 v[28:31], v[40:43], v[0:3], v[8:11]
	v_mfma_f32_16x16x32_bf16 v[12:15], v[40:43], v[142:145], v[12:15]
	v_mfma_f32_16x16x32_bf16 v[56:59], v[240:243], v[48:51], v[16:19]
	v_mfma_f32_16x16x32_bf16 v[40:43], v[240:243], v[162:165], v[20:23]
	v_mfma_f32_16x16x32_bf16 v[24:27], v[240:243], v[0:3], v[24:27]
	v_mfma_f32_16x16x32_bf16 v[8:11], v[240:243], v[142:145], v[134:137]
	v_mfma_f32_16x16x32_bf16 v[52:55], v[244:247], v[48:51], v[32:35]
	v_mfma_f32_16x16x32_bf16 v[36:39], v[244:247], v[162:165], v[36:39]
	v_mfma_f32_16x16x32_bf16 v[20:23], v[244:247], v[0:3], v[138:141]
	v_mfma_f32_16x16x32_bf16 v[4:7], v[244:247], v[142:145], v[154:157]
	v_mfma_f32_16x16x32_bf16 v[48:51], v[248:251], v[48:51], v[172:175]
	v_mfma_f32_16x16x32_bf16 v[32:35], v[248:251], v[162:165], v[220:223]
	v_mfma_f32_16x16x32_bf16 v[16:19], v[248:251], v[0:3], v[236:239]
	v_mfma_f32_16x16x32_bf16 v[0:3], v[248:251], v[142:145], v[158:161]
	v_mov_b32_e32 v141, v215
	v_lshl_add_u32 v142, s4, 1, v151
	v_and_b32_e32 v140, 15, v141
	v_lshlrev_b32_e32 v134, 1, v141
	v_and_or_b32 v155, v134, s34, v140
	v_lshl_or_b32 v139, v155, 2, v200
	v_and_b32_e32 v134, 16, v141
	v_lshrrev_b32_e32 v138, 2, v141
	ds_read_b32 v146, v139
	v_ashrrev_i32_e32 v136, 7, v141
	v_and_or_b32 v134, v138, 8, v134
	v_lshlrev_b32_e32 v138, 7, v142
	v_lshl_add_u32 v138, v136, 6, v138
	v_bfe_u32 v137, v141, 4, 2
	v_add_u32_e32 v154, 0xfffffe00, v138
	v_or_b32_e32 v138, v138, v134
	v_cmp_lt_i32_e64 s[14:15], 1, v142
	v_cmp_lt_u32_e64 s[12:13], 3, v142
	v_cmp_lt_u32_e64 s[10:11], 5, v142
	v_cmp_ne_u32_e64 s[8:9], 6, v142
	v_cmp_gt_u32_e64 s[6:7], s34, v141
	v_lshlrev_b32_e32 v135, 2, v137
	v_cmp_eq_u32_e64 s[4:5], 0, v137
	v_ashrrev_i32_e32 v137, 31, v136
	v_lshlrev_b32_e32 v152, 1, v142
	v_add_u32_e32 v138, 0xffffff00, v138
	v_or_b32_e32 v144, s48, v155
	s_and_saveexec_b64 s[18:19], s[14:15]
	s_xor_b64 s[36:37], exec, s[18:19]
	s_cbranch_execz .LBB0_323
; __device__ __forceinline__ int widen_off(int fq) { return ((fq & 1) << 4) + ((fq >> 1) << 3); }
; template <int MODE, int NSUB>
; __device__ __forceinline__ void epilogue(const Params& p, int layer, f32x4 (&acc)[4][NSUB], int tm, int tn, int g,
;                                          const float* s_rstd, const int tid_in) {
;     ...
;         if (wr == 0) {
;           const int pos = tok_pos(t);
;           float o1[4], o2[4];
; #pragma unroll
;           for (int j = 0; j < 4; ++j) {
;             float2 cs = p.rope[pos * 16 + fq * 4 + j];
;             float x1 = acc[0][n][j] * rs, x2 = acc[1][n][j] * rs;
;             o1[j] = x1 * cs.x - x2 * cs.y;
;             o2[j] = x1 * cs.y + x2 * cs.x;
;           }
;           const u32x4 w = widen_pair(pack4(o1[0], o1[1], o1[2], o1[3]), pack4(o2[0], o2[1], o2[2], o2[3]));
; #pragma unroll
;           for (int hh = 0; hh < 8; ++hh)
;             __builtin_nontemporal_store(w, reinterpret_cast<u32x4*>(p.Kb + ((long)hh * NT + t) * 96 + 64 + widen_off(fq)));
;         }
	s_and_saveexec_b64 s[18:19], s[12:13]
	s_xor_b64 s[38:39], exec, s[18:19]
	s_cbranch_execz .LBB0_320
	s_and_saveexec_b64 s[18:19], s[10:11]
	s_xor_b64 s[40:41], exec, s[18:19]
	s_cbranch_execz .LBB0_315
	s_and_saveexec_b64 s[18:19], s[8:9]
	s_xor_b64 s[42:43], exec, s[18:19]
	s_cbranch_execz .LBB0_310
	s_and_saveexec_b64 s[44:45], s[6:7]
	s_cbranch_execz .LBB0_309
	s_mov_b32 s17, 0x10000
	v_cmp_gt_i32_e32 vcc, s17, v144
	v_lshlrev_b32_e32 v113, 3, v135
	v_readlane_b32 s64, v254, 51
	v_cndmask_b32_e32 v112, v201, v202, vcc
	v_and_b32_e32 v112, v112, v144
	v_lshl_or_b32 v116, v112, 7, v113
	v_readlane_b32 s70, v254, 57
	v_readlane_b32 s71, v254, 58
	s_nop 4
	global_load_dwordx4 v[112:115], v116, s[70:71] offset:16
	s_nop 0
	global_load_dwordx4 v[116:119], v116, s[70:71]
	v_mov_b32_e32 v161, v121
	v_mov_b32_e32 v121, v125
	v_mov_b32_e32 v160, v124
	s_waitcnt lgkmcnt(0)
	v_pk_mul_f32 v[120:121], v[120:121], v[146:147] op_sel_hi:[1,0]
	v_pk_mul_f32 v[160:161], v[160:161], v[146:147] op_sel_hi:[1,0]
	v_readlane_b32 s65, v254, 52
	v_readlane_b32 s66, v254, 53
	v_readlane_b32 s67, v254, 54
	v_readlane_b32 s68, v254, 55
	v_readlane_b32 s69, v254, 56
	v_readlane_b32 s72, v254, 59
	v_readlane_b32 s73, v254, 60
	v_readlane_b32 s74, v254, 61
	v_readlane_b32 s75, v254, 62
	v_readlane_b32 s76, v254, 63
	v_readlane_b32 s77, v252, 0
	v_readlane_b32 s78, v252, 1
	v_readlane_b32 s79, v252, 2
	v_readlane_b32 s64, v252, 4
	v_readlane_b32 s68, v252, 8
	v_readlane_b32 s69, v252, 9
	s_movk_i32 s17, 0xc0
	v_readlane_b32 s65, v252, 5
	v_readlane_b32 s66, v252, 6
	v_readlane_b32 s67, v252, 7
	v_readlane_b32 s70, v252, 10
	v_readlane_b32 s71, v252, 11
	v_readlane_b32 s72, v252, 12
	v_readlane_b32 s73, v252, 13
	v_readlane_b32 s74, v252, 14
	v_readlane_b32 s75, v252, 15
	v_readlane_b32 s76, v252, 16
	v_readlane_b32 s77, v252, 17
	v_readlane_b32 s78, v252, 18
	v_readlane_b32 s79, v252, 19
	s_waitcnt vmcnt(0)
	v_mov_b32_e32 v159, v114
	v_mov_b32_e32 v124, v116
	v_mov_b32_e32 v125, v119
	v_mov_b32_e32 v156, v117
	v_mov_b32_e32 v157, v118
	v_pk_mul_f32 v[124:125], v[120:121], v[124:125]
	v_mov_b32_e32 v163, v118
	v_pk_fma_f32 v[124:125], v[160:161], v[156:157], v[124:125]
	v_mov_b32_e32 v157, v121
	v_mov_b32_e32 v121, v161
	v_mov_b32_e32 v118, v117
	v_mov_b32_e32 v162, v116
	v_pk_mul_f32 v[116:117], v[120:121], v[118:119]
	v_mov_b32_e32 v118, v126
	v_mov_b32_e32 v119, v123
	v_mov_b32_e32 v123, v127
	v_mov_b32_e32 v156, v160
	v_pk_mul_f32 v[118:119], v[118:119], v[146:147] op_sel_hi:[1,0]
	v_pk_mul_f32 v[120:121], v[122:123], v[146:147] op_sel_hi:[1,0]
	v_mov_b32_e32 v122, v112
	v_mov_b32_e32 v123, v115
	v_pk_fma_f32 v[116:117], v[156:157], v[162:163], v[116:117] neg_lo:[0,0,1] neg_hi:[0,0,1]
	v_pk_mul_f32 v[122:123], v[120:121], v[122:123]
	v_mov_b32_e32 v127, v121
	v_mov_b32_e32 v157, v114
	v_mov_b32_e32 v121, v119
	v_mov_b32_e32 v114, v113
	v_mov_b32_e32 v158, v113
	v_mov_b32_e32 v126, v118
	v_mov_b32_e32 v156, v112
	v_pk_mul_f32 v[112:113], v[120:121], v[114:115]
	v_pk_fma_f32 v[122:123], v[118:119], v[158:159], v[122:123]
	v_pk_fma_f32 v[114:115], v[126:127], v[156:157], v[112:113] neg_lo:[0,0,1] neg_hi:[0,0,1]
	v_cvt_pk_bf16_f32 v112, v116, v117
	v_mov_b64_e32 v[116:117], s[68:69]
	v_mad_i64_i32 v[116:117], s[18:19], v144, s17, v[116:117]
	v_lshlrev_b32_e32 v118, 1, v134
	v_mov_b32_e32 v119, v153
	v_lshl_add_u64 v[116:117], v[116:117], 0, v[118:119]
	s_mov_b32 s17, 0xf00000
	v_cvt_pk_bf16_f32 v113, v114, v115
	v_cvt_pk_bf16_f32 v114, v124, v125
	v_cvt_pk_bf16_f32 v115, v122, v123
	v_add_co_u32_e32 v118, vcc, s17, v116
	v_permlane16_swap_b32_e32 v112, v114
	v_permlane16_swap_b32_e32 v113, v115
	v_addc_co_u32_e32 v119, vcc, 0, v117, vcc
	s_mov_b32 s17, 0x1e00000
	global_store_dwordx4 v[118:119], v[112:115], off offset:128 nt
	v_add_co_u32_e32 v118, vcc, s17, v116
	s_mov_b32 s17, 0x2d00000
	s_nop 0
	v_addc_co_u32_e32 v119, vcc, 0, v117, vcc
	global_store_dwordx4 v[118:119], v[112:115], off offset:128 nt
	v_add_co_u32_e32 v118, vcc, s17, v116
	global_store_dwordx4 v[116:117], v[112:115], off offset:128 nt
	s_nop 0
	v_addc_co_u32_e32 v119, vcc, 0, v117, vcc
	global_store_dwordx4 v[118:119], v[112:115], off offset:128 nt
	v_add_co_u32_e32 v118, vcc, 0x3c00000, v116
	s_nop 1
	v_addc_co_u32_e32 v119, vcc, 0, v117, vcc
	global_store_dwordx4 v[118:119], v[112:115], off offset:128 nt
	v_add_co_u32_e32 v118, vcc, 0x4b00000, v116
	s_nop 1
	v_addc_co_u32_e32 v119, vcc, 0, v117, vcc
	global_store_dwordx4 v[118:119], v[112:115], off offset:128 nt
	v_add_co_u32_e32 v118, vcc, 0x5a00000, v116
	s_nop 1
	v_addc_co_u32_e32 v119, vcc, 0, v117, vcc
	v_add_co_u32_e32 v116, vcc, 0x6900000, v116
	global_store_dwordx4 v[118:119], v[112:115], off offset:128 nt
	s_nop 0
	v_addc_co_u32_e32 v117, vcc, 0, v117, vcc
	global_store_dwordx4 v[116:117], v[112:115], off offset:128 nt
